# cache policy: GEMM output stores of the in-proj, both w1, and QKV phases made write-through (sc0 sc1) so the seam buffer_wbl2 has less to flush; on top of v67
# speedup vs baseline: 1.0063x; 1.0063x over previous
; #define PG8_STAGE(bufoff, gbase, voff) do { _Pragma("unroll") for (int _i = 0; _i < 2; ++_i) \
;         __builtin_amdgcn_global_load_lds((const unsigned*)((const char*)(gbase) + (voff)[_i]), (LAS unsigned*)(lds + (bufoff) + ldsw + _i * 8192), 16, 0, 0); } while (0)
; #define PG8_LDA(dst, b, h) do { _Pragma("unroll") for (int m = 0; m < 4; ++m) _Pragma("unroll") for (int k = 0; k < 2; ++k) dst[m][k] = *(const LAS bf16x8*)(lds + PG8_SA(b, h) + aoff + m * 2048 + k * 1024); } while (0)
; #define PG8_LDB(dst, b, h) do { _Pragma("unroll") for (int n = 0; n < 2; ++n) _Pragma("unroll") for (int k = 0; k < 2; ++k) dst[n][k] = *(const LAS bf16x8*)(lds + PG8_SB(b, h) + boff + n * 2048 + k * 1024); } while (0)
; #define PG8_MMA(ai, bj, At, Bt) do { __builtin_amdgcn_s_setprio(1); _Pragma("unroll") for (int m = 0; m < 4; ++m) _Pragma("unroll") for (int n = 0; n < 2; ++n) _Pragma("unroll") for (int k = 0; k < 2; ++k) \
;         acc[ai][bj][m][n] = __builtin_amdgcn_mfma_f32_16x16x32_bf16(Bt[n][k], At[m][k], acc[ai][bj][m][n], 0, 0, 0); __builtin_amdgcn_s_setprio(0); } while (0)
; #define PG8_WAIT_L(n) asm volatile("s_waitcnt lgkmcnt(" #n ")" ::: "memory")
; #define PG8_BAR __builtin_amdgcn_s_barrier()
; #define PG8_SCHED __builtin_amdgcn_sched_barrier(0)
; template <class Epi>
; __device__ __forceinline__ void gemm_phase(LAS unsigned char* lds, const Gemm g, const Order& S, const Epi& E, const int tid) {
;     ...
;             PG8_LDB(B0, 0, 0); PG8_SCHED; PG8_LDA(At, 0, 0); PG8_STAGE(PG8_SA(1, 1), a1 + hstepA, voffA);
;             PG8_WAIT_L(8); PG8_BAR; PG8_WAIT_L(0); PG8_MMA(0, 0, At, B0); PG8_BAR; PG8_SCHED;
;             PG8_LDB(B1, 0, 1); PG8_STAGE(PG8_SB(0, 0), b2, voffB);
;             PG8_BAR; PG8_WAIT_L(0); PG8_MMA(0, 1, At, B1); PG8_BAR;
;             PG8_LDA(At, 0, 1); PG8_STAGE(PG8_SA(0, 0), a2, voffA);
;             PG8_BAR; PG8_WAIT_L(0); PG8_MMA(1, 0, At, B0); PG8_BAR; PG8_SCHED;
.LBB0_68:
	ds_read_b128 v[150:153], v147
	ds_read_b128 v[154:157], v147 offset:1024
	ds_read_b128 v[158:161], v147 offset:2048
	ds_read_b128 v[162:165], v147 offset:3072
	s_add_u32 s22, s20, 0xfff80080
	s_addc_u32 s23, s21, -1
	s_cmp_eq_u32 s47, 28
	s_cselect_b32 s25, s9, s23
	s_cselect_b32 s24, s43, s22
	s_cselect_b32 s23, s11, s46
	s_cselect_b32 s22, s44, s45
	v_lshl_add_u64 v[198:199], s[20:21], 0, v[136:137]
	s_add_i32 m0, s7, 0xc000
	ds_read_b128 v[166:169], v148
	ds_read_b128 v[170:173], v148 offset:1024
	ds_read_b128 v[174:177], v148 offset:2048
	ds_read_b128 v[178:181], v148 offset:3072
	ds_read_b128 v[182:185], v148 offset:4096
	ds_read_b128 v[186:189], v148 offset:5120
	ds_read_b128 v[190:193], v148 offset:6144
	ds_read_b128 v[194:197], v148 offset:7168
	global_load_lds_dwordx4 v[198:199], off
	v_lshl_add_u64 v[198:199], s[20:21], 0, v[138:139]
	s_add_i32 m0, s7, 0xe000
	s_nop 0
	global_load_lds_dwordx4 v[198:199], off
	s_waitcnt lgkmcnt(8)
	s_barrier
	s_waitcnt lgkmcnt(0)
	s_setprio 1
	s_waitcnt lgkmcnt(0)
	v_mfma_f32_16x16x32_bf16 v[124:127], v[150:153], v[166:169], v[124:127]
	v_mfma_f32_16x16x32_bf16 v[120:123], v[158:161], v[166:169], v[120:123]
	v_mfma_f32_16x16x32_bf16 v[116:119], v[150:153], v[174:177], v[116:119]
	v_mfma_f32_16x16x32_bf16 v[112:115], v[158:161], v[174:177], v[112:115]
	v_mfma_f32_16x16x32_bf16 v[100:103], v[150:153], v[182:185], v[100:103]
	v_mfma_f32_16x16x32_bf16 v[96:99], v[158:161], v[182:185], v[96:99]
	v_mfma_f32_16x16x32_bf16 v[84:87], v[150:153], v[190:193], v[84:87]
	v_mfma_f32_16x16x32_bf16 v[80:83], v[158:161], v[190:193], v[80:83]
	v_mfma_f32_16x16x32_bf16 v[124:127], v[154:157], v[170:173], v[124:127]
	v_mfma_f32_16x16x32_bf16 v[120:123], v[162:165], v[170:173], v[120:123]
	v_mfma_f32_16x16x32_bf16 v[116:119], v[154:157], v[178:181], v[116:119]
	v_mfma_f32_16x16x32_bf16 v[112:115], v[162:165], v[178:181], v[112:115]
	v_mfma_f32_16x16x32_bf16 v[100:103], v[154:157], v[186:189], v[100:103]
	v_mfma_f32_16x16x32_bf16 v[96:99], v[162:165], v[186:189], v[96:99]
	v_mfma_f32_16x16x32_bf16 v[84:87], v[154:157], v[194:197], v[84:87]
	v_mfma_f32_16x16x32_bf16 v[80:83], v[162:165], v[194:197], v[80:83]
	s_setprio 0
	s_barrier
	s_add_i32 s48, s39, s26
	v_lshl_add_u64 v[214:215], s[22:23], 0, v[132:133]
	s_mov_b32 m0, s48
	ds_read_b128 v[198:201], v149
	ds_read_b128 v[202:205], v149 offset:1024
	ds_read_b128 v[206:209], v149 offset:2048
	ds_read_b128 v[210:213], v149 offset:3072
	global_load_lds_dwordx4 v[214:215], off
	v_lshl_add_u64 v[216:217], s[22:23], 0, v[128:129]
	s_add_i32 m0, s48, 0x2000
	s_nop 0
	global_load_lds_dwordx4 v[216:217], off
	s_barrier
	s_waitcnt lgkmcnt(0)
	s_setprio 1
	s_waitcnt lgkmcnt(0)
	v_mfma_f32_16x16x32_bf16 v[108:111], v[198:201], v[166:169], v[108:111]
	v_mfma_f32_16x16x32_bf16 v[104:107], v[206:209], v[166:169], v[104:107]
	v_mfma_f32_16x16x32_bf16 v[92:95], v[198:201], v[174:177], v[92:95]
	v_mfma_f32_16x16x32_bf16 v[88:91], v[206:209], v[174:177], v[88:91]
	v_mfma_f32_16x16x32_bf16 v[76:79], v[198:201], v[182:185], v[76:79]
	v_mfma_f32_16x16x32_bf16 v[72:75], v[206:209], v[182:185], v[72:75]
	v_mfma_f32_16x16x32_bf16 v[68:71], v[198:201], v[190:193], v[68:71]
	v_mfma_f32_16x16x32_bf16 v[64:67], v[206:209], v[190:193], v[64:67]
	v_mfma_f32_16x16x32_bf16 v[108:111], v[202:205], v[170:173], v[108:111]
	v_mfma_f32_16x16x32_bf16 v[104:107], v[210:213], v[170:173], v[104:107]
	v_mfma_f32_16x16x32_bf16 v[92:95], v[202:205], v[178:181], v[92:95]
	v_mfma_f32_16x16x32_bf16 v[88:91], v[210:213], v[178:181], v[88:91]
	v_mfma_f32_16x16x32_bf16 v[76:79], v[202:205], v[186:189], v[76:79]
	v_mfma_f32_16x16x32_bf16 v[72:75], v[210:213], v[186:189], v[72:75]
	v_mfma_f32_16x16x32_bf16 v[68:71], v[202:205], v[194:197], v[68:71]
	v_mfma_f32_16x16x32_bf16 v[64:67], v[210:213], v[194:197], v[64:67]
	s_setprio 0
	s_mov_b32 m0, s7
	v_lshl_add_u64 v[218:219], s[24:25], 0, v[134:135]
	s_barrier
	ds_read_b128 v[166:169], v148 offset:16384
	ds_read_b128 v[170:173], v148 offset:17408
	ds_read_b128 v[174:177], v148 offset:18432
	ds_read_b128 v[178:181], v148 offset:19456
	ds_read_b128 v[182:185], v148 offset:20480
	ds_read_b128 v[186:189], v148 offset:21504
	ds_read_b128 v[190:193], v148 offset:22528
	ds_read_b128 v[194:197], v148 offset:23552
	global_load_lds_dwordx4 v[218:219], off
	v_lshl_add_u64 v[220:221], s[24:25], 0, v[130:131]
	s_mov_b32 m0, s29
	s_nop 0
	global_load_lds_dwordx4 v[220:221], off
	s_barrier
	s_waitcnt lgkmcnt(0)
	s_setprio 1
	s_waitcnt lgkmcnt(0)
	v_mfma_f32_16x16x32_bf16 v[60:63], v[150:153], v[166:169], v[60:63]
	v_mfma_f32_16x16x32_bf16 v[56:59], v[158:161], v[166:169], v[56:59]
	v_mfma_f32_16x16x32_bf16 v[52:55], v[150:153], v[174:177], v[52:55]
	v_mfma_f32_16x16x32_bf16 v[48:51], v[158:161], v[174:177], v[48:51]
	v_mfma_f32_16x16x32_bf16 v[36:39], v[150:153], v[182:185], v[36:39]
	v_mfma_f32_16x16x32_bf16 v[32:35], v[158:161], v[182:185], v[32:35]
	v_mfma_f32_16x16x32_bf16 v[20:23], v[150:153], v[190:193], v[20:23]
	v_mfma_f32_16x16x32_bf16 v[16:19], v[158:161], v[190:193], v[16:19]
	v_mfma_f32_16x16x32_bf16 v[60:63], v[154:157], v[170:173], v[60:63]
	v_mfma_f32_16x16x32_bf16 v[56:59], v[162:165], v[170:173], v[56:59]
	v_mfma_f32_16x16x32_bf16 v[52:55], v[154:157], v[178:181], v[52:55]
	v_mfma_f32_16x16x32_bf16 v[48:51], v[162:165], v[178:181], v[48:51]
	v_mfma_f32_16x16x32_bf16 v[36:39], v[154:157], v[186:189], v[36:39]
	v_mfma_f32_16x16x32_bf16 v[32:35], v[162:165], v[186:189], v[32:35]
	v_mfma_f32_16x16x32_bf16 v[20:23], v[154:157], v[194:197], v[20:23]
	v_mfma_f32_16x16x32_bf16 v[16:19], v[162:165], v[194:197], v[16:19]
	s_setprio 0
	s_barrier
; #define PG8_STAGE(bufoff, gbase, voff) do { _Pragma("unroll") for (int _i = 0; _i < 2; ++_i) \
;         __builtin_amdgcn_global_load_lds((const unsigned*)((const char*)(gbase) + (voff)[_i]), (LAS unsigned*)(lds + (bufoff) + ldsw + _i * 8192), 16, 0, 0); } while (0)
; #define PG8_LDA(dst, b, h) do { _Pragma("unroll") for (int m = 0; m < 4; ++m) _Pragma("unroll") for (int k = 0; k < 2; ++k) dst[m][k] = *(const LAS bf16x8*)(lds + PG8_SA(b, h) + aoff + m * 2048 + k * 1024); } while (0)
; #define PG8_LDB(dst, b, h) do { _Pragma("unroll") for (int n = 0; n < 2; ++n) _Pragma("unroll") for (int k = 0; k < 2; ++k) dst[n][k] = *(const LAS bf16x8*)(lds + PG8_SB(b, h) + boff + n * 2048 + k * 1024); } while (0)
; #define PG8_MMA(ai, bj, At, Bt) do { __builtin_amdgcn_s_setprio(1); _Pragma("unroll") for (int m = 0; m < 4; ++m) _Pragma("unroll") for (int n = 0; n < 2; ++n) _Pragma("unroll") for (int k = 0; k < 2; ++k) \
;         acc[ai][bj][m][n] = __builtin_amdgcn_mfma_f32_16x16x32_bf16(Bt[n][k], At[m][k], acc[ai][bj][m][n], 0, 0, 0); __builtin_amdgcn_s_setprio(0); } while (0)
; #define PG8_WAIT_V(n) asm volatile("s_waitcnt vmcnt(" #n ")" ::: "memory")
; #define PG8_WAIT_L(n) asm volatile("s_waitcnt lgkmcnt(" #n ")" ::: "memory")
; #define PG8_BAR __builtin_amdgcn_s_barrier()
; #define PG8_SCHED __builtin_amdgcn_sched_barrier(0)
; template <class Epi>
; __device__ __forceinline__ void gemm_phase(LAS unsigned char* lds, const Gemm g, const Order& S, const Epi& E, const int tid) {
;     ...
;             PG8_STAGE(PG8_SB(0, 1), b2 + hstepB, voffB);
;             PG8_WAIT_V(6); PG8_BAR; PG8_MMA(1, 1, At, B1); PG8_BAR;
;             PG8_LDB(B0, 1, 0); PG8_SCHED; PG8_LDA(At, 1, 0); PG8_STAGE(PG8_SA(0, 1), a2 + hstepA, voffA);
;             PG8_WAIT_L(8); PG8_BAR; PG8_WAIT_L(0); PG8_MMA(0, 0, At, B0); PG8_BAR; PG8_SCHED;
;             PG8_LDB(B1, 1, 1); PG8_STAGE(PG8_SB(1, 0), b3, voffB);
;             PG8_BAR; PG8_WAIT_L(0); PG8_MMA(0, 1, At, B1); PG8_BAR;
;             PG8_LDA(At, 1, 1); PG8_STAGE(PG8_SA(1, 0), a3, voffA);
	s_add_u32 s48, s22, 0x80000
	s_addc_u32 s49, s23, 0
	s_add_i32 s50, s40, s26
	v_lshl_add_u64 v[150:151], s[48:49], 0, v[132:133]
	s_mov_b32 m0, s50
	s_nop 0
	global_load_lds_dwordx4 v[150:151], off
	v_lshl_add_u64 v[150:151], s[48:49], 0, v[128:129]
	s_add_i32 m0, s50, 0x2000
	s_nop 0
	global_load_lds_dwordx4 v[150:151], off
	s_waitcnt vmcnt(6)
	s_barrier
	s_setprio 1
	v_mfma_f32_16x16x32_bf16 v[44:47], v[198:201], v[166:169], v[44:47]
	v_mfma_f32_16x16x32_bf16 v[40:43], v[206:209], v[166:169], v[40:43]
	v_mfma_f32_16x16x32_bf16 v[28:31], v[198:201], v[174:177], v[28:31]
	v_mfma_f32_16x16x32_bf16 v[24:27], v[206:209], v[174:177], v[24:27]
	v_mfma_f32_16x16x32_bf16 v[12:15], v[198:201], v[182:185], v[12:15]
	v_mfma_f32_16x16x32_bf16 v[8:11], v[206:209], v[182:185], v[8:11]
	v_mfma_f32_16x16x32_bf16 v[4:7], v[198:201], v[190:193], v[4:7]
	v_mfma_f32_16x16x32_bf16 v[0:3], v[206:209], v[190:193], v[0:3]
	v_mfma_f32_16x16x32_bf16 v[44:47], v[202:205], v[170:173], v[44:47]
	v_mfma_f32_16x16x32_bf16 v[40:43], v[210:213], v[170:173], v[40:43]
	v_mfma_f32_16x16x32_bf16 v[28:31], v[202:205], v[178:181], v[28:31]
	v_mfma_f32_16x16x32_bf16 v[24:27], v[210:213], v[178:181], v[24:27]
	v_mfma_f32_16x16x32_bf16 v[12:15], v[202:205], v[186:189], v[12:15]
	v_mfma_f32_16x16x32_bf16 v[8:11], v[210:213], v[186:189], v[8:11]
	v_mfma_f32_16x16x32_bf16 v[4:7], v[202:205], v[194:197], v[4:7]
	v_mfma_f32_16x16x32_bf16 v[0:3], v[210:213], v[194:197], v[0:3]
	s_setprio 0
	s_add_i32 s48, 0, 0x18000
	v_add_u32_e32 v162, s48, v145
	s_barrier
	ds_read_b128 v[150:153], v162
	ds_read_b128 v[154:157], v162 offset:1024
	ds_read_b128 v[158:161], v162 offset:2048
	ds_read_b128 v[162:165], v162 offset:3072
	s_add_u32 s24, s24, 0x80000
	s_addc_u32 s25, s25, 0
	s_mov_b32 m0, s30
	v_lshl_add_u64 v[198:199], s[24:25], 0, v[134:135]
	ds_read_b128 v[166:169], v148 offset:32768
	ds_read_b128 v[170:173], v148 offset:33792
	ds_read_b128 v[174:177], v148 offset:34816
	ds_read_b128 v[178:181], v148 offset:35840
	ds_read_b128 v[182:185], v148 offset:36864
	ds_read_b128 v[186:189], v148 offset:37888
	ds_read_b128 v[190:193], v148 offset:38912
	ds_read_b128 v[194:197], v148 offset:39936
	global_load_lds_dwordx4 v[198:199], off
	v_lshl_add_u64 v[198:199], s[24:25], 0, v[130:131]
	s_mov_b32 m0, s31
	s_nop 0
	global_load_lds_dwordx4 v[198:199], off
	s_waitcnt lgkmcnt(8)
	s_barrier
	s_waitcnt lgkmcnt(0)
	s_setprio 1
	s_waitcnt lgkmcnt(0)
	v_mfma_f32_16x16x32_bf16 v[124:127], v[150:153], v[166:169], v[124:127]
	v_mfma_f32_16x16x32_bf16 v[120:123], v[158:161], v[166:169], v[120:123]
	v_mfma_f32_16x16x32_bf16 v[116:119], v[150:153], v[174:177], v[116:119]
	v_mfma_f32_16x16x32_bf16 v[112:115], v[158:161], v[174:177], v[112:115]
	v_mfma_f32_16x16x32_bf16 v[100:103], v[150:153], v[182:185], v[100:103]
	v_mfma_f32_16x16x32_bf16 v[96:99], v[158:161], v[182:185], v[96:99]
	v_mfma_f32_16x16x32_bf16 v[84:87], v[150:153], v[190:193], v[84:87]
	v_mfma_f32_16x16x32_bf16 v[80:83], v[158:161], v[190:193], v[80:83]
	v_mfma_f32_16x16x32_bf16 v[124:127], v[154:157], v[170:173], v[124:127]
	v_mfma_f32_16x16x32_bf16 v[120:123], v[162:165], v[170:173], v[120:123]
	v_mfma_f32_16x16x32_bf16 v[116:119], v[154:157], v[178:181], v[116:119]
	v_mfma_f32_16x16x32_bf16 v[112:115], v[162:165], v[178:181], v[112:115]
	v_mfma_f32_16x16x32_bf16 v[100:103], v[154:157], v[186:189], v[100:103]
	v_mfma_f32_16x16x32_bf16 v[96:99], v[162:165], v[186:189], v[96:99]
	v_mfma_f32_16x16x32_bf16 v[84:87], v[154:157], v[194:197], v[84:87]
	v_mfma_f32_16x16x32_bf16 v[80:83], v[162:165], v[194:197], v[80:83]
	s_setprio 0
	s_barrier
	s_add_i32 s24, 0, 0x1c000
	s_add_i32 s25, s48, s26
	v_add_u32_e32 v210, s24, v145
	v_lshl_add_u64 v[214:215], v[214:215], 0, s[4:5]
	s_mov_b32 m0, s25
	ds_read_b128 v[198:201], v210
	ds_read_b128 v[202:205], v210 offset:1024
	ds_read_b128 v[206:209], v210 offset:2048
	ds_read_b128 v[210:213], v210 offset:3072
	global_load_lds_dwordx4 v[214:215], off
	v_lshl_add_u64 v[214:215], v[216:217], 0, s[4:5]
	s_add_i32 m0, s25, 0x2000
	s_nop 0
	global_load_lds_dwordx4 v[214:215], off
	s_barrier
	s_waitcnt lgkmcnt(0)
	s_setprio 1
	s_waitcnt lgkmcnt(0)
	v_mfma_f32_16x16x32_bf16 v[108:111], v[198:201], v[166:169], v[108:111]
	v_mfma_f32_16x16x32_bf16 v[104:107], v[206:209], v[166:169], v[104:107]
	v_mfma_f32_16x16x32_bf16 v[92:95], v[198:201], v[174:177], v[92:95]
	v_mfma_f32_16x16x32_bf16 v[88:91], v[206:209], v[174:177], v[88:91]
	v_mfma_f32_16x16x32_bf16 v[76:79], v[198:201], v[182:185], v[76:79]
	v_mfma_f32_16x16x32_bf16 v[72:75], v[206:209], v[182:185], v[72:75]
	v_mfma_f32_16x16x32_bf16 v[68:71], v[198:201], v[190:193], v[68:71]
	v_mfma_f32_16x16x32_bf16 v[64:67], v[206:209], v[190:193], v[64:67]
	v_mfma_f32_16x16x32_bf16 v[108:111], v[202:205], v[170:173], v[108:111]
	v_mfma_f32_16x16x32_bf16 v[104:107], v[210:213], v[170:173], v[104:107]
	v_mfma_f32_16x16x32_bf16 v[92:95], v[202:205], v[178:181], v[92:95]
	v_mfma_f32_16x16x32_bf16 v[88:91], v[210:213], v[178:181], v[88:91]
	v_mfma_f32_16x16x32_bf16 v[76:79], v[202:205], v[186:189], v[76:79]
	v_mfma_f32_16x16x32_bf16 v[72:75], v[210:213], v[186:189], v[72:75]
	v_mfma_f32_16x16x32_bf16 v[68:71], v[202:205], v[194:197], v[68:71]
	v_mfma_f32_16x16x32_bf16 v[64:67], v[210:213], v[194:197], v[64:67]
	s_setprio 0
	s_mov_b32 m0, s34
	v_lshl_add_u64 v[214:215], v[218:219], 0, s[4:5]
	s_barrier
	ds_read_b128 v[166:169], v148 offset:49152
	ds_read_b128 v[170:173], v148 offset:50176
	ds_read_b128 v[174:177], v148 offset:51200
	ds_read_b128 v[178:181], v148 offset:52224
	ds_read_b128 v[182:185], v148 offset:53248
	ds_read_b128 v[186:189], v148 offset:54272
	ds_read_b128 v[190:193], v148 offset:55296
	ds_read_b128 v[194:197], v148 offset:56320
	global_load_lds_dwordx4 v[214:215], off
	v_lshl_add_u64 v[214:215], v[220:221], 0, s[4:5]
	s_mov_b32 m0, s35
	s_nop 0
	global_load_lds_dwordx4 v[214:215], off
	s_barrier
; #define PG8_STAGE(bufoff, gbase, voff) do { _Pragma("unroll") for (int _i = 0; _i < 2; ++_i) \
;         __builtin_amdgcn_global_load_lds((const unsigned*)((const char*)(gbase) + (voff)[_i]), (LAS unsigned*)(lds + (bufoff) + ldsw + _i * 8192), 16, 0, 0); } while (0)
; #define PG8_MMA(ai, bj, At, Bt) do { __builtin_amdgcn_s_setprio(1); _Pragma("unroll") for (int m = 0; m < 4; ++m) _Pragma("unroll") for (int n = 0; n < 2; ++n) _Pragma("unroll") for (int k = 0; k < 2; ++k) \
;         acc[ai][bj][m][n] = __builtin_amdgcn_mfma_f32_16x16x32_bf16(Bt[n][k], At[m][k], acc[ai][bj][m][n], 0, 0, 0); __builtin_amdgcn_s_setprio(0); } while (0)
; #define PG8_WAIT_V(n) asm volatile("s_waitcnt vmcnt(" #n ")" ::: "memory")
; #define PG8_WAIT_L(n) asm volatile("s_waitcnt lgkmcnt(" #n ")" ::: "memory")
; #define PG8_BAR __builtin_amdgcn_s_barrier()
; #define PG8_SCHED __builtin_amdgcn_sched_barrier(0)
; template <class Epi>
; __device__ __forceinline__ void gemm_phase(LAS unsigned char* lds, const Gemm g, const Order& S, const Epi& E, const int tid) {
;     ...
;             PG8_BAR; PG8_WAIT_L(0); PG8_MMA(1, 0, At, B0); PG8_BAR; PG8_SCHED;
;             PG8_STAGE(PG8_SB(1, 1), b3 + hstepB, voffB);
;             PG8_WAIT_V(6); PG8_BAR; PG8_MMA(1, 1, At, B1); PG8_BAR;
	s_waitcnt lgkmcnt(0)
	s_setprio 1
	s_waitcnt lgkmcnt(0)
	v_mfma_f32_16x16x32_bf16 v[60:63], v[150:153], v[166:169], v[60:63]
	v_mfma_f32_16x16x32_bf16 v[56:59], v[158:161], v[166:169], v[56:59]
	v_mfma_f32_16x16x32_bf16 v[52:55], v[150:153], v[174:177], v[52:55]
	v_mfma_f32_16x16x32_bf16 v[48:51], v[158:161], v[174:177], v[48:51]
	v_mfma_f32_16x16x32_bf16 v[36:39], v[150:153], v[182:185], v[36:39]
	v_mfma_f32_16x16x32_bf16 v[32:35], v[158:161], v[182:185], v[32:35]
	v_mfma_f32_16x16x32_bf16 v[20:23], v[150:153], v[190:193], v[20:23]
	v_mfma_f32_16x16x32_bf16 v[16:19], v[158:161], v[190:193], v[16:19]
	v_mfma_f32_16x16x32_bf16 v[60:63], v[154:157], v[170:173], v[60:63]
	v_mfma_f32_16x16x32_bf16 v[56:59], v[162:165], v[170:173], v[56:59]
	v_mfma_f32_16x16x32_bf16 v[52:55], v[154:157], v[178:181], v[52:55]
	v_mfma_f32_16x16x32_bf16 v[48:51], v[162:165], v[178:181], v[48:51]
	v_mfma_f32_16x16x32_bf16 v[36:39], v[154:157], v[186:189], v[36:39]
	v_mfma_f32_16x16x32_bf16 v[32:35], v[162:165], v[186:189], v[32:35]
	v_mfma_f32_16x16x32_bf16 v[20:23], v[154:157], v[194:197], v[20:23]
	v_mfma_f32_16x16x32_bf16 v[16:19], v[162:165], v[194:197], v[16:19]
	s_setprio 0
	s_barrier
	s_add_u32 s22, s22, 0x80080
	s_addc_u32 s23, s23, 0
	s_add_i32 s24, s24, s26
	v_lshl_add_u64 v[150:151], s[22:23], 0, v[132:133]
	s_mov_b32 m0, s24
	s_nop 0
	global_load_lds_dwordx4 v[150:151], off
	v_lshl_add_u64 v[150:151], s[22:23], 0, v[128:129]
	s_add_i32 m0, s24, 0x2000
	s_nop 0
	global_load_lds_dwordx4 v[150:151], off
	s_waitcnt vmcnt(6)
	s_barrier
	s_setprio 1
	v_mfma_f32_16x16x32_bf16 v[44:47], v[198:201], v[166:169], v[44:47]
	v_mfma_f32_16x16x32_bf16 v[40:43], v[206:209], v[166:169], v[40:43]
	v_mfma_f32_16x16x32_bf16 v[28:31], v[198:201], v[174:177], v[28:31]
	v_mfma_f32_16x16x32_bf16 v[24:27], v[206:209], v[174:177], v[24:27]
	v_mfma_f32_16x16x32_bf16 v[12:15], v[198:201], v[182:185], v[12:15]
	v_mfma_f32_16x16x32_bf16 v[8:11], v[206:209], v[182:185], v[8:11]
	v_mfma_f32_16x16x32_bf16 v[4:7], v[198:201], v[190:193], v[4:7]
	v_mfma_f32_16x16x32_bf16 v[0:3], v[206:209], v[190:193], v[0:3]
	v_mfma_f32_16x16x32_bf16 v[44:47], v[202:205], v[170:173], v[44:47]
	v_mfma_f32_16x16x32_bf16 v[40:43], v[210:213], v[170:173], v[40:43]
	v_mfma_f32_16x16x32_bf16 v[28:31], v[202:205], v[178:181], v[28:31]
	v_mfma_f32_16x16x32_bf16 v[24:27], v[210:213], v[178:181], v[24:27]
	v_mfma_f32_16x16x32_bf16 v[12:15], v[202:205], v[186:189], v[12:15]
	v_mfma_f32_16x16x32_bf16 v[8:11], v[210:213], v[186:189], v[8:11]
	v_mfma_f32_16x16x32_bf16 v[4:7], v[202:205], v[194:197], v[4:7]
	v_mfma_f32_16x16x32_bf16 v[0:3], v[210:213], v[194:197], v[0:3]
	s_setprio 0
	s_add_i32 s47, s47, 2
	s_add_u32 s20, s20, 0x100
	s_addc_u32 s21, s21, 0
	s_add_u32 s45, s45, 0x100
	s_addc_u32 s46, s46, 0
	s_cmp_gt_u32 s47, 29
	s_barrier
	s_cbranch_scc0 .LBB0_68
; #define PG8_WAIT_V(n) asm volatile("s_waitcnt vmcnt(" #n ")" ::: "memory")
; #define PG8_BAR __builtin_amdgcn_s_barrier()
; template <class Epi>
; __device__ __forceinline__ void gemm_phase(LAS unsigned char* lds, const Gemm g, const Order& S, const Epi& E, const int tid) {
;     ...
;         E(acc, cur, wr, wc, fr, fq);
;         if (!has_next) break;
;     ...
;     PG8_WAIT_V(0);
;     if (wr == 0) PG8_BAR;
;     __device__ __forceinline__ void operator()(const f32x4 (&acc)[2][2][4][2], const Unit& u, int wr, int wc, int fr, int fq) const {
;         const int row0 = u.pm * BM + wr * 64 + fr, col0 = u.pn * BM + wc * 32 + 8 * fq;
; #pragma unroll
;         for (int ai = 0; ai < 2; ++ai)
; #pragma unroll
;             for (int m = 0; m < 4; ++m) { bf16_t* rowp = O + (size_t)(row0 + ai * HALF + m * 16) * ldc + col0;
;                 float rs = 1.0f; if (RS) rs = rt[u.i * 256 + wr * 64 + fr + ai * HALF + m * 16];
; #pragma unroll
;                 for (int bj = 0; bj < 2; ++bj) { f32x4 v0 = acc[ai][bj][m][0], v1 = acc[ai][bj][m][1];
;                     if (RS) { v0 *= rs; v1 *= rs; }
;                     if (ACT == 1) {
; #pragma unroll
;                         for (int j = 0; j < 4; ++j) { const float a = fmaxf(v0[j], 0.f), b = fmaxf(v1[j], 0.f); v0[j] = a * a; v1[j] = b * b; } }
;                     u32x4 w; w.x = pk2(v0[0], v0[1]); w.y = pk2(v0[2], v0[3]); w.z = pk2(v1[0], v1[1]); w.w = pk2(v1[2], v1[3]);
;                     *(u32x4*)(rowp + bj * HALF) = w; } }
	v_lshl_add_u32 v156, s6, 8, v144
	v_lshl_or_b32 v150, s42, 8, v146
	v_ashrrev_i32_e32 v151, 31, v150
	v_mov_b64_e32 v[152:153], s[72:73]
	v_cvt_pk_bf16_f32 v68, v68, v69
	v_cvt_pk_bf16_f32 v69, v70, v71
	v_cvt_pk_bf16_f32 v70, v64, v65
	v_add_u32_e32 v64, 0x80, v156
	v_mad_i64_i32 v[154:155], s[20:21], v156, s41, v[152:153]
	v_lshlrev_b64 v[150:151], 1, v[150:151]
	v_cvt_pk_bf16_f32 v108, v108, v109
	v_cvt_pk_bf16_f32 v109, v110, v111
	v_cvt_pk_bf16_f32 v110, v104, v105
	v_or_b32_e32 v104, 16, v156
	v_mad_i64_i32 v[64:65], s[20:21], v64, s41, v[152:153]
	v_cvt_pk_bf16_f32 v44, v44, v45
	v_cvt_pk_bf16_f32 v45, v46, v47
	v_cvt_pk_bf16_f32 v46, v40, v41
	v_add_u32_e32 v40, 0x90, v156
	v_lshl_add_u64 v[154:155], v[154:155], 0, v[150:151]
	v_cvt_pk_bf16_f32 v111, v106, v107
	v_mad_i64_i32 v[104:105], s[20:21], v104, s41, v[152:153]
	v_cvt_pk_bf16_f32 v92, v92, v93
	v_cvt_pk_bf16_f32 v93, v94, v95
	v_cvt_pk_bf16_f32 v94, v88, v89
	v_or_b32_e32 v88, 32, v156
	v_lshl_add_u64 v[64:65], v[64:65], 0, v[150:151]
	v_cvt_pk_bf16_f32 v47, v42, v43
	v_mad_i64_i32 v[40:41], s[20:21], v40, s41, v[152:153]
	v_cvt_pk_bf16_f32 v28, v28, v29
	v_cvt_pk_bf16_f32 v29, v30, v31
	v_cvt_pk_bf16_f32 v30, v24, v25
	v_add_u32_e32 v24, 0xa0, v156
	global_store_dwordx4 v[154:155], v[108:111], off offset:256 sc0 sc1
	v_cvt_pk_bf16_f32 v95, v90, v91
	v_mad_i64_i32 v[88:89], s[20:21], v88, s41, v[152:153]
	v_lshl_add_u64 v[108:109], v[104:105], 0, v[150:151]
	v_cvt_pk_bf16_f32 v76, v76, v77
	v_cvt_pk_bf16_f32 v77, v78, v79
	v_cvt_pk_bf16_f32 v78, v72, v73
	v_or_b32_e32 v72, 48, v156
	global_store_dwordx4 v[64:65], v[44:47], off offset:256 sc0 sc1
	v_cvt_pk_bf16_f32 v31, v26, v27
	v_mad_i64_i32 v[24:25], s[20:21], v24, s41, v[152:153]
	v_lshl_add_u64 v[44:45], v[40:41], 0, v[150:151]
	v_cvt_pk_bf16_f32 v12, v12, v13
	v_cvt_pk_bf16_f32 v13, v14, v15
	v_cvt_pk_bf16_f32 v14, v8, v9
	v_add_u32_e32 v8, 0xb0, v156
	global_store_dwordx4 v[108:109], v[92:95], off offset:256 sc0 sc1
	v_cvt_pk_bf16_f32 v79, v74, v75
	v_mad_i64_i32 v[72:73], s[20:21], v72, s41, v[152:153]
	v_lshl_add_u64 v[92:93], v[88:89], 0, v[150:151]
	global_store_dwordx4 v[44:45], v[28:31], off offset:256 sc0 sc1
	v_cvt_pk_bf16_f32 v15, v10, v11
	v_mad_i64_i32 v[8:9], s[20:21], v8, s41, v[152:153]
	v_lshl_add_u64 v[28:29], v[24:25], 0, v[150:151]
	v_cvt_pk_bf16_f32 v124, v124, v125
	v_cvt_pk_bf16_f32 v125, v126, v127
	v_cvt_pk_bf16_f32 v126, v120, v121
	v_cvt_pk_bf16_f32 v127, v122, v123
	v_cvt_pk_bf16_f32 v104, v116, v117
	v_cvt_pk_bf16_f32 v105, v118, v119
	v_cvt_pk_bf16_f32 v106, v112, v113
	v_cvt_pk_bf16_f32 v107, v114, v115
	v_cvt_pk_bf16_f32 v88, v100, v101
	v_cvt_pk_bf16_f32 v89, v102, v103
	v_cvt_pk_bf16_f32 v90, v96, v97
	v_cvt_pk_bf16_f32 v91, v98, v99
	global_store_dwordx4 v[92:93], v[76:79], off offset:256 sc0 sc1
	v_cvt_pk_bf16_f32 v74, v80, v81
	v_cvt_pk_bf16_f32 v75, v82, v83
	v_lshl_add_u64 v[76:77], v[72:73], 0, v[150:151]
	v_cvt_pk_bf16_f32 v72, v84, v85
	v_cvt_pk_bf16_f32 v73, v86, v87
	v_cvt_pk_bf16_f32 v71, v66, v67
	v_cvt_pk_bf16_f32 v60, v60, v61
	v_cvt_pk_bf16_f32 v61, v62, v63
	v_cvt_pk_bf16_f32 v62, v56, v57
	v_cvt_pk_bf16_f32 v63, v58, v59
	v_cvt_pk_bf16_f32 v40, v52, v53
	v_cvt_pk_bf16_f32 v41, v54, v55
	v_cvt_pk_bf16_f32 v42, v48, v49
	v_cvt_pk_bf16_f32 v43, v50, v51
	v_cvt_pk_bf16_f32 v24, v36, v37
	v_cvt_pk_bf16_f32 v25, v38, v39
	v_cvt_pk_bf16_f32 v26, v32, v33
	v_cvt_pk_bf16_f32 v27, v34, v35
	global_store_dwordx4 v[28:29], v[12:15], off offset:256 sc0 sc1
	v_cvt_pk_bf16_f32 v10, v16, v17
	v_cvt_pk_bf16_f32 v11, v18, v19
	v_lshl_add_u64 v[12:13], v[8:9], 0, v[150:151]
	v_cvt_pk_bf16_f32 v8, v20, v21
	v_cvt_pk_bf16_f32 v9, v22, v23
	v_cvt_pk_bf16_f32 v4, v4, v5
	v_cvt_pk_bf16_f32 v5, v6, v7
	v_cvt_pk_bf16_f32 v6, v0, v1
	v_cvt_pk_bf16_f32 v7, v2, v3
	s_and_b64 vcc, exec, s[0:1]
	s_mov_b32 s42, s10
	s_mov_b32 s6, s8
	s_mov_b64 s[22:23], s[18:19]
	s_mov_b64 s[20:21], s[12:13]
	global_store_dwordx4 v[154:155], v[124:127], off sc0 sc1
	global_store_dwordx4 v[108:109], v[104:107], off sc0 sc1
	global_store_dwordx4 v[92:93], v[88:91], off sc0 sc1
	global_store_dwordx4 v[76:77], v[72:75], off sc0 sc1
	global_store_dwordx4 v[76:77], v[68:71], off offset:256 sc0 sc1
	global_store_dwordx4 v[64:65], v[60:63], off sc0 sc1
	global_store_dwordx4 v[44:45], v[40:43], off sc0 sc1
	global_store_dwordx4 v[28:29], v[24:27], off sc0 sc1
	global_store_dwordx4 v[12:13], v[8:11], off sc0 sc1
	global_store_dwordx4 v[12:13], v[4:7], off offset:256 sc0 sc1
	s_cbranch_vccz .LBB0_65
	s_waitcnt vmcnt(0)
	s_cmpk_gt_u32 s3, 0xff
	s_cbranch_scc1 .LBB0_72
	s_barrier

; #define PG8_STAGE(bufoff, gbase, voff) do { _Pragma("unroll") for (int _i = 0; _i < 2; ++_i) \
;         __builtin_amdgcn_global_load_lds((const unsigned*)((const char*)(gbase) + (voff)[_i]), (LAS unsigned*)(lds + (bufoff) + ldsw + _i * 8192), 16, 0, 0); } while (0)
; #define PG8_LDA(dst, b, h) do { _Pragma("unroll") for (int m = 0; m < 4; ++m) _Pragma("unroll") for (int k = 0; k < 2; ++k) dst[m][k] = *(const LAS bf16x8*)(lds + PG8_SA(b, h) + aoff + m * 2048 + k * 1024); } while (0)
; #define PG8_LDB(dst, b, h) do { _Pragma("unroll") for (int n = 0; n < 2; ++n) _Pragma("unroll") for (int k = 0; k < 2; ++k) dst[n][k] = *(const LAS bf16x8*)(lds + PG8_SB(b, h) + boff + n * 2048 + k * 1024); } while (0)
; #define PG8_MMA(ai, bj, At, Bt) do { __builtin_amdgcn_s_setprio(1); _Pragma("unroll") for (int m = 0; m < 4; ++m) _Pragma("unroll") for (int n = 0; n < 2; ++n) _Pragma("unroll") for (int k = 0; k < 2; ++k) \
;         acc[ai][bj][m][n] = __builtin_amdgcn_mfma_f32_16x16x32_bf16(Bt[n][k], At[m][k], acc[ai][bj][m][n], 0, 0, 0); __builtin_amdgcn_s_setprio(0); } while (0)
; #define PG8_WAIT_L(n) asm volatile("s_waitcnt lgkmcnt(" #n ")" ::: "memory")
; #define PG8_BAR __builtin_amdgcn_s_barrier()
; #define PG8_SCHED __builtin_amdgcn_sched_barrier(0)
; template <class Epi>
; __device__ __forceinline__ void gemm_phase(LAS unsigned char* lds, const Gemm g, const Order& S, const Epi& E, const int tid) {
;     ...
;             PG8_LDB(B0, 0, 0); PG8_SCHED; PG8_LDA(At, 0, 0); PG8_STAGE(PG8_SA(1, 1), a1 + hstepA, voffA);
;             PG8_WAIT_L(8); PG8_BAR; PG8_WAIT_L(0); PG8_MMA(0, 0, At, B0); PG8_BAR; PG8_SCHED;
;             PG8_LDB(B1, 0, 1); PG8_STAGE(PG8_SB(0, 0), b2, voffB);
;             PG8_BAR; PG8_WAIT_L(0); PG8_MMA(0, 1, At, B1); PG8_BAR;
;             PG8_LDA(At, 0, 1); PG8_STAGE(PG8_SA(0, 0), a2, voffA);
;             PG8_BAR; PG8_WAIT_L(0); PG8_MMA(1, 0, At, B0); PG8_BAR; PG8_SCHED;
.LBB0_658:
	ds_read_b128 v[154:157], v150
	ds_read_b128 v[158:161], v150 offset:1024
	ds_read_b128 v[162:165], v150 offset:2048
	ds_read_b128 v[166:169], v150 offset:3072
	s_add_u32 s30, s28, 0xfff80080
	s_addc_u32 s31, s29, -1
	s_cmp_eq_u32 s60, 28
	s_cselect_b32 s35, s15, s31
	s_cselect_b32 s34, s56, s30
	s_cselect_b32 s31, s17, s59
	s_cselect_b32 s30, s57, s58
	v_lshl_add_u64 v[144:145], s[28:29], 0, v[136:137]
	s_add_i32 m0, s27, 0xc000
	ds_read_b128 v[170:173], v151
	ds_read_b128 v[174:177], v151 offset:1024
	ds_read_b128 v[178:181], v151 offset:2048
	ds_read_b128 v[182:185], v151 offset:3072
	ds_read_b128 v[186:189], v151 offset:4096
	ds_read_b128 v[190:193], v151 offset:5120
	ds_read_b128 v[194:197], v151 offset:6144
	ds_read_b128 v[198:201], v151 offset:7168
	global_load_lds_dwordx4 v[144:145], off
	v_lshl_add_u64 v[144:145], s[28:29], 0, v[138:139]
	s_add_i32 m0, s27, 0xe000
	s_nop 0
	global_load_lds_dwordx4 v[144:145], off
	s_waitcnt lgkmcnt(8)
	s_barrier
	s_waitcnt lgkmcnt(0)
	s_setprio 1
	s_waitcnt lgkmcnt(0)
	v_mfma_f32_16x16x32_bf16 v[124:127], v[154:157], v[170:173], v[124:127]
	v_mfma_f32_16x16x32_bf16 v[120:123], v[162:165], v[170:173], v[120:123]
	v_mfma_f32_16x16x32_bf16 v[108:111], v[154:157], v[178:181], v[108:111]
	v_mfma_f32_16x16x32_bf16 v[104:107], v[162:165], v[178:181], v[104:107]
	v_mfma_f32_16x16x32_bf16 v[92:95], v[154:157], v[186:189], v[92:95]
	v_mfma_f32_16x16x32_bf16 v[88:91], v[162:165], v[186:189], v[88:91]
	v_mfma_f32_16x16x32_bf16 v[76:79], v[154:157], v[194:197], v[76:79]
	v_mfma_f32_16x16x32_bf16 v[72:75], v[162:165], v[194:197], v[72:75]
	v_mfma_f32_16x16x32_bf16 v[124:127], v[158:161], v[174:177], v[124:127]
	v_mfma_f32_16x16x32_bf16 v[120:123], v[166:169], v[174:177], v[120:123]
	v_mfma_f32_16x16x32_bf16 v[108:111], v[158:161], v[182:185], v[108:111]
	v_mfma_f32_16x16x32_bf16 v[104:107], v[166:169], v[182:185], v[104:107]
	v_mfma_f32_16x16x32_bf16 v[92:95], v[158:161], v[190:193], v[92:95]
	v_mfma_f32_16x16x32_bf16 v[88:91], v[166:169], v[190:193], v[88:91]
	v_mfma_f32_16x16x32_bf16 v[76:79], v[158:161], v[198:201], v[76:79]
	v_mfma_f32_16x16x32_bf16 v[72:75], v[166:169], v[198:201], v[72:75]
	s_setprio 0
	s_barrier
	s_add_i32 s61, s45, s39
	v_lshl_add_u64 v[144:145], s[30:31], 0, v[132:133]
	s_mov_b32 m0, s61
	ds_read_b128 v[202:205], v152
	ds_read_b128 v[206:209], v152 offset:1024
	ds_read_b128 v[210:213], v152 offset:2048
	ds_read_b128 v[214:217], v152 offset:3072
	global_load_lds_dwordx4 v[144:145], off
	v_lshl_add_u64 v[218:219], s[30:31], 0, v[128:129]
	s_add_i32 m0, s61, 0x2000
	s_nop 0
	global_load_lds_dwordx4 v[218:219], off
	s_barrier
	s_waitcnt lgkmcnt(0)
	s_setprio 1
	s_waitcnt lgkmcnt(0)
	v_mfma_f32_16x16x32_bf16 v[116:119], v[202:205], v[170:173], v[116:119]
	v_mfma_f32_16x16x32_bf16 v[112:115], v[210:213], v[170:173], v[112:115]
	v_mfma_f32_16x16x32_bf16 v[100:103], v[202:205], v[178:181], v[100:103]
	v_mfma_f32_16x16x32_bf16 v[96:99], v[210:213], v[178:181], v[96:99]
	v_mfma_f32_16x16x32_bf16 v[84:87], v[202:205], v[186:189], v[84:87]
	v_mfma_f32_16x16x32_bf16 v[80:83], v[210:213], v[186:189], v[80:83]
	v_mfma_f32_16x16x32_bf16 v[68:71], v[202:205], v[194:197], v[68:71]
	v_mfma_f32_16x16x32_bf16 v[64:67], v[210:213], v[194:197], v[64:67]
	v_mfma_f32_16x16x32_bf16 v[116:119], v[206:209], v[174:177], v[116:119]
	v_mfma_f32_16x16x32_bf16 v[112:115], v[214:217], v[174:177], v[112:115]
	v_mfma_f32_16x16x32_bf16 v[100:103], v[206:209], v[182:185], v[100:103]
	v_mfma_f32_16x16x32_bf16 v[96:99], v[214:217], v[182:185], v[96:99]
	v_mfma_f32_16x16x32_bf16 v[84:87], v[206:209], v[190:193], v[84:87]
	v_mfma_f32_16x16x32_bf16 v[80:83], v[214:217], v[190:193], v[80:83]
	v_mfma_f32_16x16x32_bf16 v[68:71], v[206:209], v[198:201], v[68:71]
	v_mfma_f32_16x16x32_bf16 v[64:67], v[214:217], v[198:201], v[64:67]
	s_setprio 0
	s_mov_b32 m0, s27
	v_lshl_add_u64 v[220:221], s[34:35], 0, v[134:135]
	s_barrier
	ds_read_b128 v[170:173], v151 offset:16384
	ds_read_b128 v[174:177], v151 offset:17408
	ds_read_b128 v[178:181], v151 offset:18432
	ds_read_b128 v[182:185], v151 offset:19456
	ds_read_b128 v[186:189], v151 offset:20480
	ds_read_b128 v[190:193], v151 offset:21504
	ds_read_b128 v[194:197], v151 offset:22528
	ds_read_b128 v[198:201], v151 offset:23552
	global_load_lds_dwordx4 v[220:221], off
	v_lshl_add_u64 v[222:223], s[34:35], 0, v[130:131]
	s_mov_b32 m0, s40
	s_nop 0
	global_load_lds_dwordx4 v[222:223], off
	s_barrier
	s_waitcnt lgkmcnt(0)
	s_setprio 1
	s_waitcnt lgkmcnt(0)
	v_mfma_f32_16x16x32_bf16 v[60:63], v[154:157], v[170:173], v[60:63]
	v_mfma_f32_16x16x32_bf16 v[56:59], v[162:165], v[170:173], v[56:59]
	v_mfma_f32_16x16x32_bf16 v[44:47], v[154:157], v[178:181], v[44:47]
	v_mfma_f32_16x16x32_bf16 v[40:43], v[162:165], v[178:181], v[40:43]
	v_mfma_f32_16x16x32_bf16 v[28:31], v[154:157], v[186:189], v[28:31]
	v_mfma_f32_16x16x32_bf16 v[24:27], v[162:165], v[186:189], v[24:27]
	v_mfma_f32_16x16x32_bf16 v[12:15], v[154:157], v[194:197], v[12:15]
	v_mfma_f32_16x16x32_bf16 v[8:11], v[162:165], v[194:197], v[8:11]
	v_mfma_f32_16x16x32_bf16 v[60:63], v[158:161], v[174:177], v[60:63]
	v_mfma_f32_16x16x32_bf16 v[56:59], v[166:169], v[174:177], v[56:59]
	v_mfma_f32_16x16x32_bf16 v[44:47], v[158:161], v[182:185], v[44:47]
	v_mfma_f32_16x16x32_bf16 v[40:43], v[166:169], v[182:185], v[40:43]
	v_mfma_f32_16x16x32_bf16 v[28:31], v[158:161], v[190:193], v[28:31]
	v_mfma_f32_16x16x32_bf16 v[24:27], v[166:169], v[190:193], v[24:27]
	v_mfma_f32_16x16x32_bf16 v[12:15], v[158:161], v[198:201], v[12:15]
	v_mfma_f32_16x16x32_bf16 v[8:11], v[166:169], v[198:201], v[8:11]
	s_setprio 0
	s_barrier
; #define PG8_STAGE(bufoff, gbase, voff) do { _Pragma("unroll") for (int _i = 0; _i < 2; ++_i) \
;         __builtin_amdgcn_global_load_lds((const unsigned*)((const char*)(gbase) + (voff)[_i]), (LAS unsigned*)(lds + (bufoff) + ldsw + _i * 8192), 16, 0, 0); } while (0)
; #define PG8_LDA(dst, b, h) do { _Pragma("unroll") for (int m = 0; m < 4; ++m) _Pragma("unroll") for (int k = 0; k < 2; ++k) dst[m][k] = *(const LAS bf16x8*)(lds + PG8_SA(b, h) + aoff + m * 2048 + k * 1024); } while (0)
; #define PG8_LDB(dst, b, h) do { _Pragma("unroll") for (int n = 0; n < 2; ++n) _Pragma("unroll") for (int k = 0; k < 2; ++k) dst[n][k] = *(const LAS bf16x8*)(lds + PG8_SB(b, h) + boff + n * 2048 + k * 1024); } while (0)
; #define PG8_MMA(ai, bj, At, Bt) do { __builtin_amdgcn_s_setprio(1); _Pragma("unroll") for (int m = 0; m < 4; ++m) _Pragma("unroll") for (int n = 0; n < 2; ++n) _Pragma("unroll") for (int k = 0; k < 2; ++k) \
;         acc[ai][bj][m][n] = __builtin_amdgcn_mfma_f32_16x16x32_bf16(Bt[n][k], At[m][k], acc[ai][bj][m][n], 0, 0, 0); __builtin_amdgcn_s_setprio(0); } while (0)
; #define PG8_WAIT_V(n) asm volatile("s_waitcnt vmcnt(" #n ")" ::: "memory")
; #define PG8_WAIT_L(n) asm volatile("s_waitcnt lgkmcnt(" #n ")" ::: "memory")
; #define PG8_BAR __builtin_amdgcn_s_barrier()
; #define PG8_SCHED __builtin_amdgcn_sched_barrier(0)
; template <class Epi>
; __device__ __forceinline__ void gemm_phase(LAS unsigned char* lds, const Gemm g, const Order& S, const Epi& E, const int tid) {
;     ...
;             PG8_STAGE(PG8_SB(0, 1), b2 + hstepB, voffB);
;             PG8_WAIT_V(6); PG8_BAR; PG8_MMA(1, 1, At, B1); PG8_BAR;
;             PG8_LDB(B0, 1, 0); PG8_SCHED; PG8_LDA(At, 1, 0); PG8_STAGE(PG8_SA(0, 1), a2 + hstepA, voffA);
;             PG8_WAIT_L(8); PG8_BAR; PG8_WAIT_L(0); PG8_MMA(0, 0, At, B0); PG8_BAR; PG8_SCHED;
;             PG8_LDB(B1, 1, 1); PG8_STAGE(PG8_SB(1, 0), b3, voffB);
;             PG8_BAR; PG8_WAIT_L(0); PG8_MMA(0, 1, At, B1); PG8_BAR;
;             PG8_LDA(At, 1, 1); PG8_STAGE(PG8_SA(1, 0), a3, voffA);
	s_add_u32 s66, s30, 0x80000
	s_addc_u32 s67, s31, 0
	s_add_i32 s61, s46, s39
	v_lshl_add_u64 v[154:155], s[66:67], 0, v[132:133]
	s_mov_b32 m0, s61
	s_nop 0
	global_load_lds_dwordx4 v[154:155], off
	v_lshl_add_u64 v[154:155], s[66:67], 0, v[128:129]
	s_add_i32 m0, s61, 0x2000
	s_nop 0
	global_load_lds_dwordx4 v[154:155], off
	s_waitcnt vmcnt(6)
	s_barrier
	s_setprio 1
	v_mfma_f32_16x16x32_bf16 v[52:55], v[202:205], v[170:173], v[52:55]
	v_mfma_f32_16x16x32_bf16 v[48:51], v[210:213], v[170:173], v[48:51]
	v_mfma_f32_16x16x32_bf16 v[36:39], v[202:205], v[178:181], v[36:39]
	v_mfma_f32_16x16x32_bf16 v[32:35], v[210:213], v[178:181], v[32:35]
	v_mfma_f32_16x16x32_bf16 v[20:23], v[202:205], v[186:189], v[20:23]
	v_mfma_f32_16x16x32_bf16 v[16:19], v[210:213], v[186:189], v[16:19]
	v_mfma_f32_16x16x32_bf16 v[4:7], v[202:205], v[194:197], v[4:7]
	v_mfma_f32_16x16x32_bf16 v[0:3], v[210:213], v[194:197], v[0:3]
	v_mfma_f32_16x16x32_bf16 v[52:55], v[206:209], v[174:177], v[52:55]
	v_mfma_f32_16x16x32_bf16 v[48:51], v[214:217], v[174:177], v[48:51]
	v_mfma_f32_16x16x32_bf16 v[36:39], v[206:209], v[182:185], v[36:39]
	v_mfma_f32_16x16x32_bf16 v[32:35], v[214:217], v[182:185], v[32:35]
	v_mfma_f32_16x16x32_bf16 v[20:23], v[206:209], v[190:193], v[20:23]
	v_mfma_f32_16x16x32_bf16 v[16:19], v[214:217], v[190:193], v[16:19]
	v_mfma_f32_16x16x32_bf16 v[4:7], v[206:209], v[198:201], v[4:7]
	v_mfma_f32_16x16x32_bf16 v[0:3], v[214:217], v[198:201], v[0:3]
	s_setprio 0
	s_add_i32 s61, 0, 0x18000
	v_add_u32_e32 v153, s61, v147
	s_barrier
	ds_read_b128 v[154:157], v153
	ds_read_b128 v[158:161], v153 offset:1024
	ds_read_b128 v[162:165], v153 offset:2048
	ds_read_b128 v[166:169], v153 offset:3072
	s_add_u32 s34, s34, 0x80000
	s_addc_u32 s35, s35, 0
	s_mov_b32 m0, s41
	v_lshl_add_u64 v[202:203], s[34:35], 0, v[134:135]
	ds_read_b128 v[170:173], v151 offset:32768
	ds_read_b128 v[174:177], v151 offset:33792
	ds_read_b128 v[178:181], v151 offset:34816
	ds_read_b128 v[182:185], v151 offset:35840
	ds_read_b128 v[186:189], v151 offset:36864
	ds_read_b128 v[190:193], v151 offset:37888
	ds_read_b128 v[194:197], v151 offset:38912
	ds_read_b128 v[198:201], v151 offset:39936
	global_load_lds_dwordx4 v[202:203], off
	v_lshl_add_u64 v[202:203], s[34:35], 0, v[130:131]
	s_mov_b32 m0, s42
	s_nop 0
	global_load_lds_dwordx4 v[202:203], off
	s_waitcnt lgkmcnt(8)
	s_barrier
	s_waitcnt lgkmcnt(0)
	s_setprio 1
	s_waitcnt lgkmcnt(0)
	v_mfma_f32_16x16x32_bf16 v[124:127], v[154:157], v[170:173], v[124:127]
	v_mfma_f32_16x16x32_bf16 v[120:123], v[162:165], v[170:173], v[120:123]
	v_mfma_f32_16x16x32_bf16 v[108:111], v[154:157], v[178:181], v[108:111]
	v_mfma_f32_16x16x32_bf16 v[104:107], v[162:165], v[178:181], v[104:107]
	v_mfma_f32_16x16x32_bf16 v[92:95], v[154:157], v[186:189], v[92:95]
	v_mfma_f32_16x16x32_bf16 v[88:91], v[162:165], v[186:189], v[88:91]
	v_mfma_f32_16x16x32_bf16 v[76:79], v[154:157], v[194:197], v[76:79]
	v_mfma_f32_16x16x32_bf16 v[72:75], v[162:165], v[194:197], v[72:75]
	v_mfma_f32_16x16x32_bf16 v[124:127], v[158:161], v[174:177], v[124:127]
	v_mfma_f32_16x16x32_bf16 v[120:123], v[166:169], v[174:177], v[120:123]
	v_mfma_f32_16x16x32_bf16 v[108:111], v[158:161], v[182:185], v[108:111]
	v_mfma_f32_16x16x32_bf16 v[104:107], v[166:169], v[182:185], v[104:107]
	v_mfma_f32_16x16x32_bf16 v[92:95], v[158:161], v[190:193], v[92:95]
	v_mfma_f32_16x16x32_bf16 v[88:91], v[166:169], v[190:193], v[88:91]
	v_mfma_f32_16x16x32_bf16 v[76:79], v[158:161], v[198:201], v[76:79]
	v_mfma_f32_16x16x32_bf16 v[72:75], v[166:169], v[198:201], v[72:75]
	s_setprio 0
	s_barrier
	s_add_i32 s34, 0, 0x1c000
	s_add_i32 s35, s61, s39
	v_add_u32_e32 v153, s34, v147
	v_lshl_add_u64 v[144:145], v[144:145], 0, s[4:5]
	s_mov_b32 m0, s35
	ds_read_b128 v[202:205], v153
	ds_read_b128 v[206:209], v153 offset:1024
	ds_read_b128 v[210:213], v153 offset:2048
	ds_read_b128 v[214:217], v153 offset:3072
	global_load_lds_dwordx4 v[144:145], off
	v_lshl_add_u64 v[144:145], v[218:219], 0, s[4:5]
	s_add_i32 m0, s35, 0x2000
	s_nop 0
	global_load_lds_dwordx4 v[144:145], off
	s_barrier
	s_waitcnt lgkmcnt(0)
	s_setprio 1
	s_waitcnt lgkmcnt(0)
	v_mfma_f32_16x16x32_bf16 v[116:119], v[202:205], v[170:173], v[116:119]
	v_mfma_f32_16x16x32_bf16 v[112:115], v[210:213], v[170:173], v[112:115]
	v_mfma_f32_16x16x32_bf16 v[100:103], v[202:205], v[178:181], v[100:103]
	v_mfma_f32_16x16x32_bf16 v[96:99], v[210:213], v[178:181], v[96:99]
	v_mfma_f32_16x16x32_bf16 v[84:87], v[202:205], v[186:189], v[84:87]
	v_mfma_f32_16x16x32_bf16 v[80:83], v[210:213], v[186:189], v[80:83]
	v_mfma_f32_16x16x32_bf16 v[68:71], v[202:205], v[194:197], v[68:71]
	v_mfma_f32_16x16x32_bf16 v[64:67], v[210:213], v[194:197], v[64:67]
	v_mfma_f32_16x16x32_bf16 v[116:119], v[206:209], v[174:177], v[116:119]
	v_mfma_f32_16x16x32_bf16 v[112:115], v[214:217], v[174:177], v[112:115]
	v_mfma_f32_16x16x32_bf16 v[100:103], v[206:209], v[182:185], v[100:103]
	v_mfma_f32_16x16x32_bf16 v[96:99], v[214:217], v[182:185], v[96:99]
	v_mfma_f32_16x16x32_bf16 v[84:87], v[206:209], v[190:193], v[84:87]
	v_mfma_f32_16x16x32_bf16 v[80:83], v[214:217], v[190:193], v[80:83]
	v_mfma_f32_16x16x32_bf16 v[68:71], v[206:209], v[198:201], v[68:71]
	v_mfma_f32_16x16x32_bf16 v[64:67], v[214:217], v[198:201], v[64:67]
	s_setprio 0
	s_mov_b32 m0, s43
	v_lshl_add_u64 v[144:145], v[220:221], 0, s[4:5]
	s_barrier
	ds_read_b128 v[170:173], v151 offset:49152
	ds_read_b128 v[174:177], v151 offset:50176
	ds_read_b128 v[178:181], v151 offset:51200
	ds_read_b128 v[182:185], v151 offset:52224
	ds_read_b128 v[186:189], v151 offset:53248
	ds_read_b128 v[190:193], v151 offset:54272
	ds_read_b128 v[194:197], v151 offset:55296
	ds_read_b128 v[198:201], v151 offset:56320
	global_load_lds_dwordx4 v[144:145], off
	v_lshl_add_u64 v[144:145], v[222:223], 0, s[4:5]
	s_mov_b32 m0, s44
	s_nop 0
	global_load_lds_dwordx4 v[144:145], off
	s_barrier
; #define PG8_STAGE(bufoff, gbase, voff) do { _Pragma("unroll") for (int _i = 0; _i < 2; ++_i) \
;         __builtin_amdgcn_global_load_lds((const unsigned*)((const char*)(gbase) + (voff)[_i]), (LAS unsigned*)(lds + (bufoff) + ldsw + _i * 8192), 16, 0, 0); } while (0)
; #define PG8_MMA(ai, bj, At, Bt) do { __builtin_amdgcn_s_setprio(1); _Pragma("unroll") for (int m = 0; m < 4; ++m) _Pragma("unroll") for (int n = 0; n < 2; ++n) _Pragma("unroll") for (int k = 0; k < 2; ++k) \
;         acc[ai][bj][m][n] = __builtin_amdgcn_mfma_f32_16x16x32_bf16(Bt[n][k], At[m][k], acc[ai][bj][m][n], 0, 0, 0); __builtin_amdgcn_s_setprio(0); } while (0)
; #define PG8_WAIT_V(n) asm volatile("s_waitcnt vmcnt(" #n ")" ::: "memory")
; #define PG8_WAIT_L(n) asm volatile("s_waitcnt lgkmcnt(" #n ")" ::: "memory")
; #define PG8_BAR __builtin_amdgcn_s_barrier()
; #define PG8_SCHED __builtin_amdgcn_sched_barrier(0)
; template <class Epi>
; __device__ __forceinline__ void gemm_phase(LAS unsigned char* lds, const Gemm g, const Order& S, const Epi& E, const int tid) {
;     ...
;             PG8_BAR; PG8_WAIT_L(0); PG8_MMA(1, 0, At, B0); PG8_BAR; PG8_SCHED;
;             PG8_STAGE(PG8_SB(1, 1), b3 + hstepB, voffB);
;             PG8_WAIT_V(6); PG8_BAR; PG8_MMA(1, 1, At, B1); PG8_BAR;
;     __device__ __forceinline__ void operator()(const f32x4 (&acc)[2][2][4][2], const Unit& u, int wr, int wc, int fr, int fq) const {
;     ...
;             for (int m = 0; m < 4; ++m) { bf16_t* rowp = O + (size_t)(row0 + ai * HALF + m * 16) * ldc + col0;
;                 float rs = 1.0f; if (RS) rs = rt[u.i * 256 + wr * 64 + fr + ai * HALF + m * 16];
; #pragma unroll
;                 for (int bj = 0; bj < 2; ++bj) { f32x4 v0 = acc[ai][bj][m][0], v1 = acc[ai][bj][m][1];
;                     if (RS) { v0 *= rs; v1 *= rs; }
;                     if (ACT == 1) {
; #pragma unroll
;                         for (int j = 0; j < 4; ++j) { const float a = fmaxf(v0[j], 0.f), b = fmaxf(v1[j], 0.f); v0[j] = a * a; v1[j] = b * b; } }
;                     u32x4 w; w.x = pk2(v0[0], v0[1]); w.y = pk2(v0[2], v0[3]); w.z = pk2(v1[0], v1[1]); w.w = pk2(v1[2], v1[3]);
;                     *(u32x4*)(rowp + bj * HALF) = w; } }
	s_waitcnt lgkmcnt(0)
	s_setprio 1
	s_waitcnt lgkmcnt(0)
	v_mfma_f32_16x16x32_bf16 v[60:63], v[154:157], v[170:173], v[60:63]
	v_mfma_f32_16x16x32_bf16 v[56:59], v[162:165], v[170:173], v[56:59]
	v_mfma_f32_16x16x32_bf16 v[44:47], v[154:157], v[178:181], v[44:47]
	v_mfma_f32_16x16x32_bf16 v[40:43], v[162:165], v[178:181], v[40:43]
	v_mfma_f32_16x16x32_bf16 v[28:31], v[154:157], v[186:189], v[28:31]
	v_mfma_f32_16x16x32_bf16 v[24:27], v[162:165], v[186:189], v[24:27]
	v_mfma_f32_16x16x32_bf16 v[12:15], v[154:157], v[194:197], v[12:15]
	v_mfma_f32_16x16x32_bf16 v[8:11], v[162:165], v[194:197], v[8:11]
	v_mfma_f32_16x16x32_bf16 v[60:63], v[158:161], v[174:177], v[60:63]
	v_mfma_f32_16x16x32_bf16 v[56:59], v[166:169], v[174:177], v[56:59]
	v_mfma_f32_16x16x32_bf16 v[44:47], v[158:161], v[182:185], v[44:47]
	v_mfma_f32_16x16x32_bf16 v[40:43], v[166:169], v[182:185], v[40:43]
	v_mfma_f32_16x16x32_bf16 v[28:31], v[158:161], v[190:193], v[28:31]
	v_mfma_f32_16x16x32_bf16 v[24:27], v[166:169], v[190:193], v[24:27]
	v_mfma_f32_16x16x32_bf16 v[12:15], v[158:161], v[198:201], v[12:15]
	v_mfma_f32_16x16x32_bf16 v[8:11], v[166:169], v[198:201], v[8:11]
	s_setprio 0
	s_barrier
	s_add_u32 s30, s30, 0x80080
	s_addc_u32 s31, s31, 0
	s_add_i32 s34, s34, s39
	v_lshl_add_u64 v[144:145], s[30:31], 0, v[132:133]
	s_mov_b32 m0, s34
	s_nop 0
	global_load_lds_dwordx4 v[144:145], off
	v_lshl_add_u64 v[144:145], s[30:31], 0, v[128:129]
	s_add_i32 m0, s34, 0x2000
	s_nop 0
	global_load_lds_dwordx4 v[144:145], off
	s_waitcnt vmcnt(6)
	s_barrier
	s_setprio 1
	v_mfma_f32_16x16x32_bf16 v[52:55], v[202:205], v[170:173], v[52:55]
	v_mfma_f32_16x16x32_bf16 v[48:51], v[210:213], v[170:173], v[48:51]
	v_mfma_f32_16x16x32_bf16 v[36:39], v[202:205], v[178:181], v[36:39]
	v_mfma_f32_16x16x32_bf16 v[32:35], v[210:213], v[178:181], v[32:35]
	v_mfma_f32_16x16x32_bf16 v[20:23], v[202:205], v[186:189], v[20:23]
	v_mfma_f32_16x16x32_bf16 v[16:19], v[210:213], v[186:189], v[16:19]
	v_mfma_f32_16x16x32_bf16 v[4:7], v[202:205], v[194:197], v[4:7]
	v_mfma_f32_16x16x32_bf16 v[0:3], v[210:213], v[194:197], v[0:3]
	v_mfma_f32_16x16x32_bf16 v[52:55], v[206:209], v[174:177], v[52:55]
	v_mfma_f32_16x16x32_bf16 v[48:51], v[214:217], v[174:177], v[48:51]
	v_mfma_f32_16x16x32_bf16 v[36:39], v[206:209], v[182:185], v[36:39]
	v_mfma_f32_16x16x32_bf16 v[32:35], v[214:217], v[182:185], v[32:35]
	v_mfma_f32_16x16x32_bf16 v[20:23], v[206:209], v[190:193], v[20:23]
	v_mfma_f32_16x16x32_bf16 v[16:19], v[214:217], v[190:193], v[16:19]
	v_mfma_f32_16x16x32_bf16 v[4:7], v[206:209], v[198:201], v[4:7]
	v_mfma_f32_16x16x32_bf16 v[0:3], v[214:217], v[198:201], v[0:3]
	s_setprio 0
	s_add_i32 s60, s60, 2
	s_add_u32 s28, s28, 0x100
	s_addc_u32 s29, s29, 0
	s_add_u32 s58, s58, 0x100
	s_addc_u32 s59, s59, 0
	s_cmp_gt_u32 s60, 29
	s_barrier
	s_cbranch_scc0 .LBB0_658
	v_lshl_add_u32 v153, s53, 10, v148
	ds_read2_b32 v[156:157], v153 offset1:16
	v_lshl_add_u32 v154, s26, 8, v146
	v_lshl_or_b32 v144, s55, 8, v149
	v_ashrrev_i32_e32 v155, 31, v154
	v_ashrrev_i32_e32 v145, 31, v144
	s_waitcnt lgkmcnt(0)
	v_pk_mul_f32 v[122:123], v[122:123], v[156:157] op_sel_hi:[1,0]
	v_pk_mul_f32 v[120:121], v[120:121], v[156:157] op_sel_hi:[1,0]
	v_pk_mul_f32 v[126:127], v[126:127], v[156:157] op_sel_hi:[1,0]
	v_pk_mul_f32 v[124:125], v[124:125], v[156:157] op_sel_hi:[1,0]
	v_max_f32_e32 v120, 0, v120
	v_max_f32_e32 v121, 0, v121
	v_max_f32_e32 v122, 0, v122
	v_lshlrev_b64 v[158:159], 14, v[154:155]
	v_max_f32_e32 v124, 0, v124
	v_mul_f32_e32 v155, v120, v120
	v_max_f32_e32 v120, 0, v125
	v_mul_f32_e32 v125, v121, v121
	v_max_f32_e32 v121, 0, v126
	v_mul_f32_e32 v126, v122, v122
	v_max_f32_e32 v122, 0, v127
	v_max_f32_e32 v123, 0, v123
	v_lshl_add_u64 v[158:159], s[72:73], 0, v[158:159]
	v_lshlrev_b64 v[160:161], 1, v[144:145]
	v_mul_f32_e32 v124, v124, v124
	v_mul_f32_e32 v120, v120, v120
	v_mul_f32_e32 v121, v121, v121
	v_mul_f32_e32 v122, v122, v122
	v_mul_f32_e32 v123, v123, v123
	v_pk_mul_f32 v[114:115], v[114:115], v[156:157] op_sel_hi:[1,0]
	v_pk_mul_f32 v[112:113], v[112:113], v[156:157] op_sel_hi:[1,0]
	v_lshl_add_u64 v[144:145], v[158:159], 0, v[160:161]
	v_cvt_pk_bf16_f32 v120, v124, v120
	v_cvt_pk_bf16_f32 v121, v121, v122
	v_cvt_pk_bf16_f32 v122, v155, v125
	v_cvt_pk_bf16_f32 v123, v126, v123
	v_pk_mul_f32 v[118:119], v[118:119], v[156:157] op_sel_hi:[1,0]
	v_pk_mul_f32 v[116:117], v[116:117], v[156:157] op_sel_hi:[1,0]
	v_max_f32_e32 v112, 0, v112
	v_max_f32_e32 v113, 0, v113
	v_max_f32_e32 v114, 0, v114
	global_store_dwordx4 v[144:145], v[120:123], off sc0 sc1
	v_max_f32_e32 v116, 0, v116
	v_max_f32_e32 v115, 0, v115
	v_mul_f32_e32 v120, v112, v112
	v_max_f32_e32 v112, 0, v117
	v_mul_f32_e32 v117, v113, v113
	v_max_f32_e32 v113, 0, v118
	v_mul_f32_e32 v118, v114, v114
	v_max_f32_e32 v114, 0, v119
	v_mul_f32_e32 v116, v116, v116
	v_mul_f32_e32 v112, v112, v112
	v_mul_f32_e32 v113, v113, v113
	v_mul_f32_e32 v114, v114, v114
	v_mul_f32_e32 v115, v115, v115
	v_cvt_pk_bf16_f32 v112, v116, v112
	v_cvt_pk_bf16_f32 v113, v113, v114
	v_cvt_pk_bf16_f32 v114, v120, v117
	v_cvt_pk_bf16_f32 v115, v118, v115
	global_store_dwordx4 v[144:145], v[112:115], off offset:256 sc0 sc1
	s_mov_b32 s53, s52
	s_mov_b32 s55, s16
	v_mov_b32_e32 v114, v157
	v_or_b32_e32 v112, 16, v154
	v_pk_mul_f32 v[106:107], v[106:107], v[114:115] op_sel_hi:[1,0]
	v_pk_mul_f32 v[104:105], v[104:105], v[114:115] op_sel_hi:[1,0]
	v_ashrrev_i32_e32 v113, 31, v112
	v_pk_mul_f32 v[110:111], v[110:111], v[114:115] op_sel_hi:[1,0]
	v_pk_mul_f32 v[108:109], v[108:109], v[114:115] op_sel_hi:[1,0]
	v_max_f32_e32 v104, 0, v104
	v_max_f32_e32 v105, 0, v105
	v_max_f32_e32 v106, 0, v106
;     __device__ __forceinline__ void operator()(const f32x4 (&acc)[2][2][4][2], const Unit& u, int wr, int wc, int fr, int fq) const {
;     ...
;             for (int m = 0; m < 4; ++m) { bf16_t* rowp = O + (size_t)(row0 + ai * HALF + m * 16) * ldc + col0;
;                 float rs = 1.0f; if (RS) rs = rt[u.i * 256 + wr * 64 + fr + ai * HALF + m * 16];
; #pragma unroll
;                 for (int bj = 0; bj < 2; ++bj) { f32x4 v0 = acc[ai][bj][m][0], v1 = acc[ai][bj][m][1];
;                     if (RS) { v0 *= rs; v1 *= rs; }
;                     if (ACT == 1) {
; #pragma unroll
;                         for (int j = 0; j < 4; ++j) { const float a = fmaxf(v0[j], 0.f), b = fmaxf(v1[j], 0.f); v0[j] = a * a; v1[j] = b * b; } }
;                     u32x4 w; w.x = pk2(v0[0], v0[1]); w.y = pk2(v0[2], v0[3]); w.z = pk2(v1[0], v1[1]); w.w = pk2(v1[2], v1[3]);
;                     *(u32x4*)(rowp + bj * HALF) = w; } }
	v_lshlrev_b64 v[112:113], 14, v[112:113]
	v_max_f32_e32 v108, 0, v108
	v_mul_f32_e32 v115, v104, v104
	v_max_f32_e32 v104, 0, v109
	v_mul_f32_e32 v109, v105, v105
	v_max_f32_e32 v105, 0, v110
	v_mul_f32_e32 v110, v106, v106
	v_max_f32_e32 v106, 0, v111
	v_max_f32_e32 v107, 0, v107
	v_lshl_add_u64 v[112:113], s[72:73], 0, v[112:113]
	v_mul_f32_e32 v108, v108, v108
	v_mul_f32_e32 v104, v104, v104
	v_mul_f32_e32 v105, v105, v105
	v_mul_f32_e32 v106, v106, v106
	v_mul_f32_e32 v107, v107, v107
	v_pk_mul_f32 v[98:99], v[98:99], v[114:115] op_sel_hi:[1,0]
	v_pk_mul_f32 v[96:97], v[96:97], v[114:115] op_sel_hi:[1,0]
	v_lshl_add_u64 v[112:113], v[112:113], 0, v[160:161]
	v_cvt_pk_bf16_f32 v104, v108, v104
	v_cvt_pk_bf16_f32 v105, v105, v106
	v_cvt_pk_bf16_f32 v106, v115, v109
	v_cvt_pk_bf16_f32 v107, v110, v107
	v_pk_mul_f32 v[102:103], v[102:103], v[114:115] op_sel_hi:[1,0]
	v_pk_mul_f32 v[100:101], v[100:101], v[114:115] op_sel_hi:[1,0]
	v_max_f32_e32 v96, 0, v96
	v_max_f32_e32 v97, 0, v97
	v_max_f32_e32 v98, 0, v98
	global_store_dwordx4 v[112:113], v[104:107], off sc0 sc1
	v_max_f32_e32 v100, 0, v100
	v_max_f32_e32 v99, 0, v99
	v_mul_f32_e32 v104, v96, v96
	v_max_f32_e32 v96, 0, v101
	v_mul_f32_e32 v101, v97, v97
	v_max_f32_e32 v97, 0, v102
	v_mul_f32_e32 v102, v98, v98
	v_max_f32_e32 v98, 0, v103
	v_mul_f32_e32 v100, v100, v100
	v_mul_f32_e32 v96, v96, v96
	v_mul_f32_e32 v97, v97, v97
	v_mul_f32_e32 v98, v98, v98
	v_mul_f32_e32 v99, v99, v99
	v_cvt_pk_bf16_f32 v96, v100, v96
	v_cvt_pk_bf16_f32 v97, v97, v98
	v_cvt_pk_bf16_f32 v98, v104, v101
	v_cvt_pk_bf16_f32 v99, v102, v99
	global_store_dwordx4 v[112:113], v[96:99], off offset:256 sc0 sc1
	ds_read2_b32 v[98:99], v153 offset0:32 offset1:48
	s_mov_b32 s26, s14
	v_or_b32_e32 v96, 32, v154
	v_ashrrev_i32_e32 v97, 31, v96
	v_lshlrev_b64 v[96:97], 14, v[96:97]
	s_waitcnt lgkmcnt(0)
	v_pk_mul_f32 v[90:91], v[90:91], v[98:99] op_sel_hi:[1,0]
	v_pk_mul_f32 v[88:89], v[88:89], v[98:99] op_sel_hi:[1,0]
	v_pk_mul_f32 v[94:95], v[94:95], v[98:99] op_sel_hi:[1,0]
	v_pk_mul_f32 v[92:93], v[92:93], v[98:99] op_sel_hi:[1,0]
	v_max_f32_e32 v88, 0, v88
	v_max_f32_e32 v89, 0, v89
	v_max_f32_e32 v90, 0, v90
	v_max_f32_e32 v92, 0, v92
	v_mul_f32_e32 v100, v88, v88
	v_max_f32_e32 v88, 0, v93
	v_mul_f32_e32 v93, v89, v89
	v_max_f32_e32 v89, 0, v94
	v_mul_f32_e32 v94, v90, v90
	v_max_f32_e32 v90, 0, v95
	v_max_f32_e32 v91, 0, v91
	v_lshl_add_u64 v[96:97], s[72:73], 0, v[96:97]
	v_mul_f32_e32 v92, v92, v92
	v_mul_f32_e32 v88, v88, v88
	v_mul_f32_e32 v89, v89, v89
	v_mul_f32_e32 v90, v90, v90
	v_mul_f32_e32 v91, v91, v91
	v_pk_mul_f32 v[82:83], v[82:83], v[98:99] op_sel_hi:[1,0]
	v_pk_mul_f32 v[80:81], v[80:81], v[98:99] op_sel_hi:[1,0]
	v_lshl_add_u64 v[96:97], v[96:97], 0, v[160:161]
	v_cvt_pk_bf16_f32 v88, v92, v88
	v_cvt_pk_bf16_f32 v89, v89, v90
	v_cvt_pk_bf16_f32 v90, v100, v93
	v_cvt_pk_bf16_f32 v91, v94, v91
	v_pk_mul_f32 v[86:87], v[86:87], v[98:99] op_sel_hi:[1,0]
	v_pk_mul_f32 v[84:85], v[84:85], v[98:99] op_sel_hi:[1,0]
	v_max_f32_e32 v80, 0, v80
	v_max_f32_e32 v81, 0, v81
	v_max_f32_e32 v82, 0, v82
	global_store_dwordx4 v[96:97], v[88:91], off sc0 sc1
	v_max_f32_e32 v84, 0, v84
	v_max_f32_e32 v83, 0, v83
	v_mul_f32_e32 v88, v80, v80
	v_max_f32_e32 v80, 0, v85
	v_mul_f32_e32 v85, v81, v81
	v_max_f32_e32 v81, 0, v86
	v_mul_f32_e32 v86, v82, v82
	v_max_f32_e32 v82, 0, v87
	v_mul_f32_e32 v84, v84, v84
	v_mul_f32_e32 v80, v80, v80
	v_mul_f32_e32 v81, v81, v81
	v_mul_f32_e32 v82, v82, v82
	v_mul_f32_e32 v83, v83, v83
	v_cvt_pk_bf16_f32 v80, v84, v80
	v_cvt_pk_bf16_f32 v81, v81, v82
	v_cvt_pk_bf16_f32 v82, v88, v85
	v_cvt_pk_bf16_f32 v83, v86, v83
	global_store_dwordx4 v[96:97], v[80:83], off offset:256 sc0 sc1
	s_mov_b64 s[30:31], s[20:21]
	s_mov_b64 s[28:29], s[18:19]
	v_mov_b32_e32 v82, v99
	v_or_b32_e32 v80, 48, v154
	v_pk_mul_f32 v[74:75], v[74:75], v[82:83] op_sel_hi:[1,0]
	v_pk_mul_f32 v[72:73], v[72:73], v[82:83] op_sel_hi:[1,0]
	v_ashrrev_i32_e32 v81, 31, v80
	v_pk_mul_f32 v[78:79], v[78:79], v[82:83] op_sel_hi:[1,0]
	v_pk_mul_f32 v[76:77], v[76:77], v[82:83] op_sel_hi:[1,0]
	v_max_f32_e32 v72, 0, v72
	v_max_f32_e32 v73, 0, v73
	v_max_f32_e32 v74, 0, v74
	v_lshlrev_b64 v[80:81], 14, v[80:81]
	v_max_f32_e32 v76, 0, v76
	v_mul_f32_e32 v83, v72, v72
	v_max_f32_e32 v72, 0, v77
	v_mul_f32_e32 v77, v73, v73
	v_max_f32_e32 v73, 0, v78
	v_mul_f32_e32 v78, v74, v74
	v_max_f32_e32 v74, 0, v79
	v_max_f32_e32 v75, 0, v75
	v_lshl_add_u64 v[80:81], s[72:73], 0, v[80:81]
	v_mul_f32_e32 v76, v76, v76
	v_mul_f32_e32 v72, v72, v72
	v_mul_f32_e32 v73, v73, v73
	v_mul_f32_e32 v74, v74, v74
	v_mul_f32_e32 v75, v75, v75
	v_pk_mul_f32 v[64:65], v[64:65], v[82:83] op_sel_hi:[1,0]
	v_lshl_add_u64 v[80:81], v[80:81], 0, v[160:161]
	v_cvt_pk_bf16_f32 v72, v76, v72
	v_cvt_pk_bf16_f32 v73, v73, v74
	v_cvt_pk_bf16_f32 v74, v83, v77
	v_cvt_pk_bf16_f32 v75, v78, v75
	v_pk_mul_f32 v[68:69], v[68:69], v[82:83] op_sel_hi:[1,0]
	v_max_f32_e32 v64, 0, v64
	global_store_dwordx4 v[80:81], v[72:75], off sc0 sc1
	v_max_f32_e32 v68, 0, v68
	v_mul_f32_e32 v68, v68, v68
	v_mul_f32_e32 v72, v64, v64
	v_max_f32_e32 v64, 0, v69
	v_mul_f32_e32 v64, v64, v64
	v_cvt_pk_bf16_f32 v64, v68, v64
	ds_read2_b32 v[68:69], v153 offset0:128 offset1:144
	v_pk_mul_f32 v[66:67], v[66:67], v[82:83] op_sel_hi:[1,0]
	v_pk_mul_f32 v[70:71], v[70:71], v[82:83] op_sel_hi:[1,0]
	v_max_f32_e32 v65, 0, v65
	v_max_f32_e32 v66, 0, v66
	v_mul_f32_e32 v73, v65, v65
	v_max_f32_e32 v65, 0, v70
	v_mul_f32_e32 v70, v66, v66
	v_max_f32_e32 v66, 0, v71
	v_max_f32_e32 v67, 0, v67
	v_mul_f32_e32 v65, v65, v65
	v_mul_f32_e32 v66, v66, v66
	v_mul_f32_e32 v67, v67, v67
	s_waitcnt lgkmcnt(0)
;     __device__ __forceinline__ void operator()(const f32x4 (&acc)[2][2][4][2], const Unit& u, int wr, int wc, int fr, int fq) const {
;     ...
;             for (int m = 0; m < 4; ++m) { bf16_t* rowp = O + (size_t)(row0 + ai * HALF + m * 16) * ldc + col0;
;                 float rs = 1.0f; if (RS) rs = rt[u.i * 256 + wr * 64 + fr + ai * HALF + m * 16];
; #pragma unroll
;                 for (int bj = 0; bj < 2; ++bj) { f32x4 v0 = acc[ai][bj][m][0], v1 = acc[ai][bj][m][1];
;                     if (RS) { v0 *= rs; v1 *= rs; }
;                     if (ACT == 1) {
; #pragma unroll
;                         for (int j = 0; j < 4; ++j) { const float a = fmaxf(v0[j], 0.f), b = fmaxf(v1[j], 0.f); v0[j] = a * a; v1[j] = b * b; } }
;                     u32x4 w; w.x = pk2(v0[0], v0[1]); w.y = pk2(v0[2], v0[3]); w.z = pk2(v1[0], v1[1]); w.w = pk2(v1[2], v1[3]);
;                     *(u32x4*)(rowp + bj * HALF) = w; } }
	v_pk_mul_f32 v[56:57], v[56:57], v[68:69] op_sel_hi:[1,0]
	v_cvt_pk_bf16_f32 v65, v65, v66
	v_cvt_pk_bf16_f32 v66, v72, v73
	v_cvt_pk_bf16_f32 v67, v70, v67
	v_pk_mul_f32 v[60:61], v[60:61], v[68:69] op_sel_hi:[1,0]
	v_pk_mul_f32 v[58:59], v[58:59], v[68:69] op_sel_hi:[1,0]
	v_max_f32_e32 v56, 0, v56
	global_store_dwordx4 v[80:81], v[64:67], off offset:256 sc0 sc1
	v_pk_mul_f32 v[62:63], v[62:63], v[68:69] op_sel_hi:[1,0]
	v_max_f32_e32 v60, 0, v60
	v_mul_f32_e32 v66, v56, v56
	v_max_f32_e32 v56, 0, v61
	v_max_f32_e32 v57, 0, v57
	v_max_f32_e32 v58, 0, v58
	v_mul_f32_e32 v60, v60, v60
	v_mul_f32_e32 v56, v56, v56
	v_mul_f32_e32 v61, v57, v57
	v_max_f32_e32 v57, 0, v62
	v_mul_f32_e32 v62, v58, v58
	v_max_f32_e32 v58, 0, v63
	v_max_f32_e32 v59, 0, v59
	v_mul_f32_e32 v57, v57, v57
	v_mul_f32_e32 v58, v58, v58
	v_mul_f32_e32 v59, v59, v59
	v_cvt_pk_bf16_f32 v56, v60, v56
	v_add_co_u32_e32 v60, vcc, s47, v144
	v_pk_mul_f32 v[50:51], v[50:51], v[68:69] op_sel_hi:[1,0]
	v_pk_mul_f32 v[48:49], v[48:49], v[68:69] op_sel_hi:[1,0]
	v_cvt_pk_bf16_f32 v57, v57, v58
	v_cvt_pk_bf16_f32 v58, v66, v61
	v_cvt_pk_bf16_f32 v59, v62, v59
	v_addc_co_u32_e32 v61, vcc, 0, v145, vcc
	v_pk_mul_f32 v[54:55], v[54:55], v[68:69] op_sel_hi:[1,0]
	v_pk_mul_f32 v[52:53], v[52:53], v[68:69] op_sel_hi:[1,0]
	v_max_f32_e32 v48, 0, v48
	v_max_f32_e32 v49, 0, v49
	v_max_f32_e32 v50, 0, v50
	global_store_dwordx4 v[60:61], v[56:59], off sc0 sc1
	v_max_f32_e32 v52, 0, v52
	v_max_f32_e32 v51, 0, v51
	v_mul_f32_e32 v56, v48, v48
	v_max_f32_e32 v48, 0, v53
	v_mul_f32_e32 v53, v49, v49
	v_max_f32_e32 v49, 0, v54
	v_mul_f32_e32 v54, v50, v50
	v_max_f32_e32 v50, 0, v55
	v_mul_f32_e32 v52, v52, v52
	v_mul_f32_e32 v48, v48, v48
	v_mul_f32_e32 v49, v49, v49
	v_mul_f32_e32 v50, v50, v50
	v_mul_f32_e32 v51, v51, v51
	v_lshl_add_u64 v[64:65], v[144:145], 0, s[6:7]
	v_cvt_pk_bf16_f32 v48, v52, v48
	v_cvt_pk_bf16_f32 v49, v49, v50
	v_cvt_pk_bf16_f32 v50, v56, v53
	v_cvt_pk_bf16_f32 v51, v54, v51
	global_store_dwordx4 v[64:65], v[48:51], off offset:256 sc0 sc1
	s_nop 1
	v_mov_b32_e32 v50, v69
	v_pk_mul_f32 v[40:41], v[40:41], v[50:51] op_sel_hi:[1,0]
	v_pk_mul_f32 v[44:45], v[44:45], v[50:51] op_sel_hi:[1,0]
	v_pk_mul_f32 v[42:43], v[42:43], v[50:51] op_sel_hi:[1,0]
	v_max_f32_e32 v40, 0, v40
	v_pk_mul_f32 v[46:47], v[46:47], v[50:51] op_sel_hi:[1,0]
	v_max_f32_e32 v44, 0, v44
	v_mul_f32_e32 v51, v40, v40
	v_max_f32_e32 v40, 0, v45
	v_max_f32_e32 v41, 0, v41
	v_max_f32_e32 v42, 0, v42
	v_mul_f32_e32 v44, v44, v44
	v_mul_f32_e32 v40, v40, v40
	v_mul_f32_e32 v45, v41, v41
	v_max_f32_e32 v41, 0, v46
	v_mul_f32_e32 v46, v42, v42
	v_max_f32_e32 v42, 0, v47
	v_max_f32_e32 v43, 0, v43
	v_mul_f32_e32 v41, v41, v41
	v_mul_f32_e32 v42, v42, v42
	v_mul_f32_e32 v43, v43, v43
	v_cvt_pk_bf16_f32 v40, v44, v40
	v_add_co_u32_e32 v44, vcc, s48, v144
	v_pk_mul_f32 v[32:33], v[32:33], v[50:51] op_sel_hi:[1,0]
	v_cvt_pk_bf16_f32 v41, v41, v42
	v_cvt_pk_bf16_f32 v42, v51, v45
	v_cvt_pk_bf16_f32 v43, v46, v43
	v_addc_co_u32_e32 v45, vcc, 0, v145, vcc
	v_pk_mul_f32 v[36:37], v[36:37], v[50:51] op_sel_hi:[1,0]
	v_max_f32_e32 v32, 0, v32
	global_store_dwordx4 v[44:45], v[40:43], off sc0 sc1
	v_max_f32_e32 v36, 0, v36
	v_mul_f32_e32 v36, v36, v36
	v_mul_f32_e32 v40, v32, v32
	v_max_f32_e32 v32, 0, v37
	v_mul_f32_e32 v32, v32, v32
	v_cvt_pk_bf16_f32 v32, v36, v32
	ds_read2_b32 v[36:37], v153 offset0:160 offset1:176
	v_pk_mul_f32 v[34:35], v[34:35], v[50:51] op_sel_hi:[1,0]
	v_pk_mul_f32 v[38:39], v[38:39], v[50:51] op_sel_hi:[1,0]
	v_max_f32_e32 v33, 0, v33
	v_max_f32_e32 v34, 0, v34
	v_mul_f32_e32 v41, v33, v33
	v_max_f32_e32 v33, 0, v38
	v_mul_f32_e32 v38, v34, v34
	v_max_f32_e32 v34, 0, v39
	v_max_f32_e32 v35, 0, v35
	v_mul_f32_e32 v33, v33, v33
	v_mul_f32_e32 v34, v34, v34
	v_mul_f32_e32 v35, v35, v35
	s_waitcnt lgkmcnt(0)
; #define PG8_WAIT_V(n) asm volatile("s_waitcnt vmcnt(" #n ")" ::: "memory")
; #define PG8_BAR __builtin_amdgcn_s_barrier()
; template <class Epi>
; __device__ __forceinline__ void gemm_phase(LAS unsigned char* lds, const Gemm g, const Order& S, const Epi& E, const int tid) {
;     ...
;         E(acc, cur, wr, wc, fr, fq);
;         if (!has_next) break;
;     ...
;     PG8_WAIT_V(0);
;     if (wr == 0) PG8_BAR;
;     __device__ __forceinline__ void operator()(const f32x4 (&acc)[2][2][4][2], const Unit& u, int wr, int wc, int fr, int fq) const {
;     ...
;             for (int m = 0; m < 4; ++m) { bf16_t* rowp = O + (size_t)(row0 + ai * HALF + m * 16) * ldc + col0;
;                 float rs = 1.0f; if (RS) rs = rt[u.i * 256 + wr * 64 + fr + ai * HALF + m * 16];
; #pragma unroll
;                 for (int bj = 0; bj < 2; ++bj) { f32x4 v0 = acc[ai][bj][m][0], v1 = acc[ai][bj][m][1];
;                     if (RS) { v0 *= rs; v1 *= rs; }
;                     if (ACT == 1) {
; #pragma unroll
;                         for (int j = 0; j < 4; ++j) { const float a = fmaxf(v0[j], 0.f), b = fmaxf(v1[j], 0.f); v0[j] = a * a; v1[j] = b * b; } }
;                     u32x4 w; w.x = pk2(v0[0], v0[1]); w.y = pk2(v0[2], v0[3]); w.z = pk2(v1[0], v1[1]); w.w = pk2(v1[2], v1[3]);
;                     *(u32x4*)(rowp + bj * HALF) = w; } }
	v_pk_mul_f32 v[24:25], v[24:25], v[36:37] op_sel_hi:[1,0]
	v_lshl_add_u64 v[48:49], v[144:145], 0, s[8:9]
	v_cvt_pk_bf16_f32 v33, v33, v34
	v_cvt_pk_bf16_f32 v34, v40, v41
	v_cvt_pk_bf16_f32 v35, v38, v35
	v_pk_mul_f32 v[28:29], v[28:29], v[36:37] op_sel_hi:[1,0]
	v_pk_mul_f32 v[26:27], v[26:27], v[36:37] op_sel_hi:[1,0]
	v_max_f32_e32 v24, 0, v24
	global_store_dwordx4 v[48:49], v[32:35], off offset:256 sc0 sc1
	v_pk_mul_f32 v[30:31], v[30:31], v[36:37] op_sel_hi:[1,0]
	v_max_f32_e32 v28, 0, v28
	v_mul_f32_e32 v34, v24, v24
	v_max_f32_e32 v24, 0, v29
	v_max_f32_e32 v25, 0, v25
	v_max_f32_e32 v26, 0, v26
	v_mul_f32_e32 v28, v28, v28
	v_mul_f32_e32 v24, v24, v24
	v_mul_f32_e32 v29, v25, v25
	v_max_f32_e32 v25, 0, v30
	v_mul_f32_e32 v30, v26, v26
	v_max_f32_e32 v26, 0, v31
	v_max_f32_e32 v27, 0, v27
	v_mul_f32_e32 v25, v25, v25
	v_mul_f32_e32 v26, v26, v26
	v_mul_f32_e32 v27, v27, v27
	v_cvt_pk_bf16_f32 v24, v28, v24
	v_add_co_u32_e32 v28, vcc, s49, v144
	v_pk_mul_f32 v[18:19], v[18:19], v[36:37] op_sel_hi:[1,0]
	v_pk_mul_f32 v[16:17], v[16:17], v[36:37] op_sel_hi:[1,0]
	v_cvt_pk_bf16_f32 v25, v25, v26
	v_cvt_pk_bf16_f32 v26, v34, v29
	v_cvt_pk_bf16_f32 v27, v30, v27
	v_addc_co_u32_e32 v29, vcc, 0, v145, vcc
	v_pk_mul_f32 v[22:23], v[22:23], v[36:37] op_sel_hi:[1,0]
	v_pk_mul_f32 v[20:21], v[20:21], v[36:37] op_sel_hi:[1,0]
	v_max_f32_e32 v16, 0, v16
	v_max_f32_e32 v17, 0, v17
	v_max_f32_e32 v18, 0, v18
	global_store_dwordx4 v[28:29], v[24:27], off sc0 sc1
	v_max_f32_e32 v20, 0, v20
	v_max_f32_e32 v19, 0, v19
	v_mul_f32_e32 v24, v16, v16
	v_max_f32_e32 v16, 0, v21
	v_mul_f32_e32 v21, v17, v17
	v_max_f32_e32 v17, 0, v22
	v_mul_f32_e32 v22, v18, v18
	v_max_f32_e32 v18, 0, v23
	v_mul_f32_e32 v20, v20, v20
	v_mul_f32_e32 v16, v16, v16
	v_mul_f32_e32 v17, v17, v17
	v_mul_f32_e32 v18, v18, v18
	v_mul_f32_e32 v19, v19, v19
	v_lshl_add_u64 v[32:33], v[144:145], 0, s[10:11]
	v_cvt_pk_bf16_f32 v16, v20, v16
	v_cvt_pk_bf16_f32 v17, v17, v18
	v_cvt_pk_bf16_f32 v18, v24, v21
	v_cvt_pk_bf16_f32 v19, v22, v19
	global_store_dwordx4 v[32:33], v[16:19], off offset:256 sc0 sc1
	s_nop 1
	v_mov_b32_e32 v18, v37
	v_pk_mul_f32 v[8:9], v[8:9], v[18:19] op_sel_hi:[1,0]
	v_pk_mul_f32 v[12:13], v[12:13], v[18:19] op_sel_hi:[1,0]
	v_pk_mul_f32 v[10:11], v[10:11], v[18:19] op_sel_hi:[1,0]
	v_max_f32_e32 v8, 0, v8
	v_pk_mul_f32 v[14:15], v[14:15], v[18:19] op_sel_hi:[1,0]
	v_max_f32_e32 v12, 0, v12
	v_mul_f32_e32 v19, v8, v8
	v_max_f32_e32 v8, 0, v13
	v_max_f32_e32 v9, 0, v9
	v_max_f32_e32 v10, 0, v10
	v_mul_f32_e32 v12, v12, v12
	v_mul_f32_e32 v8, v8, v8
	v_mul_f32_e32 v13, v9, v9
	v_max_f32_e32 v9, 0, v14
	v_mul_f32_e32 v14, v10, v10
	v_max_f32_e32 v10, 0, v15
	v_max_f32_e32 v11, 0, v11
	v_mul_f32_e32 v9, v9, v9
	v_mul_f32_e32 v10, v10, v10
	v_mul_f32_e32 v11, v11, v11
	v_cvt_pk_bf16_f32 v8, v12, v8
	v_add_co_u32_e32 v12, vcc, s50, v144
	v_pk_mul_f32 v[2:3], v[2:3], v[18:19] op_sel_hi:[1,0]
	v_pk_mul_f32 v[0:1], v[0:1], v[18:19] op_sel_hi:[1,0]
	v_cvt_pk_bf16_f32 v9, v9, v10
	v_cvt_pk_bf16_f32 v10, v19, v13
	v_cvt_pk_bf16_f32 v11, v14, v11
	v_addc_co_u32_e32 v13, vcc, 0, v145, vcc
	v_pk_mul_f32 v[6:7], v[6:7], v[18:19] op_sel_hi:[1,0]
	v_pk_mul_f32 v[4:5], v[4:5], v[18:19] op_sel_hi:[1,0]
	v_max_f32_e32 v0, 0, v0
	v_max_f32_e32 v1, 0, v1
	v_max_f32_e32 v2, 0, v2
	global_store_dwordx4 v[12:13], v[8:11], off sc0 sc1
	v_max_f32_e32 v4, 0, v4
	v_max_f32_e32 v3, 0, v3
	v_mul_f32_e32 v8, v0, v0
	v_max_f32_e32 v0, 0, v5
	v_mul_f32_e32 v5, v1, v1
	v_max_f32_e32 v1, 0, v6
	v_mul_f32_e32 v6, v2, v2
	v_max_f32_e32 v2, 0, v7
	v_mul_f32_e32 v4, v4, v4
	v_mul_f32_e32 v0, v0, v0
	v_mul_f32_e32 v1, v1, v1
	v_mul_f32_e32 v2, v2, v2
	v_mul_f32_e32 v3, v3, v3
	v_lshl_add_u64 v[16:17], v[144:145], 0, s[12:13]
	v_cvt_pk_bf16_f32 v0, v4, v0
	v_cvt_pk_bf16_f32 v1, v1, v2
	v_cvt_pk_bf16_f32 v2, v8, v5
	v_cvt_pk_bf16_f32 v3, v6, v3
	s_and_b64 vcc, exec, s[0:1]
	global_store_dwordx4 v[16:17], v[0:3], off offset:256 sc0 sc1
	s_cbranch_vccz .LBB0_651
	s_waitcnt vmcnt(0)
	s_cmpk_gt_u32 s33, 0xff
	s_cbranch_scc1 .LBB0_662
	s_barrier

;     __device__ __forceinline__ void operator()(f32x4 (&acc)[2][2][4][2], const Unit& u, int wr, int wc, int fr, int fq) const {
;     ...
;                 bf16_t* rowp = O + (size_t)row * INC + col0;
; #pragma unroll
;                 for (int bj = 0; bj < 2; ++bj)
; #pragma unroll
;                     for (int n = 0; n < 2; ++n) { const f32x4 v = acc[ai][bj][m][n] * (scale * rt[u.i * 256 + wr * 64 + fr + ai * HALF + m * 16]); u32x2 w; w.x = pk2(v[0], v[1]); w.y = pk2(v[2], v[3]); *(u32x2*)(rowp + bj * HALF + n * 16) = w; }
.LBB0_743:
	ds_read_b32 v20, v154 offset:704
	v_mov_b64_e32 v[18:19], s[72:73]
	v_mad_i64_i32 v[16:17], s[4:5], v16, s43, v[18:19]
	v_lshl_add_u64 v[16:17], v[142:143], 1, v[16:17]
	s_waitcnt lgkmcnt(0)
	v_mul_f32_e32 v18, v145, v20
	v_pk_mul_f32 v[14:15], v[14:15], v[18:19] op_sel_hi:[1,0]
	v_pk_mul_f32 v[12:13], v[12:13], v[18:19] op_sel_hi:[1,0]
	v_pk_mul_f32 v[10:11], v[10:11], v[18:19] op_sel_hi:[1,0]
	v_pk_mul_f32 v[8:9], v[8:9], v[18:19] op_sel_hi:[1,0]
	v_pk_mul_f32 v[6:7], v[6:7], v[18:19] op_sel_hi:[1,0]
	v_pk_mul_f32 v[4:5], v[4:5], v[18:19] op_sel_hi:[1,0]
	v_pk_mul_f32 v[2:3], v[2:3], v[18:19] op_sel_hi:[1,0]
	v_pk_mul_f32 v[0:1], v[0:1], v[18:19] op_sel_hi:[1,0]
	v_cvt_pk_bf16_f32 v12, v12, v13
	v_cvt_pk_bf16_f32 v13, v14, v15
	v_cvt_pk_bf16_f32 v8, v8, v9
	v_cvt_pk_bf16_f32 v9, v10, v11
	v_cvt_pk_bf16_f32 v4, v4, v5
	v_cvt_pk_bf16_f32 v5, v6, v7
	v_cvt_pk_bf16_f32 v0, v0, v1
	v_cvt_pk_bf16_f32 v1, v2, v3
	s_and_b64 vcc, exec, s[0:1]
	s_mov_b32 s46, s45
	s_mov_b32 s47, s12
	s_mov_b32 s4, s10
	s_mov_b64 s[20:21], s[16:17]
	s_mov_b64 s[18:19], s[14:15]
	s_nop 1
	v_permlane16_swap_b32_e32 v12, v8
	v_permlane16_swap_b32_e32 v13, v9
	v_permlane16_swap_b32_e32 v4, v0
	v_permlane16_swap_b32_e32 v5, v1
	v_mov_b32_e32 v14, v8
	v_mov_b32_e32 v15, v9
	v_mov_b32_e32 v6, v0
	v_mov_b32_e32 v7, v1
	v_lshl_add_u64 v[246:247], v[16:17], 0, v[244:245]
	global_store_dwordx4 v[246:247], v[12:15], off sc0 sc1
	global_store_dwordx4 v[246:247], v[4:7], off offset:256 sc0 sc1
	s_nop 1
	s_cbranch_vccnz .LBB0_764

;     __device__ __forceinline__ void operator()(f32x4 (&acc)[2][2][4][2], const Unit& u, int wr, int wc, int fr, int fq) const {
;         const int row0 = u.pm * BM + wr * 64 + fr, col0 = u.pn * BM + wc * 32 + 4 * fq;
;         const int sec = u.pn >> 3;
;         const float scale = (sec == 0) ? 0.08838834764831845f : 1.0f;
; #pragma unroll
;         for (int ai = 0; ai < 2; ++ai)
; #pragma unroll
;             for (int m = 0; m < 4; ++m) {
;                 const int row = row0 + ai * HALF + m * 16;
;                 if (sec < 2 && wc == 0) {
;                     const f32x4 t0 = *(const f32x4*)(tab + (size_t)row * 32 + 8 * fq), t1 = *(const f32x4*)(tab + (size_t)row * 32 + 8 * fq + 4);
;                     const float cs[4] = {t0[0], t0[2], t1[0], t1[2]}, sn[4] = {t0[1], t0[3], t1[1], t1[3]};
; #pragma unroll
;                     for (int bj = 0; bj < 2; ++bj)
; #pragma unroll
;                         for (int j = 0; j < 4; ++j) { const float a = acc[ai][bj][m][0][j], b = acc[ai][bj][m][1][j];
;                             acc[ai][bj][m][0][j] = a * cs[j] - b * sn[j]; acc[ai][bj][m][1][j] = b * cs[j] + a * sn[j]; }
;                 }
;                 bf16_t* rowp = O + (size_t)row * INC + col0;
; #pragma unroll
;                 for (int bj = 0; bj < 2; ++bj)
; #pragma unroll
;                     for (int n = 0; n < 2; ++n) { const f32x4 v = acc[ai][bj][m][n] * (scale * rt[u.i * 256 + wr * 64 + fr + ai * HALF + m * 16]); u32x2 w; w.x = pk2(v[0], v[1]); w.y = pk2(v[2], v[3]); *(u32x2*)(rowp + bj * HALF + n * 16) = w; }
.LBB0_750:
	s_cmp_lt_u32 s47, 8
	s_cselect_b64 vcc, -1, 0
	s_lshl_b32 s11, s46, 10
	v_add_u32_e32 v154, s11, v149
	ds_read_b32 v155, v154
	v_cndmask_b32_e32 v145, 1.0, v153, vcc
	v_lshl_or_b32 v142, s47, 8, v148
	v_mov_b64_e32 v[156:157], s[72:73]
	v_ashrrev_i32_e32 v143, 31, v142
	s_waitcnt lgkmcnt(0)
	v_mul_f32_e32 v158, v145, v155
	v_mad_i64_i32 v[156:157], s[18:19], v144, s43, v[156:157]
	v_pk_mul_f32 v[114:115], v[114:115], v[158:159] op_sel_hi:[1,0]
	v_pk_mul_f32 v[112:113], v[112:113], v[158:159] op_sel_hi:[1,0]
	v_lshl_add_u64 v[156:157], v[142:143], 1, v[156:157]
	v_cvt_pk_bf16_f32 v112, v112, v113
	v_cvt_pk_bf16_f32 v113, v114, v115
	v_pk_mul_f32 v[126:127], v[126:127], v[158:159] op_sel_hi:[1,0]
	v_pk_mul_f32 v[124:125], v[124:125], v[158:159] op_sel_hi:[1,0]
	v_pk_mul_f32 v[122:123], v[122:123], v[158:159] op_sel_hi:[1,0]
	v_pk_mul_f32 v[120:121], v[120:121], v[158:159] op_sel_hi:[1,0]
	v_pk_mul_f32 v[118:119], v[118:119], v[158:159] op_sel_hi:[1,0]
	v_pk_mul_f32 v[116:117], v[116:117], v[158:159] op_sel_hi:[1,0]
	v_cvt_pk_bf16_f32 v124, v124, v125
	v_cvt_pk_bf16_f32 v125, v126, v127
	v_cvt_pk_bf16_f32 v120, v120, v121
	v_cvt_pk_bf16_f32 v121, v122, v123
	v_cvt_pk_bf16_f32 v116, v116, v117
	v_cvt_pk_bf16_f32 v117, v118, v119
	s_and_b64 vcc, exec, s[4:5]
	s_nop 1
	v_permlane16_swap_b32_e32 v124, v120
	v_permlane16_swap_b32_e32 v125, v121
	v_permlane16_swap_b32_e32 v116, v112
	v_permlane16_swap_b32_e32 v117, v113
	v_mov_b32_e32 v126, v120
	v_mov_b32_e32 v127, v121
	v_mov_b32_e32 v118, v112
	v_mov_b32_e32 v119, v113
	v_lshl_add_u64 v[246:247], v[156:157], 0, v[244:245]
	global_store_dwordx4 v[246:247], v[124:127], off sc0 sc1
	global_store_dwordx4 v[246:247], v[116:119], off offset:256 sc0 sc1
	v_or_b32_e32 v112, 16, v144
	v_ashrrev_i32_e32 v113, 31, v112
	s_cbranch_vccnz .LBB0_752
	s_waitcnt vmcnt(14)
	v_mov_b32_e32 v114, v186
	v_mov_b32_e32 v115, v187
	v_mov_b32_e32 v116, v188
	v_mov_b32_e32 v117, v189
	v_mov_b32_e32 v118, v190
	v_mov_b32_e32 v119, v191
	v_mov_b32_e32 v120, v192
	v_mov_b32_e32 v121, v193
	v_mov_b32_e32 v122, v114
	v_mov_b32_e32 v123, v116
	v_mov_b32_e32 v116, v115
	v_mul_f32_e32 v114, v110, v118
	v_mul_f32_e32 v124, v106, v119
	v_mul_f32_e32 v126, v106, v118
	v_mul_f32_e32 v156, v110, v119
	v_mov_b32_e32 v106, v111
	v_mov_b32_e32 v110, v107
	v_mul_f32_e32 v158, v102, v118
	v_mul_f32_e32 v160, v98, v119
	v_mul_f32_e32 v118, v98, v118
	v_mul_f32_e32 v162, v102, v119
	v_mov_b32_e32 v98, v103
	v_mov_b32_e32 v102, v99
	v_pk_mul_f32 v[164:165], v[104:105], v[116:117]
	v_pk_mul_f32 v[104:105], v[104:105], v[122:123]
	v_pk_mul_f32 v[106:107], v[106:107], v[120:121]
	v_pk_mul_f32 v[110:111], v[110:111], v[120:121]
	v_pk_mul_f32 v[166:167], v[96:97], v[116:117]
	v_pk_mul_f32 v[98:99], v[98:99], v[120:121]
	v_pk_mul_f32 v[102:103], v[102:103], v[120:121]
	v_pk_mul_f32 v[96:97], v[96:97], v[122:123]
	v_mov_b32_e32 v115, v106
	v_mov_b32_e32 v125, v107
	v_pk_fma_f32 v[120:121], v[108:109], v[122:123], v[164:165] neg_lo:[0,0,1] neg_hi:[0,0,1]
	v_mov_b32_e32 v157, v111
	v_mov_b32_e32 v127, v110
	v_pk_fma_f32 v[104:105], v[108:109], v[116:117], v[104:105]
	v_mov_b32_e32 v159, v98
	v_mov_b32_e32 v161, v99
	v_pk_fma_f32 v[108:109], v[100:101], v[122:123], v[166:167] neg_lo:[0,0,1] neg_hi:[0,0,1]
	v_mov_b32_e32 v163, v103
	v_mov_b32_e32 v119, v102
	v_pk_fma_f32 v[96:97], v[100:101], v[116:117], v[96:97]
	v_pk_add_f32 v[110:111], v[114:115], v[124:125] neg_lo:[0,1] neg_hi:[0,1]
	v_pk_add_f32 v[106:107], v[156:157], v[126:127]
	v_pk_add_f32 v[102:103], v[158:159], v[160:161] neg_lo:[0,1] neg_hi:[0,1]
	v_pk_add_f32 v[98:99], v[162:163], v[118:119]
	v_mov_b32_e32 v100, v108
	v_mov_b32_e32 v101, v109
	v_mov_b32_e32 v108, v120
	v_mov_b32_e32 v109, v121
.LBB0_752:
	ds_read_b32 v116, v154 offset:64
	v_mov_b64_e32 v[114:115], s[72:73]
	v_mad_i64_i32 v[112:113], s[18:19], v112, s43, v[114:115]
	v_lshl_add_u64 v[112:113], v[142:143], 1, v[112:113]
	s_waitcnt lgkmcnt(0)
	v_mul_f32_e32 v114, v145, v116
	v_pk_mul_f32 v[98:99], v[98:99], v[114:115] op_sel_hi:[1,0]
	v_pk_mul_f32 v[96:97], v[96:97], v[114:115] op_sel_hi:[1,0]
	v_pk_mul_f32 v[110:111], v[110:111], v[114:115] op_sel_hi:[1,0]
	v_cvt_pk_bf16_f32 v96, v96, v97
	v_cvt_pk_bf16_f32 v97, v98, v99
	v_pk_mul_f32 v[108:109], v[108:109], v[114:115] op_sel_hi:[1,0]
	v_pk_mul_f32 v[106:107], v[106:107], v[114:115] op_sel_hi:[1,0]
	v_pk_mul_f32 v[104:105], v[104:105], v[114:115] op_sel_hi:[1,0]
	v_pk_mul_f32 v[102:103], v[102:103], v[114:115] op_sel_hi:[1,0]
	v_pk_mul_f32 v[100:101], v[100:101], v[114:115] op_sel_hi:[1,0]
	v_cvt_pk_bf16_f32 v108, v108, v109
	v_cvt_pk_bf16_f32 v109, v110, v111
	v_cvt_pk_bf16_f32 v104, v104, v105
	v_cvt_pk_bf16_f32 v105, v106, v107
	v_cvt_pk_bf16_f32 v100, v100, v101
	v_cvt_pk_bf16_f32 v101, v102, v103
	s_and_b64 vcc, exec, s[4:5]
	s_nop 1
	v_permlane16_swap_b32_e32 v108, v104
	v_permlane16_swap_b32_e32 v109, v105
	v_permlane16_swap_b32_e32 v100, v96
	v_permlane16_swap_b32_e32 v101, v97
	v_mov_b32_e32 v110, v104
	v_mov_b32_e32 v111, v105
	v_mov_b32_e32 v102, v96
	v_mov_b32_e32 v103, v97
	v_lshl_add_u64 v[246:247], v[112:113], 0, v[244:245]
	global_store_dwordx4 v[246:247], v[108:111], off sc0 sc1
	global_store_dwordx4 v[246:247], v[100:103], off offset:256 sc0 sc1
	v_or_b32_e32 v96, 32, v144
	v_ashrrev_i32_e32 v97, 31, v96
	s_cbranch_vccnz .LBB0_754
;     __device__ __forceinline__ void operator()(f32x4 (&acc)[2][2][4][2], const Unit& u, int wr, int wc, int fr, int fq) const {
;     ...
;                 if (sec < 2 && wc == 0) {
;                     const f32x4 t0 = *(const f32x4*)(tab + (size_t)row * 32 + 8 * fq), t1 = *(const f32x4*)(tab + (size_t)row * 32 + 8 * fq + 4);
;                     const float cs[4] = {t0[0], t0[2], t1[0], t1[2]}, sn[4] = {t0[1], t0[3], t1[1], t1[3]};
; #pragma unroll
;                     for (int bj = 0; bj < 2; ++bj)
; #pragma unroll
;                         for (int j = 0; j < 4; ++j) { const float a = acc[ai][bj][m][0][j], b = acc[ai][bj][m][1][j];
;                             acc[ai][bj][m][0][j] = a * cs[j] - b * sn[j]; acc[ai][bj][m][1][j] = b * cs[j] + a * sn[j]; }
;                 }
;                 bf16_t* rowp = O + (size_t)row * INC + col0;
; #pragma unroll
;                 for (int bj = 0; bj < 2; ++bj)
; #pragma unroll
;                     for (int n = 0; n < 2; ++n) { const f32x4 v = acc[ai][bj][m][n] * (scale * rt[u.i * 256 + wr * 64 + fr + ai * HALF + m * 16]); u32x2 w; w.x = pk2(v[0], v[1]); w.y = pk2(v[2], v[3]); *(u32x2*)(rowp + bj * HALF + n * 16) = w; }
	s_waitcnt vmcnt(14)
	v_mov_b32_e32 v98, v194
	v_mov_b32_e32 v99, v195
	v_mov_b32_e32 v100, v196
	v_mov_b32_e32 v101, v197
	v_mov_b32_e32 v102, v198
	v_mov_b32_e32 v103, v199
	v_mov_b32_e32 v104, v200
	v_mov_b32_e32 v105, v201
	v_mov_b32_e32 v106, v98
	v_mov_b32_e32 v107, v100
	v_mov_b32_e32 v100, v99
	v_mul_f32_e32 v98, v94, v102
	v_mul_f32_e32 v108, v90, v103
	v_mul_f32_e32 v110, v90, v102
	v_mul_f32_e32 v112, v94, v103
	v_mov_b32_e32 v90, v95
	v_mov_b32_e32 v94, v91
	v_mul_f32_e32 v114, v86, v102
	v_mul_f32_e32 v116, v82, v103
	v_mul_f32_e32 v102, v82, v102
	v_mul_f32_e32 v118, v86, v103
	v_mov_b32_e32 v82, v87
	v_mov_b32_e32 v86, v83
	v_pk_mul_f32 v[120:121], v[88:89], v[100:101]
	v_pk_mul_f32 v[88:89], v[88:89], v[106:107]
	v_pk_mul_f32 v[90:91], v[90:91], v[104:105]
	v_pk_mul_f32 v[94:95], v[94:95], v[104:105]
	v_pk_mul_f32 v[122:123], v[80:81], v[100:101]
	v_pk_mul_f32 v[82:83], v[82:83], v[104:105]
	v_pk_mul_f32 v[86:87], v[86:87], v[104:105]
	v_pk_mul_f32 v[80:81], v[80:81], v[106:107]
	v_mov_b32_e32 v99, v90
	v_mov_b32_e32 v109, v91
	v_pk_fma_f32 v[104:105], v[92:93], v[106:107], v[120:121] neg_lo:[0,0,1] neg_hi:[0,0,1]
	v_mov_b32_e32 v113, v95
	v_mov_b32_e32 v111, v94
	v_pk_fma_f32 v[88:89], v[92:93], v[100:101], v[88:89]
	v_mov_b32_e32 v115, v82
	v_mov_b32_e32 v117, v83
	v_pk_fma_f32 v[92:93], v[84:85], v[106:107], v[122:123] neg_lo:[0,0,1] neg_hi:[0,0,1]
	v_mov_b32_e32 v119, v87
	v_mov_b32_e32 v103, v86
	v_pk_fma_f32 v[80:81], v[84:85], v[100:101], v[80:81]
	v_pk_add_f32 v[94:95], v[98:99], v[108:109] neg_lo:[0,1] neg_hi:[0,1]
	v_pk_add_f32 v[90:91], v[112:113], v[110:111]
	v_pk_add_f32 v[86:87], v[114:115], v[116:117] neg_lo:[0,1] neg_hi:[0,1]
	v_pk_add_f32 v[82:83], v[118:119], v[102:103]
	v_mov_b32_e32 v84, v92
	v_mov_b32_e32 v85, v93
	v_mov_b32_e32 v92, v104
	v_mov_b32_e32 v93, v105
.LBB0_754:
	ds_read_b32 v100, v154 offset:128
	v_mov_b64_e32 v[98:99], s[72:73]
	v_mad_i64_i32 v[96:97], s[18:19], v96, s43, v[98:99]
	v_lshl_add_u64 v[96:97], v[142:143], 1, v[96:97]
	s_waitcnt lgkmcnt(0)
	v_mul_f32_e32 v98, v145, v100
	v_pk_mul_f32 v[82:83], v[82:83], v[98:99] op_sel_hi:[1,0]
	v_pk_mul_f32 v[80:81], v[80:81], v[98:99] op_sel_hi:[1,0]
	v_pk_mul_f32 v[94:95], v[94:95], v[98:99] op_sel_hi:[1,0]
	v_cvt_pk_bf16_f32 v80, v80, v81
	v_cvt_pk_bf16_f32 v81, v82, v83
	v_pk_mul_f32 v[92:93], v[92:93], v[98:99] op_sel_hi:[1,0]
	v_pk_mul_f32 v[90:91], v[90:91], v[98:99] op_sel_hi:[1,0]
	v_pk_mul_f32 v[88:89], v[88:89], v[98:99] op_sel_hi:[1,0]
	v_pk_mul_f32 v[86:87], v[86:87], v[98:99] op_sel_hi:[1,0]
	v_pk_mul_f32 v[84:85], v[84:85], v[98:99] op_sel_hi:[1,0]
	v_cvt_pk_bf16_f32 v92, v92, v93
	v_cvt_pk_bf16_f32 v93, v94, v95
	v_cvt_pk_bf16_f32 v88, v88, v89
	v_cvt_pk_bf16_f32 v89, v90, v91
	v_cvt_pk_bf16_f32 v84, v84, v85
	v_cvt_pk_bf16_f32 v85, v86, v87
	s_and_b64 vcc, exec, s[4:5]
	s_nop 1
	v_permlane16_swap_b32_e32 v92, v88
	v_permlane16_swap_b32_e32 v93, v89
	v_permlane16_swap_b32_e32 v84, v80
	v_permlane16_swap_b32_e32 v85, v81
	v_mov_b32_e32 v94, v88
	v_mov_b32_e32 v95, v89
	v_mov_b32_e32 v86, v80
	v_mov_b32_e32 v87, v81
	v_lshl_add_u64 v[246:247], v[96:97], 0, v[244:245]
	global_store_dwordx4 v[246:247], v[92:95], off sc0 sc1
	global_store_dwordx4 v[246:247], v[84:87], off offset:256 sc0 sc1
	v_or_b32_e32 v80, 48, v144
	v_ashrrev_i32_e32 v81, 31, v80
	s_cbranch_vccnz .LBB0_756
	s_waitcnt vmcnt(14)
	v_mov_b32_e32 v82, v202
	v_mov_b32_e32 v83, v203
	v_mov_b32_e32 v84, v204
	v_mov_b32_e32 v85, v205
	v_mov_b32_e32 v86, v206
	v_mov_b32_e32 v87, v207
	v_mov_b32_e32 v88, v208
	v_mov_b32_e32 v89, v209
	v_mov_b32_e32 v90, v82
	v_mov_b32_e32 v91, v84
	v_mov_b32_e32 v84, v83
	v_mul_f32_e32 v82, v78, v86
	v_mul_f32_e32 v92, v74, v87
	v_mul_f32_e32 v94, v74, v86
	v_mul_f32_e32 v96, v78, v87
	v_mov_b32_e32 v74, v79
	v_mov_b32_e32 v78, v75
	v_mul_f32_e32 v98, v70, v86
	v_mul_f32_e32 v100, v66, v87
	v_mul_f32_e32 v86, v66, v86
	v_mul_f32_e32 v102, v70, v87
	v_mov_b32_e32 v66, v71
	v_mov_b32_e32 v70, v67
	v_pk_mul_f32 v[104:105], v[72:73], v[84:85]
	v_pk_mul_f32 v[72:73], v[72:73], v[90:91]
	v_pk_mul_f32 v[74:75], v[74:75], v[88:89]
	v_pk_mul_f32 v[78:79], v[78:79], v[88:89]
	v_pk_mul_f32 v[106:107], v[64:65], v[84:85]
	v_pk_mul_f32 v[66:67], v[66:67], v[88:89]
	v_pk_mul_f32 v[70:71], v[70:71], v[88:89]
	v_pk_mul_f32 v[64:65], v[64:65], v[90:91]
	v_mov_b32_e32 v83, v74
	v_mov_b32_e32 v93, v75
	v_pk_fma_f32 v[88:89], v[76:77], v[90:91], v[104:105] neg_lo:[0,0,1] neg_hi:[0,0,1]
	v_mov_b32_e32 v97, v79
	v_mov_b32_e32 v95, v78
	v_pk_fma_f32 v[72:73], v[76:77], v[84:85], v[72:73]
	v_mov_b32_e32 v99, v66
	v_mov_b32_e32 v101, v67
	v_pk_fma_f32 v[76:77], v[68:69], v[90:91], v[106:107] neg_lo:[0,0,1] neg_hi:[0,0,1]
	v_mov_b32_e32 v103, v71
	v_mov_b32_e32 v87, v70
	v_pk_fma_f32 v[64:65], v[68:69], v[84:85], v[64:65]
	v_pk_add_f32 v[78:79], v[82:83], v[92:93] neg_lo:[0,1] neg_hi:[0,1]
	v_pk_add_f32 v[74:75], v[96:97], v[94:95]
	v_pk_add_f32 v[70:71], v[98:99], v[100:101] neg_lo:[0,1] neg_hi:[0,1]
	v_pk_add_f32 v[66:67], v[102:103], v[86:87]
	v_mov_b32_e32 v68, v76
	v_mov_b32_e32 v69, v77
	v_mov_b32_e32 v76, v88
	v_mov_b32_e32 v77, v89
;     __device__ __forceinline__ void operator()(f32x4 (&acc)[2][2][4][2], const Unit& u, int wr, int wc, int fr, int fq) const {
;     ...
;                 if (sec < 2 && wc == 0) {
;                     const f32x4 t0 = *(const f32x4*)(tab + (size_t)row * 32 + 8 * fq), t1 = *(const f32x4*)(tab + (size_t)row * 32 + 8 * fq + 4);
;                     const float cs[4] = {t0[0], t0[2], t1[0], t1[2]}, sn[4] = {t0[1], t0[3], t1[1], t1[3]};
; #pragma unroll
;                     for (int bj = 0; bj < 2; ++bj)
; #pragma unroll
;                         for (int j = 0; j < 4; ++j) { const float a = acc[ai][bj][m][0][j], b = acc[ai][bj][m][1][j];
;                             acc[ai][bj][m][0][j] = a * cs[j] - b * sn[j]; acc[ai][bj][m][1][j] = b * cs[j] + a * sn[j]; }
;                 }
;                 bf16_t* rowp = O + (size_t)row * INC + col0;
; #pragma unroll
;                 for (int bj = 0; bj < 2; ++bj)
; #pragma unroll
;                     for (int n = 0; n < 2; ++n) { const f32x4 v = acc[ai][bj][m][n] * (scale * rt[u.i * 256 + wr * 64 + fr + ai * HALF + m * 16]); u32x2 w; w.x = pk2(v[0], v[1]); w.y = pk2(v[2], v[3]); *(u32x2*)(rowp + bj * HALF + n * 16) = w; }
.LBB0_756:
	ds_read_b32 v84, v154 offset:192
	v_mov_b64_e32 v[82:83], s[72:73]
	v_mad_i64_i32 v[80:81], s[18:19], v80, s43, v[82:83]
	v_lshl_add_u64 v[80:81], v[142:143], 1, v[80:81]
	s_waitcnt lgkmcnt(0)
	v_mul_f32_e32 v82, v145, v84
	v_pk_mul_f32 v[66:67], v[66:67], v[82:83] op_sel_hi:[1,0]
	v_pk_mul_f32 v[64:65], v[64:65], v[82:83] op_sel_hi:[1,0]
	v_pk_mul_f32 v[78:79], v[78:79], v[82:83] op_sel_hi:[1,0]
	v_cvt_pk_bf16_f32 v64, v64, v65
	v_cvt_pk_bf16_f32 v65, v66, v67
	v_pk_mul_f32 v[76:77], v[76:77], v[82:83] op_sel_hi:[1,0]
	v_pk_mul_f32 v[74:75], v[74:75], v[82:83] op_sel_hi:[1,0]
	v_pk_mul_f32 v[72:73], v[72:73], v[82:83] op_sel_hi:[1,0]
	v_pk_mul_f32 v[70:71], v[70:71], v[82:83] op_sel_hi:[1,0]
	v_pk_mul_f32 v[68:69], v[68:69], v[82:83] op_sel_hi:[1,0]
	v_cvt_pk_bf16_f32 v76, v76, v77
	v_cvt_pk_bf16_f32 v77, v78, v79
	v_cvt_pk_bf16_f32 v72, v72, v73
	v_cvt_pk_bf16_f32 v73, v74, v75
	v_cvt_pk_bf16_f32 v68, v68, v69
	v_cvt_pk_bf16_f32 v69, v70, v71
	s_and_b64 vcc, exec, s[4:5]
	s_nop 1
	v_permlane16_swap_b32_e32 v76, v72
	v_permlane16_swap_b32_e32 v77, v73
	v_permlane16_swap_b32_e32 v68, v64
	v_permlane16_swap_b32_e32 v69, v65
	v_mov_b32_e32 v78, v72
	v_mov_b32_e32 v79, v73
	v_mov_b32_e32 v70, v64
	v_mov_b32_e32 v71, v65
	v_lshl_add_u64 v[246:247], v[80:81], 0, v[244:245]
	global_store_dwordx4 v[246:247], v[76:79], off sc0 sc1
	global_store_dwordx4 v[246:247], v[68:71], off offset:256 sc0 sc1
	v_add_u32_e32 v64, 0x80, v144
	v_ashrrev_i32_e32 v65, 31, v64
	s_cbranch_vccnz .LBB0_758
	s_waitcnt vmcnt(14)
	v_mov_b32_e32 v66, v210
	v_mov_b32_e32 v67, v211
	v_mov_b32_e32 v68, v212
	v_mov_b32_e32 v69, v213
	v_mov_b32_e32 v70, v214
	v_mov_b32_e32 v71, v215
	v_mov_b32_e32 v72, v216
	v_mov_b32_e32 v73, v217
	v_mov_b32_e32 v74, v66
	v_mov_b32_e32 v75, v68
	v_mov_b32_e32 v68, v67
	v_mul_f32_e32 v66, v62, v70
	v_mul_f32_e32 v76, v58, v71
	v_mul_f32_e32 v78, v58, v70
	v_mul_f32_e32 v80, v62, v71
	v_mov_b32_e32 v58, v63
	v_mov_b32_e32 v62, v59
	v_mul_f32_e32 v82, v54, v70
	v_mul_f32_e32 v84, v50, v71
	v_mul_f32_e32 v70, v50, v70
	v_mul_f32_e32 v86, v54, v71
	v_mov_b32_e32 v50, v55
	v_mov_b32_e32 v54, v51
	v_pk_mul_f32 v[88:89], v[56:57], v[68:69]
	v_pk_mul_f32 v[56:57], v[56:57], v[74:75]
	v_pk_mul_f32 v[58:59], v[58:59], v[72:73]
	v_pk_mul_f32 v[62:63], v[62:63], v[72:73]
	v_pk_mul_f32 v[90:91], v[48:49], v[68:69]
	v_pk_mul_f32 v[50:51], v[50:51], v[72:73]
	v_pk_mul_f32 v[54:55], v[54:55], v[72:73]
	v_pk_mul_f32 v[48:49], v[48:49], v[74:75]
	v_mov_b32_e32 v67, v58
	v_mov_b32_e32 v77, v59
	v_pk_fma_f32 v[72:73], v[60:61], v[74:75], v[88:89] neg_lo:[0,0,1] neg_hi:[0,0,1]
	v_mov_b32_e32 v81, v63
	v_mov_b32_e32 v79, v62
	v_pk_fma_f32 v[56:57], v[60:61], v[68:69], v[56:57]
	v_mov_b32_e32 v83, v50
	v_mov_b32_e32 v85, v51
	v_pk_fma_f32 v[60:61], v[52:53], v[74:75], v[90:91] neg_lo:[0,0,1] neg_hi:[0,0,1]
	v_mov_b32_e32 v87, v55
	v_mov_b32_e32 v71, v54
	v_pk_fma_f32 v[48:49], v[52:53], v[68:69], v[48:49]
	v_pk_add_f32 v[62:63], v[66:67], v[76:77] neg_lo:[0,1] neg_hi:[0,1]
	v_pk_add_f32 v[58:59], v[80:81], v[78:79]
	v_pk_add_f32 v[54:55], v[82:83], v[84:85] neg_lo:[0,1] neg_hi:[0,1]
	v_pk_add_f32 v[50:51], v[86:87], v[70:71]
	v_mov_b32_e32 v52, v60
	v_mov_b32_e32 v53, v61
	v_mov_b32_e32 v60, v72
	v_mov_b32_e32 v61, v73
.LBB0_758:
	ds_read_b32 v68, v154 offset:512
	v_mov_b64_e32 v[66:67], s[72:73]
	v_mad_i64_i32 v[64:65], s[18:19], v64, s43, v[66:67]
	v_lshl_add_u64 v[64:65], v[142:143], 1, v[64:65]
	s_waitcnt lgkmcnt(0)
	v_mul_f32_e32 v66, v145, v68
	v_pk_mul_f32 v[50:51], v[50:51], v[66:67] op_sel_hi:[1,0]
	v_pk_mul_f32 v[48:49], v[48:49], v[66:67] op_sel_hi:[1,0]
	v_pk_mul_f32 v[62:63], v[62:63], v[66:67] op_sel_hi:[1,0]
	v_cvt_pk_bf16_f32 v48, v48, v49
	v_cvt_pk_bf16_f32 v49, v50, v51
	v_pk_mul_f32 v[60:61], v[60:61], v[66:67] op_sel_hi:[1,0]
	v_pk_mul_f32 v[58:59], v[58:59], v[66:67] op_sel_hi:[1,0]
	v_pk_mul_f32 v[56:57], v[56:57], v[66:67] op_sel_hi:[1,0]
	v_pk_mul_f32 v[54:55], v[54:55], v[66:67] op_sel_hi:[1,0]
	v_pk_mul_f32 v[52:53], v[52:53], v[66:67] op_sel_hi:[1,0]
	v_cvt_pk_bf16_f32 v60, v60, v61
	v_cvt_pk_bf16_f32 v61, v62, v63
	v_cvt_pk_bf16_f32 v56, v56, v57
	v_cvt_pk_bf16_f32 v57, v58, v59
	v_cvt_pk_bf16_f32 v52, v52, v53
	v_cvt_pk_bf16_f32 v53, v54, v55
	s_and_b64 vcc, exec, s[4:5]
	s_nop 1
	v_permlane16_swap_b32_e32 v60, v56
	v_permlane16_swap_b32_e32 v61, v57
	v_permlane16_swap_b32_e32 v52, v48
	v_permlane16_swap_b32_e32 v53, v49
	v_mov_b32_e32 v62, v56
	v_mov_b32_e32 v63, v57
	v_mov_b32_e32 v54, v48
	v_mov_b32_e32 v55, v49
	v_lshl_add_u64 v[246:247], v[64:65], 0, v[244:245]
	global_store_dwordx4 v[246:247], v[60:63], off sc0 sc1
	global_store_dwordx4 v[246:247], v[52:55], off offset:256 sc0 sc1
	v_add_u32_e32 v48, 0x90, v144
	v_ashrrev_i32_e32 v49, 31, v48
	s_cbranch_vccnz .LBB0_760
	s_waitcnt vmcnt(14)
	v_mov_b32_e32 v50, v218
	v_mov_b32_e32 v51, v219
	v_mov_b32_e32 v52, v220
	v_mov_b32_e32 v53, v221
	v_mov_b32_e32 v54, v222
	v_mov_b32_e32 v55, v223
	v_mov_b32_e32 v56, v224
	v_mov_b32_e32 v57, v225
	v_mov_b32_e32 v58, v50
	v_mov_b32_e32 v59, v52
	v_mov_b32_e32 v52, v51
	v_mul_f32_e32 v50, v46, v54
	v_mul_f32_e32 v60, v42, v55
	v_mul_f32_e32 v62, v42, v54
	v_mul_f32_e32 v64, v46, v55
	v_mov_b32_e32 v42, v47
	v_mov_b32_e32 v46, v43
	v_mul_f32_e32 v66, v38, v54
	v_mul_f32_e32 v68, v34, v55
	v_mul_f32_e32 v54, v34, v54
	v_mul_f32_e32 v70, v38, v55
	v_mov_b32_e32 v34, v39
	v_mov_b32_e32 v38, v35
	v_pk_mul_f32 v[72:73], v[40:41], v[52:53]
	v_pk_mul_f32 v[40:41], v[40:41], v[58:59]
	v_pk_mul_f32 v[42:43], v[42:43], v[56:57]
	v_pk_mul_f32 v[46:47], v[46:47], v[56:57]
	v_pk_mul_f32 v[74:75], v[32:33], v[52:53]
	v_pk_mul_f32 v[34:35], v[34:35], v[56:57]
	v_pk_mul_f32 v[38:39], v[38:39], v[56:57]
	v_pk_mul_f32 v[32:33], v[32:33], v[58:59]
	v_mov_b32_e32 v51, v42
	v_mov_b32_e32 v61, v43
	v_pk_fma_f32 v[56:57], v[44:45], v[58:59], v[72:73] neg_lo:[0,0,1] neg_hi:[0,0,1]
	v_mov_b32_e32 v65, v47
	v_mov_b32_e32 v63, v46
	v_pk_fma_f32 v[40:41], v[44:45], v[52:53], v[40:41]
	v_mov_b32_e32 v67, v34
	v_mov_b32_e32 v69, v35
	v_pk_fma_f32 v[44:45], v[36:37], v[58:59], v[74:75] neg_lo:[0,0,1] neg_hi:[0,0,1]
	v_mov_b32_e32 v71, v39
	v_mov_b32_e32 v55, v38
	v_pk_fma_f32 v[32:33], v[36:37], v[52:53], v[32:33]
	v_pk_add_f32 v[46:47], v[50:51], v[60:61] neg_lo:[0,1] neg_hi:[0,1]
	v_pk_add_f32 v[42:43], v[64:65], v[62:63]
	v_pk_add_f32 v[38:39], v[66:67], v[68:69] neg_lo:[0,1] neg_hi:[0,1]
	v_pk_add_f32 v[34:35], v[70:71], v[54:55]
	v_mov_b32_e32 v36, v44
	v_mov_b32_e32 v37, v45
	v_mov_b32_e32 v44, v56
	v_mov_b32_e32 v45, v57
;     __device__ __forceinline__ void operator()(f32x4 (&acc)[2][2][4][2], const Unit& u, int wr, int wc, int fr, int fq) const {
;     ...
;                 if (sec < 2 && wc == 0) {
;                     const f32x4 t0 = *(const f32x4*)(tab + (size_t)row * 32 + 8 * fq), t1 = *(const f32x4*)(tab + (size_t)row * 32 + 8 * fq + 4);
;                     const float cs[4] = {t0[0], t0[2], t1[0], t1[2]}, sn[4] = {t0[1], t0[3], t1[1], t1[3]};
; #pragma unroll
;                     for (int bj = 0; bj < 2; ++bj)
; #pragma unroll
;                         for (int j = 0; j < 4; ++j) { const float a = acc[ai][bj][m][0][j], b = acc[ai][bj][m][1][j];
;                             acc[ai][bj][m][0][j] = a * cs[j] - b * sn[j]; acc[ai][bj][m][1][j] = b * cs[j] + a * sn[j]; }
;                 }
;                 bf16_t* rowp = O + (size_t)row * INC + col0;
; #pragma unroll
;                 for (int bj = 0; bj < 2; ++bj)
; #pragma unroll
;                     for (int n = 0; n < 2; ++n) { const f32x4 v = acc[ai][bj][m][n] * (scale * rt[u.i * 256 + wr * 64 + fr + ai * HALF + m * 16]); u32x2 w; w.x = pk2(v[0], v[1]); w.y = pk2(v[2], v[3]); *(u32x2*)(rowp + bj * HALF + n * 16) = w; }
.LBB0_760:
	ds_read_b32 v52, v154 offset:576
	v_mov_b64_e32 v[50:51], s[72:73]
	v_mad_i64_i32 v[48:49], s[18:19], v48, s43, v[50:51]
	v_lshl_add_u64 v[48:49], v[142:143], 1, v[48:49]
	s_waitcnt lgkmcnt(0)
	v_mul_f32_e32 v50, v145, v52
	v_pk_mul_f32 v[34:35], v[34:35], v[50:51] op_sel_hi:[1,0]
	v_pk_mul_f32 v[32:33], v[32:33], v[50:51] op_sel_hi:[1,0]
	v_pk_mul_f32 v[46:47], v[46:47], v[50:51] op_sel_hi:[1,0]
	v_cvt_pk_bf16_f32 v32, v32, v33
	v_cvt_pk_bf16_f32 v33, v34, v35
	v_pk_mul_f32 v[44:45], v[44:45], v[50:51] op_sel_hi:[1,0]
	v_pk_mul_f32 v[42:43], v[42:43], v[50:51] op_sel_hi:[1,0]
	v_pk_mul_f32 v[40:41], v[40:41], v[50:51] op_sel_hi:[1,0]
	v_pk_mul_f32 v[38:39], v[38:39], v[50:51] op_sel_hi:[1,0]
	v_pk_mul_f32 v[36:37], v[36:37], v[50:51] op_sel_hi:[1,0]
	v_cvt_pk_bf16_f32 v44, v44, v45
	v_cvt_pk_bf16_f32 v45, v46, v47
	v_cvt_pk_bf16_f32 v40, v40, v41
	v_cvt_pk_bf16_f32 v41, v42, v43
	v_cvt_pk_bf16_f32 v36, v36, v37
	v_cvt_pk_bf16_f32 v37, v38, v39
	s_and_b64 vcc, exec, s[4:5]
	s_nop 1
	v_permlane16_swap_b32_e32 v44, v40
	v_permlane16_swap_b32_e32 v45, v41
	v_permlane16_swap_b32_e32 v36, v32
	v_permlane16_swap_b32_e32 v37, v33
	v_mov_b32_e32 v46, v40
	v_mov_b32_e32 v47, v41
	v_mov_b32_e32 v38, v32
	v_mov_b32_e32 v39, v33
	v_lshl_add_u64 v[246:247], v[48:49], 0, v[244:245]
	global_store_dwordx4 v[246:247], v[44:47], off sc0 sc1
	global_store_dwordx4 v[246:247], v[36:39], off offset:256 sc0 sc1
	v_add_u32_e32 v32, 0xa0, v144
	v_ashrrev_i32_e32 v33, 31, v32
	s_cbranch_vccnz .LBB0_762
	s_waitcnt vmcnt(14)
	v_mov_b32_e32 v34, v226
	v_mov_b32_e32 v35, v227
	v_mov_b32_e32 v36, v228
	v_mov_b32_e32 v37, v229
	v_mov_b32_e32 v38, v230
	v_mov_b32_e32 v39, v231
	v_mov_b32_e32 v40, v232
	v_mov_b32_e32 v41, v233
	v_mov_b32_e32 v42, v34
	v_mov_b32_e32 v43, v36
	v_mov_b32_e32 v36, v35
	v_mul_f32_e32 v34, v30, v38
	v_mul_f32_e32 v44, v26, v39
	v_mul_f32_e32 v46, v26, v38
	v_mul_f32_e32 v48, v30, v39
	v_mov_b32_e32 v26, v31
	v_mov_b32_e32 v30, v27
	v_mul_f32_e32 v50, v22, v38
	v_mul_f32_e32 v52, v18, v39
	v_mul_f32_e32 v38, v18, v38
	v_mul_f32_e32 v54, v22, v39
	v_mov_b32_e32 v18, v23
	v_mov_b32_e32 v22, v19
	v_pk_mul_f32 v[56:57], v[24:25], v[36:37]
	v_pk_mul_f32 v[24:25], v[24:25], v[42:43]
	v_pk_mul_f32 v[26:27], v[26:27], v[40:41]
	v_pk_mul_f32 v[30:31], v[30:31], v[40:41]
	v_pk_mul_f32 v[58:59], v[16:17], v[36:37]
	v_pk_mul_f32 v[18:19], v[18:19], v[40:41]
	v_pk_mul_f32 v[22:23], v[22:23], v[40:41]
	v_pk_mul_f32 v[16:17], v[16:17], v[42:43]
	v_mov_b32_e32 v35, v26
	v_mov_b32_e32 v45, v27
	v_pk_fma_f32 v[40:41], v[28:29], v[42:43], v[56:57] neg_lo:[0,0,1] neg_hi:[0,0,1]
	v_mov_b32_e32 v49, v31
	v_mov_b32_e32 v47, v30
	v_pk_fma_f32 v[24:25], v[28:29], v[36:37], v[24:25]
	v_mov_b32_e32 v51, v18
	v_mov_b32_e32 v53, v19
	v_pk_fma_f32 v[28:29], v[20:21], v[42:43], v[58:59] neg_lo:[0,0,1] neg_hi:[0,0,1]
	v_mov_b32_e32 v55, v23
	v_mov_b32_e32 v39, v22
	v_pk_fma_f32 v[16:17], v[20:21], v[36:37], v[16:17]
	v_pk_add_f32 v[30:31], v[34:35], v[44:45] neg_lo:[0,1] neg_hi:[0,1]
	v_pk_add_f32 v[26:27], v[48:49], v[46:47]
	v_pk_add_f32 v[22:23], v[50:51], v[52:53] neg_lo:[0,1] neg_hi:[0,1]
	v_pk_add_f32 v[18:19], v[54:55], v[38:39]
	v_mov_b32_e32 v20, v28
	v_mov_b32_e32 v21, v29
	v_mov_b32_e32 v28, v40
	v_mov_b32_e32 v29, v41
.LBB0_762:
	ds_read_b32 v36, v154 offset:640
	v_mov_b64_e32 v[34:35], s[72:73]
	v_mad_i64_i32 v[32:33], s[18:19], v32, s43, v[34:35]
	v_lshl_add_u64 v[32:33], v[142:143], 1, v[32:33]
	s_waitcnt lgkmcnt(0)
	v_mul_f32_e32 v34, v145, v36
	v_pk_mul_f32 v[18:19], v[18:19], v[34:35] op_sel_hi:[1,0]
	v_pk_mul_f32 v[16:17], v[16:17], v[34:35] op_sel_hi:[1,0]
	v_pk_mul_f32 v[30:31], v[30:31], v[34:35] op_sel_hi:[1,0]
	v_cvt_pk_bf16_f32 v16, v16, v17
	v_cvt_pk_bf16_f32 v17, v18, v19
	v_pk_mul_f32 v[28:29], v[28:29], v[34:35] op_sel_hi:[1,0]
	v_pk_mul_f32 v[26:27], v[26:27], v[34:35] op_sel_hi:[1,0]
	v_pk_mul_f32 v[24:25], v[24:25], v[34:35] op_sel_hi:[1,0]
	v_pk_mul_f32 v[22:23], v[22:23], v[34:35] op_sel_hi:[1,0]
	v_pk_mul_f32 v[20:21], v[20:21], v[34:35] op_sel_hi:[1,0]
	v_cvt_pk_bf16_f32 v28, v28, v29
	v_cvt_pk_bf16_f32 v29, v30, v31
	v_cvt_pk_bf16_f32 v24, v24, v25
	v_cvt_pk_bf16_f32 v25, v26, v27
	v_cvt_pk_bf16_f32 v20, v20, v21
	v_cvt_pk_bf16_f32 v21, v22, v23
	s_and_b64 vcc, exec, s[4:5]
	s_nop 1
	v_permlane16_swap_b32_e32 v28, v24
	v_permlane16_swap_b32_e32 v29, v25
	v_permlane16_swap_b32_e32 v20, v16
	v_permlane16_swap_b32_e32 v21, v17
	v_mov_b32_e32 v30, v24
	v_mov_b32_e32 v31, v25
	v_mov_b32_e32 v22, v16
	v_mov_b32_e32 v23, v17
	v_lshl_add_u64 v[246:247], v[32:33], 0, v[244:245]
	global_store_dwordx4 v[246:247], v[28:31], off sc0 sc1
	global_store_dwordx4 v[246:247], v[20:23], off offset:256 sc0 sc1
	v_add_u32_e32 v16, 0xb0, v144
	v_ashrrev_i32_e32 v17, 31, v16
	s_cbranch_vccnz .LBB0_743
	s_waitcnt vmcnt(14)
	v_mov_b32_e32 v18, v234
	v_mov_b32_e32 v19, v235
	v_mov_b32_e32 v20, v236
	v_mov_b32_e32 v21, v237
	v_mov_b32_e32 v22, v238
	v_mov_b32_e32 v23, v239
	v_mov_b32_e32 v24, v240
	v_mov_b32_e32 v25, v241
	v_mov_b32_e32 v26, v18
	v_mov_b32_e32 v27, v20
	v_mov_b32_e32 v20, v19
	v_mul_f32_e32 v18, v14, v22
	v_mul_f32_e32 v28, v10, v23
	v_mul_f32_e32 v30, v10, v22
	v_mul_f32_e32 v32, v14, v23
	v_mov_b32_e32 v10, v15
	v_mov_b32_e32 v14, v11
	v_mul_f32_e32 v34, v6, v22
	v_mul_f32_e32 v36, v2, v23
	v_mul_f32_e32 v22, v2, v22
	v_mul_f32_e32 v38, v6, v23
	v_mov_b32_e32 v2, v7
	v_mov_b32_e32 v6, v3
	v_pk_mul_f32 v[40:41], v[8:9], v[20:21]
	v_pk_mul_f32 v[8:9], v[8:9], v[26:27]
	v_pk_mul_f32 v[10:11], v[10:11], v[24:25]
	v_pk_mul_f32 v[14:15], v[14:15], v[24:25]
	v_pk_mul_f32 v[42:43], v[0:1], v[20:21]
	v_pk_mul_f32 v[2:3], v[2:3], v[24:25]
	v_pk_mul_f32 v[6:7], v[6:7], v[24:25]
	v_pk_mul_f32 v[0:1], v[0:1], v[26:27]
	v_mov_b32_e32 v19, v10
	v_mov_b32_e32 v29, v11
	v_pk_fma_f32 v[24:25], v[12:13], v[26:27], v[40:41] neg_lo:[0,0,1] neg_hi:[0,0,1]
	v_mov_b32_e32 v33, v15
	v_mov_b32_e32 v31, v14
	v_pk_fma_f32 v[8:9], v[12:13], v[20:21], v[8:9]
	v_mov_b32_e32 v35, v2
	v_mov_b32_e32 v37, v3
	v_pk_fma_f32 v[12:13], v[4:5], v[26:27], v[42:43] neg_lo:[0,0,1] neg_hi:[0,0,1]
	v_mov_b32_e32 v39, v7
	v_mov_b32_e32 v23, v6
	v_pk_fma_f32 v[0:1], v[4:5], v[20:21], v[0:1]
	v_pk_add_f32 v[14:15], v[18:19], v[28:29] neg_lo:[0,1] neg_hi:[0,1]
	v_pk_add_f32 v[10:11], v[32:33], v[30:31]
	v_pk_add_f32 v[6:7], v[34:35], v[36:37] neg_lo:[0,1] neg_hi:[0,1]
	v_pk_add_f32 v[2:3], v[38:39], v[22:23]
	v_mov_b32_e32 v4, v12
	v_mov_b32_e32 v5, v13
	v_mov_b32_e32 v12, v24
	v_mov_b32_e32 v13, v25
	s_branch .LBB0_743

; #define PG8_STAGE(bufoff, gbase, voff) do { _Pragma("unroll") for (int _i = 0; _i < 2; ++_i) \
;         __builtin_amdgcn_global_load_lds((const unsigned*)((const char*)(gbase) + (voff)[_i]), (LAS unsigned*)(lds + (bufoff) + ldsw + _i * 8192), 16, 0, 0); } while (0)
; #define PG8_LDA(dst, b, h) do { _Pragma("unroll") for (int m = 0; m < 4; ++m) _Pragma("unroll") for (int k = 0; k < 2; ++k) dst[m][k] = *(const LAS bf16x8*)(lds + PG8_SA(b, h) + aoff + m * 2048 + k * 1024); } while (0)
; #define PG8_LDB(dst, b, h) do { _Pragma("unroll") for (int n = 0; n < 2; ++n) _Pragma("unroll") for (int k = 0; k < 2; ++k) dst[n][k] = *(const LAS bf16x8*)(lds + PG8_SB(b, h) + boff + n * 2048 + k * 1024); } while (0)
; #define PG8_MMA(ai, bj, At, Bt) do { __builtin_amdgcn_s_setprio(1); _Pragma("unroll") for (int m = 0; m < 4; ++m) _Pragma("unroll") for (int n = 0; n < 2; ++n) _Pragma("unroll") for (int k = 0; k < 2; ++k) \
;         acc[ai][bj][m][n] = __builtin_amdgcn_mfma_f32_16x16x32_bf16(Bt[n][k], At[m][k], acc[ai][bj][m][n], 0, 0, 0); __builtin_amdgcn_s_setprio(0); } while (0)
; #define PG8_WAIT_L(n) asm volatile("s_waitcnt lgkmcnt(" #n ")" ::: "memory")
; #define PG8_BAR __builtin_amdgcn_s_barrier()
; #define PG8_SCHED __builtin_amdgcn_sched_barrier(0)
; template <class Epi>
; __device__ __forceinline__ void gemm_phase(LAS unsigned char* lds, const Gemm g, const Order& S, const Epi& E, const int tid) {
;     ...
;             PG8_LDB(B0, 0, 0); PG8_SCHED; PG8_LDA(At, 0, 0); PG8_STAGE(PG8_SA(1, 1), a1 + hstepA, voffA);
;             PG8_WAIT_L(8); PG8_BAR; PG8_WAIT_L(0); PG8_MMA(0, 0, At, B0); PG8_BAR; PG8_SCHED;
;             PG8_LDB(B1, 0, 1); PG8_STAGE(PG8_SB(0, 0), b2, voffB);
;             PG8_BAR; PG8_WAIT_L(0); PG8_MMA(0, 1, At, B1); PG8_BAR;
;             PG8_LDA(At, 0, 1); PG8_STAGE(PG8_SA(0, 0), a2, voffA);
;             PG8_BAR; PG8_WAIT_L(0); PG8_MMA(1, 0, At, B0); PG8_BAR; PG8_SCHED;
.LBB0_912:
	ds_read_b128 v[154:157], v150
	ds_read_b128 v[158:161], v150 offset:1024
	ds_read_b128 v[162:165], v150 offset:2048
	ds_read_b128 v[166:169], v150 offset:3072
	s_add_u32 s28, s26, 0xfff80080
	s_addc_u32 s29, s27, -1
	s_cmp_eq_u32 s55, 28
	s_cselect_b32 s31, s15, s29
	s_cselect_b32 s30, s50, s28
	s_cselect_b32 s29, s17, s53
	s_cselect_b32 s28, s51, s52
	v_lshl_add_u64 v[144:145], s[26:27], 0, v[136:137]
	s_add_i32 m0, s25, 0xc000
	ds_read_b128 v[170:173], v151
	ds_read_b128 v[174:177], v151 offset:1024
	ds_read_b128 v[178:181], v151 offset:2048
	ds_read_b128 v[182:185], v151 offset:3072
	ds_read_b128 v[186:189], v151 offset:4096
	ds_read_b128 v[190:193], v151 offset:5120
	ds_read_b128 v[194:197], v151 offset:6144
	ds_read_b128 v[198:201], v151 offset:7168
	global_load_lds_dwordx4 v[144:145], off
	v_lshl_add_u64 v[144:145], s[26:27], 0, v[138:139]
	s_add_i32 m0, s25, 0xe000
	s_nop 0
	global_load_lds_dwordx4 v[144:145], off
	s_waitcnt lgkmcnt(8)
	s_barrier
	s_waitcnt lgkmcnt(0)
	s_setprio 1
	s_waitcnt lgkmcnt(0)
	v_mfma_f32_16x16x32_bf16 v[124:127], v[154:157], v[170:173], v[124:127]
	v_mfma_f32_16x16x32_bf16 v[120:123], v[162:165], v[170:173], v[120:123]
	v_mfma_f32_16x16x32_bf16 v[108:111], v[154:157], v[178:181], v[108:111]
	v_mfma_f32_16x16x32_bf16 v[104:107], v[162:165], v[178:181], v[104:107]
	v_mfma_f32_16x16x32_bf16 v[92:95], v[154:157], v[186:189], v[92:95]
	v_mfma_f32_16x16x32_bf16 v[88:91], v[162:165], v[186:189], v[88:91]
	v_mfma_f32_16x16x32_bf16 v[76:79], v[154:157], v[194:197], v[76:79]
	v_mfma_f32_16x16x32_bf16 v[72:75], v[162:165], v[194:197], v[72:75]
	v_mfma_f32_16x16x32_bf16 v[124:127], v[158:161], v[174:177], v[124:127]
	v_mfma_f32_16x16x32_bf16 v[120:123], v[166:169], v[174:177], v[120:123]
	v_mfma_f32_16x16x32_bf16 v[108:111], v[158:161], v[182:185], v[108:111]
	v_mfma_f32_16x16x32_bf16 v[104:107], v[166:169], v[182:185], v[104:107]
	v_mfma_f32_16x16x32_bf16 v[92:95], v[158:161], v[190:193], v[92:95]
	v_mfma_f32_16x16x32_bf16 v[88:91], v[166:169], v[190:193], v[88:91]
	v_mfma_f32_16x16x32_bf16 v[76:79], v[158:161], v[198:201], v[76:79]
	v_mfma_f32_16x16x32_bf16 v[72:75], v[166:169], v[198:201], v[72:75]
	s_setprio 0
	s_barrier
	s_add_i32 s56, s40, s34
	v_lshl_add_u64 v[144:145], s[28:29], 0, v[132:133]
	s_mov_b32 m0, s56
	ds_read_b128 v[202:205], v152
	ds_read_b128 v[206:209], v152 offset:1024
	ds_read_b128 v[210:213], v152 offset:2048
	ds_read_b128 v[214:217], v152 offset:3072
	global_load_lds_dwordx4 v[144:145], off
	v_lshl_add_u64 v[218:219], s[28:29], 0, v[128:129]
	s_add_i32 m0, s56, 0x2000
	s_nop 0
	global_load_lds_dwordx4 v[218:219], off
	s_barrier
	s_waitcnt lgkmcnt(0)
	s_setprio 1
	s_waitcnt lgkmcnt(0)
	v_mfma_f32_16x16x32_bf16 v[116:119], v[202:205], v[170:173], v[116:119]
	v_mfma_f32_16x16x32_bf16 v[112:115], v[210:213], v[170:173], v[112:115]
	v_mfma_f32_16x16x32_bf16 v[100:103], v[202:205], v[178:181], v[100:103]
	v_mfma_f32_16x16x32_bf16 v[96:99], v[210:213], v[178:181], v[96:99]
	v_mfma_f32_16x16x32_bf16 v[84:87], v[202:205], v[186:189], v[84:87]
	v_mfma_f32_16x16x32_bf16 v[80:83], v[210:213], v[186:189], v[80:83]
	v_mfma_f32_16x16x32_bf16 v[68:71], v[202:205], v[194:197], v[68:71]
	v_mfma_f32_16x16x32_bf16 v[64:67], v[210:213], v[194:197], v[64:67]
	v_mfma_f32_16x16x32_bf16 v[116:119], v[206:209], v[174:177], v[116:119]
	v_mfma_f32_16x16x32_bf16 v[112:115], v[214:217], v[174:177], v[112:115]
	v_mfma_f32_16x16x32_bf16 v[100:103], v[206:209], v[182:185], v[100:103]
	v_mfma_f32_16x16x32_bf16 v[96:99], v[214:217], v[182:185], v[96:99]
	v_mfma_f32_16x16x32_bf16 v[84:87], v[206:209], v[190:193], v[84:87]
	v_mfma_f32_16x16x32_bf16 v[80:83], v[214:217], v[190:193], v[80:83]
	v_mfma_f32_16x16x32_bf16 v[68:71], v[206:209], v[198:201], v[68:71]
	v_mfma_f32_16x16x32_bf16 v[64:67], v[214:217], v[198:201], v[64:67]
	s_setprio 0
	s_mov_b32 m0, s25
	v_lshl_add_u64 v[220:221], s[30:31], 0, v[134:135]
	s_barrier
	ds_read_b128 v[170:173], v151 offset:16384
	ds_read_b128 v[174:177], v151 offset:17408
	ds_read_b128 v[178:181], v151 offset:18432
	ds_read_b128 v[182:185], v151 offset:19456
	ds_read_b128 v[186:189], v151 offset:20480
	ds_read_b128 v[190:193], v151 offset:21504
	ds_read_b128 v[194:197], v151 offset:22528
	ds_read_b128 v[198:201], v151 offset:23552
	global_load_lds_dwordx4 v[220:221], off
	v_lshl_add_u64 v[222:223], s[30:31], 0, v[130:131]
	s_mov_b32 m0, s35
	s_nop 0
	global_load_lds_dwordx4 v[222:223], off
	s_barrier
	s_waitcnt lgkmcnt(0)
	s_setprio 1
	s_waitcnt lgkmcnt(0)
	v_mfma_f32_16x16x32_bf16 v[60:63], v[154:157], v[170:173], v[60:63]
	v_mfma_f32_16x16x32_bf16 v[56:59], v[162:165], v[170:173], v[56:59]
	v_mfma_f32_16x16x32_bf16 v[44:47], v[154:157], v[178:181], v[44:47]
	v_mfma_f32_16x16x32_bf16 v[40:43], v[162:165], v[178:181], v[40:43]
	v_mfma_f32_16x16x32_bf16 v[28:31], v[154:157], v[186:189], v[28:31]
	v_mfma_f32_16x16x32_bf16 v[24:27], v[162:165], v[186:189], v[24:27]
	v_mfma_f32_16x16x32_bf16 v[12:15], v[154:157], v[194:197], v[12:15]
	v_mfma_f32_16x16x32_bf16 v[8:11], v[162:165], v[194:197], v[8:11]
	v_mfma_f32_16x16x32_bf16 v[60:63], v[158:161], v[174:177], v[60:63]
	v_mfma_f32_16x16x32_bf16 v[56:59], v[166:169], v[174:177], v[56:59]
	v_mfma_f32_16x16x32_bf16 v[44:47], v[158:161], v[182:185], v[44:47]
	v_mfma_f32_16x16x32_bf16 v[40:43], v[166:169], v[182:185], v[40:43]
	v_mfma_f32_16x16x32_bf16 v[28:31], v[158:161], v[190:193], v[28:31]
	v_mfma_f32_16x16x32_bf16 v[24:27], v[166:169], v[190:193], v[24:27]
	v_mfma_f32_16x16x32_bf16 v[12:15], v[158:161], v[198:201], v[12:15]
	v_mfma_f32_16x16x32_bf16 v[8:11], v[166:169], v[198:201], v[8:11]
	s_setprio 0
	s_barrier
; #define PG8_STAGE(bufoff, gbase, voff) do { _Pragma("unroll") for (int _i = 0; _i < 2; ++_i) \
;         __builtin_amdgcn_global_load_lds((const unsigned*)((const char*)(gbase) + (voff)[_i]), (LAS unsigned*)(lds + (bufoff) + ldsw + _i * 8192), 16, 0, 0); } while (0)
; #define PG8_LDA(dst, b, h) do { _Pragma("unroll") for (int m = 0; m < 4; ++m) _Pragma("unroll") for (int k = 0; k < 2; ++k) dst[m][k] = *(const LAS bf16x8*)(lds + PG8_SA(b, h) + aoff + m * 2048 + k * 1024); } while (0)
; #define PG8_LDB(dst, b, h) do { _Pragma("unroll") for (int n = 0; n < 2; ++n) _Pragma("unroll") for (int k = 0; k < 2; ++k) dst[n][k] = *(const LAS bf16x8*)(lds + PG8_SB(b, h) + boff + n * 2048 + k * 1024); } while (0)
; #define PG8_MMA(ai, bj, At, Bt) do { __builtin_amdgcn_s_setprio(1); _Pragma("unroll") for (int m = 0; m < 4; ++m) _Pragma("unroll") for (int n = 0; n < 2; ++n) _Pragma("unroll") for (int k = 0; k < 2; ++k) \
;         acc[ai][bj][m][n] = __builtin_amdgcn_mfma_f32_16x16x32_bf16(Bt[n][k], At[m][k], acc[ai][bj][m][n], 0, 0, 0); __builtin_amdgcn_s_setprio(0); } while (0)
; #define PG8_WAIT_V(n) asm volatile("s_waitcnt vmcnt(" #n ")" ::: "memory")
; #define PG8_WAIT_L(n) asm volatile("s_waitcnt lgkmcnt(" #n ")" ::: "memory")
; #define PG8_BAR __builtin_amdgcn_s_barrier()
; #define PG8_SCHED __builtin_amdgcn_sched_barrier(0)
; template <class Epi>
; __device__ __forceinline__ void gemm_phase(LAS unsigned char* lds, const Gemm g, const Order& S, const Epi& E, const int tid) {
;     ...
;             PG8_STAGE(PG8_SB(0, 1), b2 + hstepB, voffB);
;             PG8_WAIT_V(6); PG8_BAR; PG8_MMA(1, 1, At, B1); PG8_BAR;
;             PG8_LDB(B0, 1, 0); PG8_SCHED; PG8_LDA(At, 1, 0); PG8_STAGE(PG8_SA(0, 1), a2 + hstepA, voffA);
;             PG8_WAIT_L(8); PG8_BAR; PG8_WAIT_L(0); PG8_MMA(0, 0, At, B0); PG8_BAR; PG8_SCHED;
;             PG8_LDB(B1, 1, 1); PG8_STAGE(PG8_SB(1, 0), b3, voffB);
;             PG8_BAR; PG8_WAIT_L(0); PG8_MMA(0, 1, At, B1); PG8_BAR;
;             PG8_LDA(At, 1, 1); PG8_STAGE(PG8_SA(1, 0), a3, voffA);
	s_add_u32 s56, s28, 0x80000
	s_addc_u32 s57, s29, 0
	s_add_i32 s58, s41, s34
	v_lshl_add_u64 v[154:155], s[56:57], 0, v[132:133]
	s_mov_b32 m0, s58
	s_nop 0
	global_load_lds_dwordx4 v[154:155], off
	v_lshl_add_u64 v[154:155], s[56:57], 0, v[128:129]
	s_add_i32 m0, s58, 0x2000
	s_nop 0
	global_load_lds_dwordx4 v[154:155], off
	s_waitcnt vmcnt(6)
	s_barrier
	s_setprio 1
	v_mfma_f32_16x16x32_bf16 v[52:55], v[202:205], v[170:173], v[52:55]
	v_mfma_f32_16x16x32_bf16 v[48:51], v[210:213], v[170:173], v[48:51]
	v_mfma_f32_16x16x32_bf16 v[36:39], v[202:205], v[178:181], v[36:39]
	v_mfma_f32_16x16x32_bf16 v[32:35], v[210:213], v[178:181], v[32:35]
	v_mfma_f32_16x16x32_bf16 v[20:23], v[202:205], v[186:189], v[20:23]
	v_mfma_f32_16x16x32_bf16 v[16:19], v[210:213], v[186:189], v[16:19]
	v_mfma_f32_16x16x32_bf16 v[4:7], v[202:205], v[194:197], v[4:7]
	v_mfma_f32_16x16x32_bf16 v[0:3], v[210:213], v[194:197], v[0:3]
	v_mfma_f32_16x16x32_bf16 v[52:55], v[206:209], v[174:177], v[52:55]
	v_mfma_f32_16x16x32_bf16 v[48:51], v[214:217], v[174:177], v[48:51]
	v_mfma_f32_16x16x32_bf16 v[36:39], v[206:209], v[182:185], v[36:39]
	v_mfma_f32_16x16x32_bf16 v[32:35], v[214:217], v[182:185], v[32:35]
	v_mfma_f32_16x16x32_bf16 v[20:23], v[206:209], v[190:193], v[20:23]
	v_mfma_f32_16x16x32_bf16 v[16:19], v[214:217], v[190:193], v[16:19]
	v_mfma_f32_16x16x32_bf16 v[4:7], v[206:209], v[198:201], v[4:7]
	v_mfma_f32_16x16x32_bf16 v[0:3], v[214:217], v[198:201], v[0:3]
	s_setprio 0
	s_add_i32 s56, 0, 0x18000
	v_add_u32_e32 v153, s56, v147
	s_barrier
	ds_read_b128 v[154:157], v153
	ds_read_b128 v[158:161], v153 offset:1024
	ds_read_b128 v[162:165], v153 offset:2048
	ds_read_b128 v[166:169], v153 offset:3072
	s_add_u32 s30, s30, 0x80000
	s_addc_u32 s31, s31, 0
	s_mov_b32 m0, s36
	v_lshl_add_u64 v[202:203], s[30:31], 0, v[134:135]
	ds_read_b128 v[170:173], v151 offset:32768
	ds_read_b128 v[174:177], v151 offset:33792
	ds_read_b128 v[178:181], v151 offset:34816
	ds_read_b128 v[182:185], v151 offset:35840
	ds_read_b128 v[186:189], v151 offset:36864
	ds_read_b128 v[190:193], v151 offset:37888
	ds_read_b128 v[194:197], v151 offset:38912
	ds_read_b128 v[198:201], v151 offset:39936
	global_load_lds_dwordx4 v[202:203], off
	v_lshl_add_u64 v[202:203], s[30:31], 0, v[130:131]
	s_mov_b32 m0, s37
	s_nop 0
	global_load_lds_dwordx4 v[202:203], off
	s_waitcnt lgkmcnt(8)
	s_barrier
	s_waitcnt lgkmcnt(0)
	s_setprio 1
	s_waitcnt lgkmcnt(0)
	v_mfma_f32_16x16x32_bf16 v[124:127], v[154:157], v[170:173], v[124:127]
	v_mfma_f32_16x16x32_bf16 v[120:123], v[162:165], v[170:173], v[120:123]
	v_mfma_f32_16x16x32_bf16 v[108:111], v[154:157], v[178:181], v[108:111]
	v_mfma_f32_16x16x32_bf16 v[104:107], v[162:165], v[178:181], v[104:107]
	v_mfma_f32_16x16x32_bf16 v[92:95], v[154:157], v[186:189], v[92:95]
	v_mfma_f32_16x16x32_bf16 v[88:91], v[162:165], v[186:189], v[88:91]
	v_mfma_f32_16x16x32_bf16 v[76:79], v[154:157], v[194:197], v[76:79]
	v_mfma_f32_16x16x32_bf16 v[72:75], v[162:165], v[194:197], v[72:75]
	v_mfma_f32_16x16x32_bf16 v[124:127], v[158:161], v[174:177], v[124:127]
	v_mfma_f32_16x16x32_bf16 v[120:123], v[166:169], v[174:177], v[120:123]
	v_mfma_f32_16x16x32_bf16 v[108:111], v[158:161], v[182:185], v[108:111]
	v_mfma_f32_16x16x32_bf16 v[104:107], v[166:169], v[182:185], v[104:107]
	v_mfma_f32_16x16x32_bf16 v[92:95], v[158:161], v[190:193], v[92:95]
	v_mfma_f32_16x16x32_bf16 v[88:91], v[166:169], v[190:193], v[88:91]
	v_mfma_f32_16x16x32_bf16 v[76:79], v[158:161], v[198:201], v[76:79]
	v_mfma_f32_16x16x32_bf16 v[72:75], v[166:169], v[198:201], v[72:75]
	s_setprio 0
	s_barrier
	s_add_i32 s30, 0, 0x1c000
	s_add_i32 s31, s56, s34
	v_add_u32_e32 v153, s30, v147
	v_lshl_add_u64 v[144:145], v[144:145], 0, s[4:5]
	s_mov_b32 m0, s31
	ds_read_b128 v[202:205], v153
	ds_read_b128 v[206:209], v153 offset:1024
	ds_read_b128 v[210:213], v153 offset:2048
	ds_read_b128 v[214:217], v153 offset:3072
	global_load_lds_dwordx4 v[144:145], off
	v_lshl_add_u64 v[144:145], v[218:219], 0, s[4:5]
	s_add_i32 m0, s31, 0x2000
	s_nop 0
	global_load_lds_dwordx4 v[144:145], off
	s_barrier
	s_waitcnt lgkmcnt(0)
	s_setprio 1
	s_waitcnt lgkmcnt(0)
	v_mfma_f32_16x16x32_bf16 v[116:119], v[202:205], v[170:173], v[116:119]
	v_mfma_f32_16x16x32_bf16 v[112:115], v[210:213], v[170:173], v[112:115]
	v_mfma_f32_16x16x32_bf16 v[100:103], v[202:205], v[178:181], v[100:103]
	v_mfma_f32_16x16x32_bf16 v[96:99], v[210:213], v[178:181], v[96:99]
	v_mfma_f32_16x16x32_bf16 v[84:87], v[202:205], v[186:189], v[84:87]
	v_mfma_f32_16x16x32_bf16 v[80:83], v[210:213], v[186:189], v[80:83]
	v_mfma_f32_16x16x32_bf16 v[68:71], v[202:205], v[194:197], v[68:71]
	v_mfma_f32_16x16x32_bf16 v[64:67], v[210:213], v[194:197], v[64:67]
	v_mfma_f32_16x16x32_bf16 v[116:119], v[206:209], v[174:177], v[116:119]
	v_mfma_f32_16x16x32_bf16 v[112:115], v[214:217], v[174:177], v[112:115]
	v_mfma_f32_16x16x32_bf16 v[100:103], v[206:209], v[182:185], v[100:103]
	v_mfma_f32_16x16x32_bf16 v[96:99], v[214:217], v[182:185], v[96:99]
	v_mfma_f32_16x16x32_bf16 v[84:87], v[206:209], v[190:193], v[84:87]
	v_mfma_f32_16x16x32_bf16 v[80:83], v[214:217], v[190:193], v[80:83]
	v_mfma_f32_16x16x32_bf16 v[68:71], v[206:209], v[198:201], v[68:71]
	v_mfma_f32_16x16x32_bf16 v[64:67], v[214:217], v[198:201], v[64:67]
	s_setprio 0
	s_mov_b32 m0, s38
	v_lshl_add_u64 v[144:145], v[220:221], 0, s[4:5]
	s_barrier
	ds_read_b128 v[170:173], v151 offset:49152
	ds_read_b128 v[174:177], v151 offset:50176
	ds_read_b128 v[178:181], v151 offset:51200
	ds_read_b128 v[182:185], v151 offset:52224
	ds_read_b128 v[186:189], v151 offset:53248
	ds_read_b128 v[190:193], v151 offset:54272
	ds_read_b128 v[194:197], v151 offset:55296
	ds_read_b128 v[198:201], v151 offset:56320
	global_load_lds_dwordx4 v[144:145], off
	v_lshl_add_u64 v[144:145], v[222:223], 0, s[4:5]
	s_mov_b32 m0, s39
	s_nop 0
	global_load_lds_dwordx4 v[144:145], off
	s_barrier
; #define PG8_STAGE(bufoff, gbase, voff) do { _Pragma("unroll") for (int _i = 0; _i < 2; ++_i) \
;         __builtin_amdgcn_global_load_lds((const unsigned*)((const char*)(gbase) + (voff)[_i]), (LAS unsigned*)(lds + (bufoff) + ldsw + _i * 8192), 16, 0, 0); } while (0)
; #define PG8_MMA(ai, bj, At, Bt) do { __builtin_amdgcn_s_setprio(1); _Pragma("unroll") for (int m = 0; m < 4; ++m) _Pragma("unroll") for (int n = 0; n < 2; ++n) _Pragma("unroll") for (int k = 0; k < 2; ++k) \
;         acc[ai][bj][m][n] = __builtin_amdgcn_mfma_f32_16x16x32_bf16(Bt[n][k], At[m][k], acc[ai][bj][m][n], 0, 0, 0); __builtin_amdgcn_s_setprio(0); } while (0)
; #define PG8_WAIT_V(n) asm volatile("s_waitcnt vmcnt(" #n ")" ::: "memory")
; #define PG8_WAIT_L(n) asm volatile("s_waitcnt lgkmcnt(" #n ")" ::: "memory")
; #define PG8_BAR __builtin_amdgcn_s_barrier()
; #define PG8_SCHED __builtin_amdgcn_sched_barrier(0)
; template <class Epi>
; __device__ __forceinline__ void gemm_phase(LAS unsigned char* lds, const Gemm g, const Order& S, const Epi& E, const int tid) {
;     ...
;             PG8_BAR; PG8_WAIT_L(0); PG8_MMA(1, 0, At, B0); PG8_BAR; PG8_SCHED;
;             PG8_STAGE(PG8_SB(1, 1), b3 + hstepB, voffB);
;             PG8_WAIT_V(6); PG8_BAR; PG8_MMA(1, 1, At, B1); PG8_BAR;
;     __device__ __forceinline__ void operator()(const f32x4 (&acc)[2][2][4][2], const Unit& u, int wr, int wc, int fr, int fq) const {
;     ...
;             for (int m = 0; m < 4; ++m) { bf16_t* rowp = O + (size_t)(row0 + ai * HALF + m * 16) * ldc + col0;
;                 float rs = 1.0f; if (RS) rs = rt[u.i * 256 + wr * 64 + fr + ai * HALF + m * 16];
; #pragma unroll
;                 for (int bj = 0; bj < 2; ++bj) { f32x4 v0 = acc[ai][bj][m][0], v1 = acc[ai][bj][m][1];
;                     if (RS) { v0 *= rs; v1 *= rs; }
;                     if (ACT == 1) {
; #pragma unroll
;                         for (int j = 0; j < 4; ++j) { const float a = fmaxf(v0[j], 0.f), b = fmaxf(v1[j], 0.f); v0[j] = a * a; v1[j] = b * b; } }
;                     u32x4 w; w.x = pk2(v0[0], v0[1]); w.y = pk2(v0[2], v0[3]); w.z = pk2(v1[0], v1[1]); w.w = pk2(v1[2], v1[3]);
;                     *(u32x4*)(rowp + bj * HALF) = w; } }
	s_waitcnt lgkmcnt(0)
	s_setprio 1
	s_waitcnt lgkmcnt(0)
	v_mfma_f32_16x16x32_bf16 v[60:63], v[154:157], v[170:173], v[60:63]
	v_mfma_f32_16x16x32_bf16 v[56:59], v[162:165], v[170:173], v[56:59]
	v_mfma_f32_16x16x32_bf16 v[44:47], v[154:157], v[178:181], v[44:47]
	v_mfma_f32_16x16x32_bf16 v[40:43], v[162:165], v[178:181], v[40:43]
	v_mfma_f32_16x16x32_bf16 v[28:31], v[154:157], v[186:189], v[28:31]
	v_mfma_f32_16x16x32_bf16 v[24:27], v[162:165], v[186:189], v[24:27]
	v_mfma_f32_16x16x32_bf16 v[12:15], v[154:157], v[194:197], v[12:15]
	v_mfma_f32_16x16x32_bf16 v[8:11], v[162:165], v[194:197], v[8:11]
	v_mfma_f32_16x16x32_bf16 v[60:63], v[158:161], v[174:177], v[60:63]
	v_mfma_f32_16x16x32_bf16 v[56:59], v[166:169], v[174:177], v[56:59]
	v_mfma_f32_16x16x32_bf16 v[44:47], v[158:161], v[182:185], v[44:47]
	v_mfma_f32_16x16x32_bf16 v[40:43], v[166:169], v[182:185], v[40:43]
	v_mfma_f32_16x16x32_bf16 v[28:31], v[158:161], v[190:193], v[28:31]
	v_mfma_f32_16x16x32_bf16 v[24:27], v[166:169], v[190:193], v[24:27]
	v_mfma_f32_16x16x32_bf16 v[12:15], v[158:161], v[198:201], v[12:15]
	v_mfma_f32_16x16x32_bf16 v[8:11], v[166:169], v[198:201], v[8:11]
	s_setprio 0
	s_barrier
	s_add_u32 s28, s28, 0x80080
	s_addc_u32 s29, s29, 0
	s_add_i32 s30, s30, s34
	v_lshl_add_u64 v[144:145], s[28:29], 0, v[132:133]
	s_mov_b32 m0, s30
	s_nop 0
	global_load_lds_dwordx4 v[144:145], off
	v_lshl_add_u64 v[144:145], s[28:29], 0, v[128:129]
	s_add_i32 m0, s30, 0x2000
	s_nop 0
	global_load_lds_dwordx4 v[144:145], off
	s_waitcnt vmcnt(6)
	s_barrier
	s_setprio 1
	v_mfma_f32_16x16x32_bf16 v[52:55], v[202:205], v[170:173], v[52:55]
	v_mfma_f32_16x16x32_bf16 v[48:51], v[210:213], v[170:173], v[48:51]
	v_mfma_f32_16x16x32_bf16 v[36:39], v[202:205], v[178:181], v[36:39]
	v_mfma_f32_16x16x32_bf16 v[32:35], v[210:213], v[178:181], v[32:35]
	v_mfma_f32_16x16x32_bf16 v[20:23], v[202:205], v[186:189], v[20:23]
	v_mfma_f32_16x16x32_bf16 v[16:19], v[210:213], v[186:189], v[16:19]
	v_mfma_f32_16x16x32_bf16 v[4:7], v[202:205], v[194:197], v[4:7]
	v_mfma_f32_16x16x32_bf16 v[0:3], v[210:213], v[194:197], v[0:3]
	v_mfma_f32_16x16x32_bf16 v[52:55], v[206:209], v[174:177], v[52:55]
	v_mfma_f32_16x16x32_bf16 v[48:51], v[214:217], v[174:177], v[48:51]
	v_mfma_f32_16x16x32_bf16 v[36:39], v[206:209], v[182:185], v[36:39]
	v_mfma_f32_16x16x32_bf16 v[32:35], v[214:217], v[182:185], v[32:35]
	v_mfma_f32_16x16x32_bf16 v[20:23], v[206:209], v[190:193], v[20:23]
	v_mfma_f32_16x16x32_bf16 v[16:19], v[214:217], v[190:193], v[16:19]
	v_mfma_f32_16x16x32_bf16 v[4:7], v[206:209], v[198:201], v[4:7]
	v_mfma_f32_16x16x32_bf16 v[0:3], v[214:217], v[198:201], v[0:3]
	s_setprio 0
	s_add_i32 s55, s55, 2
	s_add_u32 s26, s26, 0x100
	s_addc_u32 s27, s27, 0
	s_add_u32 s52, s52, 0x100
	s_addc_u32 s53, s53, 0
	s_cmp_gt_u32 s55, 29
	s_barrier
	s_cbranch_scc0 .LBB0_912
	v_lshl_add_u32 v153, s48, 10, v148
	ds_read2_b32 v[156:157], v153 offset1:16
	v_lshl_add_u32 v154, s24, 8, v146
	v_lshl_or_b32 v144, s49, 8, v149
	v_ashrrev_i32_e32 v155, 31, v154
	v_ashrrev_i32_e32 v145, 31, v144
	s_waitcnt lgkmcnt(0)
	v_pk_mul_f32 v[122:123], v[122:123], v[156:157] op_sel_hi:[1,0]
	v_pk_mul_f32 v[120:121], v[120:121], v[156:157] op_sel_hi:[1,0]
	v_pk_mul_f32 v[126:127], v[126:127], v[156:157] op_sel_hi:[1,0]
	v_pk_mul_f32 v[124:125], v[124:125], v[156:157] op_sel_hi:[1,0]
	v_max_f32_e32 v120, 0, v120
	v_max_f32_e32 v121, 0, v121
	v_max_f32_e32 v122, 0, v122
	v_lshlrev_b64 v[158:159], 14, v[154:155]
	v_max_f32_e32 v124, 0, v124
	v_mul_f32_e32 v155, v120, v120
	v_max_f32_e32 v120, 0, v125
	v_mul_f32_e32 v125, v121, v121
	v_max_f32_e32 v121, 0, v126
	v_mul_f32_e32 v126, v122, v122
	v_max_f32_e32 v122, 0, v127
	v_max_f32_e32 v123, 0, v123
	v_lshl_add_u64 v[158:159], s[72:73], 0, v[158:159]
	v_lshlrev_b64 v[160:161], 1, v[144:145]
	v_mul_f32_e32 v124, v124, v124
	v_mul_f32_e32 v120, v120, v120
	v_mul_f32_e32 v121, v121, v121
	v_mul_f32_e32 v122, v122, v122
	v_mul_f32_e32 v123, v123, v123
	v_pk_mul_f32 v[114:115], v[114:115], v[156:157] op_sel_hi:[1,0]
	v_pk_mul_f32 v[112:113], v[112:113], v[156:157] op_sel_hi:[1,0]
	v_lshl_add_u64 v[144:145], v[158:159], 0, v[160:161]
	v_cvt_pk_bf16_f32 v120, v124, v120
	v_cvt_pk_bf16_f32 v121, v121, v122
	v_cvt_pk_bf16_f32 v122, v155, v125
	v_cvt_pk_bf16_f32 v123, v126, v123
	v_pk_mul_f32 v[118:119], v[118:119], v[156:157] op_sel_hi:[1,0]
	v_pk_mul_f32 v[116:117], v[116:117], v[156:157] op_sel_hi:[1,0]
	v_max_f32_e32 v112, 0, v112
	v_max_f32_e32 v113, 0, v113
	v_max_f32_e32 v114, 0, v114
	global_store_dwordx4 v[144:145], v[120:123], off sc0 sc1
	v_max_f32_e32 v116, 0, v116
	v_max_f32_e32 v115, 0, v115
	v_mul_f32_e32 v120, v112, v112
	v_max_f32_e32 v112, 0, v117
	v_mul_f32_e32 v117, v113, v113
	v_max_f32_e32 v113, 0, v118
	v_mul_f32_e32 v118, v114, v114
	v_max_f32_e32 v114, 0, v119
	v_mul_f32_e32 v116, v116, v116
	v_mul_f32_e32 v112, v112, v112
	v_mul_f32_e32 v113, v113, v113
	v_mul_f32_e32 v114, v114, v114
	v_mul_f32_e32 v115, v115, v115
	v_cvt_pk_bf16_f32 v112, v116, v112
	v_cvt_pk_bf16_f32 v113, v113, v114
	v_cvt_pk_bf16_f32 v114, v120, v117
	v_cvt_pk_bf16_f32 v115, v118, v115
	global_store_dwordx4 v[144:145], v[112:115], off offset:256 sc0 sc1
	s_mov_b32 s48, s47
	s_mov_b32 s49, s16
	v_mov_b32_e32 v114, v157
	v_or_b32_e32 v112, 16, v154
	v_pk_mul_f32 v[106:107], v[106:107], v[114:115] op_sel_hi:[1,0]
	v_pk_mul_f32 v[104:105], v[104:105], v[114:115] op_sel_hi:[1,0]
	v_ashrrev_i32_e32 v113, 31, v112
	v_pk_mul_f32 v[110:111], v[110:111], v[114:115] op_sel_hi:[1,0]
	v_pk_mul_f32 v[108:109], v[108:109], v[114:115] op_sel_hi:[1,0]
	v_max_f32_e32 v104, 0, v104
	v_max_f32_e32 v105, 0, v105
	v_max_f32_e32 v106, 0, v106
;     __device__ __forceinline__ void operator()(const f32x4 (&acc)[2][2][4][2], const Unit& u, int wr, int wc, int fr, int fq) const {
;     ...
;             for (int m = 0; m < 4; ++m) { bf16_t* rowp = O + (size_t)(row0 + ai * HALF + m * 16) * ldc + col0;
;                 float rs = 1.0f; if (RS) rs = rt[u.i * 256 + wr * 64 + fr + ai * HALF + m * 16];
; #pragma unroll
;                 for (int bj = 0; bj < 2; ++bj) { f32x4 v0 = acc[ai][bj][m][0], v1 = acc[ai][bj][m][1];
;                     if (RS) { v0 *= rs; v1 *= rs; }
;                     if (ACT == 1) {
; #pragma unroll
;                         for (int j = 0; j < 4; ++j) { const float a = fmaxf(v0[j], 0.f), b = fmaxf(v1[j], 0.f); v0[j] = a * a; v1[j] = b * b; } }
;                     u32x4 w; w.x = pk2(v0[0], v0[1]); w.y = pk2(v0[2], v0[3]); w.z = pk2(v1[0], v1[1]); w.w = pk2(v1[2], v1[3]);
;                     *(u32x4*)(rowp + bj * HALF) = w; } }
	v_lshlrev_b64 v[112:113], 14, v[112:113]
	v_max_f32_e32 v108, 0, v108
	v_mul_f32_e32 v115, v104, v104
	v_max_f32_e32 v104, 0, v109
	v_mul_f32_e32 v109, v105, v105
	v_max_f32_e32 v105, 0, v110
	v_mul_f32_e32 v110, v106, v106
	v_max_f32_e32 v106, 0, v111
	v_max_f32_e32 v107, 0, v107
	v_lshl_add_u64 v[112:113], s[72:73], 0, v[112:113]
	v_mul_f32_e32 v108, v108, v108
	v_mul_f32_e32 v104, v104, v104
	v_mul_f32_e32 v105, v105, v105
	v_mul_f32_e32 v106, v106, v106
	v_mul_f32_e32 v107, v107, v107
	v_pk_mul_f32 v[98:99], v[98:99], v[114:115] op_sel_hi:[1,0]
	v_pk_mul_f32 v[96:97], v[96:97], v[114:115] op_sel_hi:[1,0]
	v_lshl_add_u64 v[112:113], v[112:113], 0, v[160:161]
	v_cvt_pk_bf16_f32 v104, v108, v104
	v_cvt_pk_bf16_f32 v105, v105, v106
	v_cvt_pk_bf16_f32 v106, v115, v109
	v_cvt_pk_bf16_f32 v107, v110, v107
	v_pk_mul_f32 v[102:103], v[102:103], v[114:115] op_sel_hi:[1,0]
	v_pk_mul_f32 v[100:101], v[100:101], v[114:115] op_sel_hi:[1,0]
	v_max_f32_e32 v96, 0, v96
	v_max_f32_e32 v97, 0, v97
	v_max_f32_e32 v98, 0, v98
	global_store_dwordx4 v[112:113], v[104:107], off sc0 sc1
	v_max_f32_e32 v100, 0, v100
	v_max_f32_e32 v99, 0, v99
	v_mul_f32_e32 v104, v96, v96
	v_max_f32_e32 v96, 0, v101
	v_mul_f32_e32 v101, v97, v97
	v_max_f32_e32 v97, 0, v102
	v_mul_f32_e32 v102, v98, v98
	v_max_f32_e32 v98, 0, v103
	v_mul_f32_e32 v100, v100, v100
	v_mul_f32_e32 v96, v96, v96
	v_mul_f32_e32 v97, v97, v97
	v_mul_f32_e32 v98, v98, v98
	v_mul_f32_e32 v99, v99, v99
	v_cvt_pk_bf16_f32 v96, v100, v96
	v_cvt_pk_bf16_f32 v97, v97, v98
	v_cvt_pk_bf16_f32 v98, v104, v101
	v_cvt_pk_bf16_f32 v99, v102, v99
	global_store_dwordx4 v[112:113], v[96:99], off offset:256 sc0 sc1
	ds_read2_b32 v[98:99], v153 offset0:32 offset1:48
	s_mov_b32 s24, s14
	v_or_b32_e32 v96, 32, v154
	v_ashrrev_i32_e32 v97, 31, v96
	v_lshlrev_b64 v[96:97], 14, v[96:97]
	s_waitcnt lgkmcnt(0)
	v_pk_mul_f32 v[90:91], v[90:91], v[98:99] op_sel_hi:[1,0]
	v_pk_mul_f32 v[88:89], v[88:89], v[98:99] op_sel_hi:[1,0]
	v_pk_mul_f32 v[94:95], v[94:95], v[98:99] op_sel_hi:[1,0]
	v_pk_mul_f32 v[92:93], v[92:93], v[98:99] op_sel_hi:[1,0]
	v_max_f32_e32 v88, 0, v88
	v_max_f32_e32 v89, 0, v89
	v_max_f32_e32 v90, 0, v90
	v_max_f32_e32 v92, 0, v92
	v_mul_f32_e32 v100, v88, v88
	v_max_f32_e32 v88, 0, v93
	v_mul_f32_e32 v93, v89, v89
	v_max_f32_e32 v89, 0, v94
	v_mul_f32_e32 v94, v90, v90
	v_max_f32_e32 v90, 0, v95
	v_max_f32_e32 v91, 0, v91
	v_lshl_add_u64 v[96:97], s[72:73], 0, v[96:97]
	v_mul_f32_e32 v92, v92, v92
	v_mul_f32_e32 v88, v88, v88
	v_mul_f32_e32 v89, v89, v89
	v_mul_f32_e32 v90, v90, v90
	v_mul_f32_e32 v91, v91, v91
	v_pk_mul_f32 v[82:83], v[82:83], v[98:99] op_sel_hi:[1,0]
	v_pk_mul_f32 v[80:81], v[80:81], v[98:99] op_sel_hi:[1,0]
	v_lshl_add_u64 v[96:97], v[96:97], 0, v[160:161]
	v_cvt_pk_bf16_f32 v88, v92, v88
	v_cvt_pk_bf16_f32 v89, v89, v90
	v_cvt_pk_bf16_f32 v90, v100, v93
	v_cvt_pk_bf16_f32 v91, v94, v91
	v_pk_mul_f32 v[86:87], v[86:87], v[98:99] op_sel_hi:[1,0]
	v_pk_mul_f32 v[84:85], v[84:85], v[98:99] op_sel_hi:[1,0]
	v_max_f32_e32 v80, 0, v80
	v_max_f32_e32 v81, 0, v81
	v_max_f32_e32 v82, 0, v82
	global_store_dwordx4 v[96:97], v[88:91], off sc0 sc1
	v_max_f32_e32 v84, 0, v84
	v_max_f32_e32 v83, 0, v83
	v_mul_f32_e32 v88, v80, v80
	v_max_f32_e32 v80, 0, v85
	v_mul_f32_e32 v85, v81, v81
	v_max_f32_e32 v81, 0, v86
	v_mul_f32_e32 v86, v82, v82
	v_max_f32_e32 v82, 0, v87
	v_mul_f32_e32 v84, v84, v84
	v_mul_f32_e32 v80, v80, v80
	v_mul_f32_e32 v81, v81, v81
	v_mul_f32_e32 v82, v82, v82
	v_mul_f32_e32 v83, v83, v83
	v_cvt_pk_bf16_f32 v80, v84, v80
	v_cvt_pk_bf16_f32 v81, v81, v82
	v_cvt_pk_bf16_f32 v82, v88, v85
	v_cvt_pk_bf16_f32 v83, v86, v83
	global_store_dwordx4 v[96:97], v[80:83], off offset:256 sc0 sc1
	s_mov_b64 s[28:29], s[20:21]
	s_mov_b64 s[26:27], s[18:19]
	v_mov_b32_e32 v82, v99
	v_or_b32_e32 v80, 48, v154
	v_pk_mul_f32 v[74:75], v[74:75], v[82:83] op_sel_hi:[1,0]
	v_pk_mul_f32 v[72:73], v[72:73], v[82:83] op_sel_hi:[1,0]
	v_ashrrev_i32_e32 v81, 31, v80
	v_pk_mul_f32 v[78:79], v[78:79], v[82:83] op_sel_hi:[1,0]
	v_pk_mul_f32 v[76:77], v[76:77], v[82:83] op_sel_hi:[1,0]
	v_max_f32_e32 v72, 0, v72
	v_max_f32_e32 v73, 0, v73
	v_max_f32_e32 v74, 0, v74
	v_lshlrev_b64 v[80:81], 14, v[80:81]
	v_max_f32_e32 v76, 0, v76
	v_mul_f32_e32 v83, v72, v72
	v_max_f32_e32 v72, 0, v77
	v_mul_f32_e32 v77, v73, v73
	v_max_f32_e32 v73, 0, v78
	v_mul_f32_e32 v78, v74, v74
	v_max_f32_e32 v74, 0, v79
	v_max_f32_e32 v75, 0, v75
	v_lshl_add_u64 v[80:81], s[72:73], 0, v[80:81]
	v_mul_f32_e32 v76, v76, v76
	v_mul_f32_e32 v72, v72, v72
	v_mul_f32_e32 v73, v73, v73
	v_mul_f32_e32 v74, v74, v74
	v_mul_f32_e32 v75, v75, v75
	v_pk_mul_f32 v[64:65], v[64:65], v[82:83] op_sel_hi:[1,0]
	v_lshl_add_u64 v[80:81], v[80:81], 0, v[160:161]
	v_cvt_pk_bf16_f32 v72, v76, v72
	v_cvt_pk_bf16_f32 v73, v73, v74
	v_cvt_pk_bf16_f32 v74, v83, v77
	v_cvt_pk_bf16_f32 v75, v78, v75
	v_pk_mul_f32 v[68:69], v[68:69], v[82:83] op_sel_hi:[1,0]
	v_max_f32_e32 v64, 0, v64
	global_store_dwordx4 v[80:81], v[72:75], off sc0 sc1
	v_max_f32_e32 v68, 0, v68
	v_mul_f32_e32 v68, v68, v68
	v_mul_f32_e32 v72, v64, v64
	v_max_f32_e32 v64, 0, v69
	v_mul_f32_e32 v64, v64, v64
	v_cvt_pk_bf16_f32 v64, v68, v64
	ds_read2_b32 v[68:69], v153 offset0:128 offset1:144
	v_pk_mul_f32 v[66:67], v[66:67], v[82:83] op_sel_hi:[1,0]
	v_pk_mul_f32 v[70:71], v[70:71], v[82:83] op_sel_hi:[1,0]
	v_max_f32_e32 v65, 0, v65
	v_max_f32_e32 v66, 0, v66
	v_mul_f32_e32 v73, v65, v65
	v_max_f32_e32 v65, 0, v70
	v_mul_f32_e32 v70, v66, v66
	v_max_f32_e32 v66, 0, v71
	v_max_f32_e32 v67, 0, v67
	v_mul_f32_e32 v65, v65, v65
	v_mul_f32_e32 v66, v66, v66
	v_mul_f32_e32 v67, v67, v67
	s_waitcnt lgkmcnt(0)
;     __device__ __forceinline__ void operator()(const f32x4 (&acc)[2][2][4][2], const Unit& u, int wr, int wc, int fr, int fq) const {
;     ...
;             for (int m = 0; m < 4; ++m) { bf16_t* rowp = O + (size_t)(row0 + ai * HALF + m * 16) * ldc + col0;
;                 float rs = 1.0f; if (RS) rs = rt[u.i * 256 + wr * 64 + fr + ai * HALF + m * 16];
; #pragma unroll
;                 for (int bj = 0; bj < 2; ++bj) { f32x4 v0 = acc[ai][bj][m][0], v1 = acc[ai][bj][m][1];
;                     if (RS) { v0 *= rs; v1 *= rs; }
;                     if (ACT == 1) {
; #pragma unroll
;                         for (int j = 0; j < 4; ++j) { const float a = fmaxf(v0[j], 0.f), b = fmaxf(v1[j], 0.f); v0[j] = a * a; v1[j] = b * b; } }
;                     u32x4 w; w.x = pk2(v0[0], v0[1]); w.y = pk2(v0[2], v0[3]); w.z = pk2(v1[0], v1[1]); w.w = pk2(v1[2], v1[3]);
;                     *(u32x4*)(rowp + bj * HALF) = w; } }
	v_pk_mul_f32 v[56:57], v[56:57], v[68:69] op_sel_hi:[1,0]
	v_cvt_pk_bf16_f32 v65, v65, v66
	v_cvt_pk_bf16_f32 v66, v72, v73
	v_cvt_pk_bf16_f32 v67, v70, v67
	v_pk_mul_f32 v[60:61], v[60:61], v[68:69] op_sel_hi:[1,0]
	v_pk_mul_f32 v[58:59], v[58:59], v[68:69] op_sel_hi:[1,0]
	v_max_f32_e32 v56, 0, v56
	global_store_dwordx4 v[80:81], v[64:67], off offset:256 sc0 sc1
	v_pk_mul_f32 v[62:63], v[62:63], v[68:69] op_sel_hi:[1,0]
	v_max_f32_e32 v60, 0, v60
	v_mul_f32_e32 v66, v56, v56
	v_max_f32_e32 v56, 0, v61
	v_max_f32_e32 v57, 0, v57
	v_max_f32_e32 v58, 0, v58
	v_mul_f32_e32 v60, v60, v60
	v_mul_f32_e32 v56, v56, v56
	v_mul_f32_e32 v61, v57, v57
	v_max_f32_e32 v57, 0, v62
	v_mul_f32_e32 v62, v58, v58
	v_max_f32_e32 v58, 0, v63
	v_max_f32_e32 v59, 0, v59
	v_mul_f32_e32 v57, v57, v57
	v_mul_f32_e32 v58, v58, v58
	v_mul_f32_e32 v59, v59, v59
	v_cvt_pk_bf16_f32 v56, v60, v56
	v_add_co_u32_e32 v60, vcc, s42, v144
	v_pk_mul_f32 v[50:51], v[50:51], v[68:69] op_sel_hi:[1,0]
	v_pk_mul_f32 v[48:49], v[48:49], v[68:69] op_sel_hi:[1,0]
	v_cvt_pk_bf16_f32 v57, v57, v58
	v_cvt_pk_bf16_f32 v58, v66, v61
	v_cvt_pk_bf16_f32 v59, v62, v59
	v_addc_co_u32_e32 v61, vcc, 0, v145, vcc
	v_pk_mul_f32 v[54:55], v[54:55], v[68:69] op_sel_hi:[1,0]
	v_pk_mul_f32 v[52:53], v[52:53], v[68:69] op_sel_hi:[1,0]
	v_max_f32_e32 v48, 0, v48
	v_max_f32_e32 v49, 0, v49
	v_max_f32_e32 v50, 0, v50
	global_store_dwordx4 v[60:61], v[56:59], off sc0 sc1
	v_max_f32_e32 v52, 0, v52
	v_max_f32_e32 v51, 0, v51
	v_mul_f32_e32 v56, v48, v48
	v_max_f32_e32 v48, 0, v53
	v_mul_f32_e32 v53, v49, v49
	v_max_f32_e32 v49, 0, v54
	v_mul_f32_e32 v54, v50, v50
	v_max_f32_e32 v50, 0, v55
	v_mul_f32_e32 v52, v52, v52
	v_mul_f32_e32 v48, v48, v48
	v_mul_f32_e32 v49, v49, v49
	v_mul_f32_e32 v50, v50, v50
	v_mul_f32_e32 v51, v51, v51
	v_lshl_add_u64 v[64:65], v[144:145], 0, s[6:7]
	v_cvt_pk_bf16_f32 v48, v52, v48
	v_cvt_pk_bf16_f32 v49, v49, v50
	v_cvt_pk_bf16_f32 v50, v56, v53
	v_cvt_pk_bf16_f32 v51, v54, v51
	global_store_dwordx4 v[64:65], v[48:51], off offset:256 sc0 sc1
	s_nop 1
	v_mov_b32_e32 v50, v69
	v_pk_mul_f32 v[40:41], v[40:41], v[50:51] op_sel_hi:[1,0]
	v_pk_mul_f32 v[44:45], v[44:45], v[50:51] op_sel_hi:[1,0]
	v_pk_mul_f32 v[42:43], v[42:43], v[50:51] op_sel_hi:[1,0]
	v_max_f32_e32 v40, 0, v40
	v_pk_mul_f32 v[46:47], v[46:47], v[50:51] op_sel_hi:[1,0]
	v_max_f32_e32 v44, 0, v44
	v_mul_f32_e32 v51, v40, v40
	v_max_f32_e32 v40, 0, v45
	v_max_f32_e32 v41, 0, v41
	v_max_f32_e32 v42, 0, v42
	v_mul_f32_e32 v44, v44, v44
	v_mul_f32_e32 v40, v40, v40
	v_mul_f32_e32 v45, v41, v41
	v_max_f32_e32 v41, 0, v46
	v_mul_f32_e32 v46, v42, v42
	v_max_f32_e32 v42, 0, v47
	v_max_f32_e32 v43, 0, v43
	v_mul_f32_e32 v41, v41, v41
	v_mul_f32_e32 v42, v42, v42
	v_mul_f32_e32 v43, v43, v43
	v_cvt_pk_bf16_f32 v40, v44, v40
	v_add_co_u32_e32 v44, vcc, s43, v144
	v_pk_mul_f32 v[32:33], v[32:33], v[50:51] op_sel_hi:[1,0]
	v_cvt_pk_bf16_f32 v41, v41, v42
	v_cvt_pk_bf16_f32 v42, v51, v45
	v_cvt_pk_bf16_f32 v43, v46, v43
	v_addc_co_u32_e32 v45, vcc, 0, v145, vcc
	v_pk_mul_f32 v[36:37], v[36:37], v[50:51] op_sel_hi:[1,0]
	v_max_f32_e32 v32, 0, v32
	global_store_dwordx4 v[44:45], v[40:43], off sc0 sc1
	v_max_f32_e32 v36, 0, v36
	v_mul_f32_e32 v36, v36, v36
	v_mul_f32_e32 v40, v32, v32
	v_max_f32_e32 v32, 0, v37
	v_mul_f32_e32 v32, v32, v32
	v_cvt_pk_bf16_f32 v32, v36, v32
	ds_read2_b32 v[36:37], v153 offset0:160 offset1:176
	v_pk_mul_f32 v[34:35], v[34:35], v[50:51] op_sel_hi:[1,0]
	v_pk_mul_f32 v[38:39], v[38:39], v[50:51] op_sel_hi:[1,0]
	v_max_f32_e32 v33, 0, v33
	v_max_f32_e32 v34, 0, v34
	v_mul_f32_e32 v41, v33, v33
	v_max_f32_e32 v33, 0, v38
	v_mul_f32_e32 v38, v34, v34
	v_max_f32_e32 v34, 0, v39
	v_max_f32_e32 v35, 0, v35
	v_mul_f32_e32 v33, v33, v33
	v_mul_f32_e32 v34, v34, v34
	v_mul_f32_e32 v35, v35, v35
	s_waitcnt lgkmcnt(0)
; #define PG8_WAIT_V(n) asm volatile("s_waitcnt vmcnt(" #n ")" ::: "memory")
; #define PG8_BAR __builtin_amdgcn_s_barrier()
; template <class Epi>
; __device__ __forceinline__ void gemm_phase(LAS unsigned char* lds, const Gemm g, const Order& S, const Epi& E, const int tid) {
;     ...
;         E(acc, cur, wr, wc, fr, fq);
;         if (!has_next) break;
;     ...
;     PG8_WAIT_V(0);
;     if (wr == 0) PG8_BAR;
;     __device__ __forceinline__ void operator()(const f32x4 (&acc)[2][2][4][2], const Unit& u, int wr, int wc, int fr, int fq) const {
;     ...
;             for (int m = 0; m < 4; ++m) { bf16_t* rowp = O + (size_t)(row0 + ai * HALF + m * 16) * ldc + col0;
;                 float rs = 1.0f; if (RS) rs = rt[u.i * 256 + wr * 64 + fr + ai * HALF + m * 16];
; #pragma unroll
;                 for (int bj = 0; bj < 2; ++bj) { f32x4 v0 = acc[ai][bj][m][0], v1 = acc[ai][bj][m][1];
;                     if (RS) { v0 *= rs; v1 *= rs; }
;                     if (ACT == 1) {
; #pragma unroll
;                         for (int j = 0; j < 4; ++j) { const float a = fmaxf(v0[j], 0.f), b = fmaxf(v1[j], 0.f); v0[j] = a * a; v1[j] = b * b; } }
;                     u32x4 w; w.x = pk2(v0[0], v0[1]); w.y = pk2(v0[2], v0[3]); w.z = pk2(v1[0], v1[1]); w.w = pk2(v1[2], v1[3]);
;                     *(u32x4*)(rowp + bj * HALF) = w; } }
	v_pk_mul_f32 v[24:25], v[24:25], v[36:37] op_sel_hi:[1,0]
	v_lshl_add_u64 v[48:49], v[144:145], 0, s[8:9]
	v_cvt_pk_bf16_f32 v33, v33, v34
	v_cvt_pk_bf16_f32 v34, v40, v41
	v_cvt_pk_bf16_f32 v35, v38, v35
	v_pk_mul_f32 v[28:29], v[28:29], v[36:37] op_sel_hi:[1,0]
	v_pk_mul_f32 v[26:27], v[26:27], v[36:37] op_sel_hi:[1,0]
	v_max_f32_e32 v24, 0, v24
	global_store_dwordx4 v[48:49], v[32:35], off offset:256 sc0 sc1
	v_pk_mul_f32 v[30:31], v[30:31], v[36:37] op_sel_hi:[1,0]
	v_max_f32_e32 v28, 0, v28
	v_mul_f32_e32 v34, v24, v24
	v_max_f32_e32 v24, 0, v29
	v_max_f32_e32 v25, 0, v25
	v_max_f32_e32 v26, 0, v26
	v_mul_f32_e32 v28, v28, v28
	v_mul_f32_e32 v24, v24, v24
	v_mul_f32_e32 v29, v25, v25
	v_max_f32_e32 v25, 0, v30
	v_mul_f32_e32 v30, v26, v26
	v_max_f32_e32 v26, 0, v31
	v_max_f32_e32 v27, 0, v27
	v_mul_f32_e32 v25, v25, v25
	v_mul_f32_e32 v26, v26, v26
	v_mul_f32_e32 v27, v27, v27
	v_cvt_pk_bf16_f32 v24, v28, v24
	v_add_co_u32_e32 v28, vcc, s44, v144
	v_pk_mul_f32 v[18:19], v[18:19], v[36:37] op_sel_hi:[1,0]
	v_pk_mul_f32 v[16:17], v[16:17], v[36:37] op_sel_hi:[1,0]
	v_cvt_pk_bf16_f32 v25, v25, v26
	v_cvt_pk_bf16_f32 v26, v34, v29
	v_cvt_pk_bf16_f32 v27, v30, v27
	v_addc_co_u32_e32 v29, vcc, 0, v145, vcc
	v_pk_mul_f32 v[22:23], v[22:23], v[36:37] op_sel_hi:[1,0]
	v_pk_mul_f32 v[20:21], v[20:21], v[36:37] op_sel_hi:[1,0]
	v_max_f32_e32 v16, 0, v16
	v_max_f32_e32 v17, 0, v17
	v_max_f32_e32 v18, 0, v18
	global_store_dwordx4 v[28:29], v[24:27], off sc0 sc1
	v_max_f32_e32 v20, 0, v20
	v_max_f32_e32 v19, 0, v19
	v_mul_f32_e32 v24, v16, v16
	v_max_f32_e32 v16, 0, v21
	v_mul_f32_e32 v21, v17, v17
	v_max_f32_e32 v17, 0, v22
	v_mul_f32_e32 v22, v18, v18
	v_max_f32_e32 v18, 0, v23
	v_mul_f32_e32 v20, v20, v20
	v_mul_f32_e32 v16, v16, v16
	v_mul_f32_e32 v17, v17, v17
	v_mul_f32_e32 v18, v18, v18
	v_mul_f32_e32 v19, v19, v19
	v_lshl_add_u64 v[32:33], v[144:145], 0, s[10:11]
	v_cvt_pk_bf16_f32 v16, v20, v16
	v_cvt_pk_bf16_f32 v17, v17, v18
	v_cvt_pk_bf16_f32 v18, v24, v21
	v_cvt_pk_bf16_f32 v19, v22, v19
	global_store_dwordx4 v[32:33], v[16:19], off offset:256 sc0 sc1
	s_nop 1
	v_mov_b32_e32 v18, v37
	v_pk_mul_f32 v[8:9], v[8:9], v[18:19] op_sel_hi:[1,0]
	v_pk_mul_f32 v[12:13], v[12:13], v[18:19] op_sel_hi:[1,0]
	v_pk_mul_f32 v[10:11], v[10:11], v[18:19] op_sel_hi:[1,0]
	v_max_f32_e32 v8, 0, v8
	v_pk_mul_f32 v[14:15], v[14:15], v[18:19] op_sel_hi:[1,0]
	v_max_f32_e32 v12, 0, v12
	v_mul_f32_e32 v19, v8, v8
	v_max_f32_e32 v8, 0, v13
	v_max_f32_e32 v9, 0, v9
	v_max_f32_e32 v10, 0, v10
	v_mul_f32_e32 v12, v12, v12
	v_mul_f32_e32 v8, v8, v8
	v_mul_f32_e32 v13, v9, v9
	v_max_f32_e32 v9, 0, v14
	v_mul_f32_e32 v14, v10, v10
	v_max_f32_e32 v10, 0, v15
	v_max_f32_e32 v11, 0, v11
	v_mul_f32_e32 v9, v9, v9
	v_mul_f32_e32 v10, v10, v10
	v_mul_f32_e32 v11, v11, v11
	v_cvt_pk_bf16_f32 v8, v12, v8
	v_add_co_u32_e32 v12, vcc, s45, v144
	v_pk_mul_f32 v[2:3], v[2:3], v[18:19] op_sel_hi:[1,0]
	v_pk_mul_f32 v[0:1], v[0:1], v[18:19] op_sel_hi:[1,0]
	v_cvt_pk_bf16_f32 v9, v9, v10
	v_cvt_pk_bf16_f32 v10, v19, v13
	v_cvt_pk_bf16_f32 v11, v14, v11
	v_addc_co_u32_e32 v13, vcc, 0, v145, vcc
	v_pk_mul_f32 v[6:7], v[6:7], v[18:19] op_sel_hi:[1,0]
	v_pk_mul_f32 v[4:5], v[4:5], v[18:19] op_sel_hi:[1,0]
	v_max_f32_e32 v0, 0, v0
	v_max_f32_e32 v1, 0, v1
	v_max_f32_e32 v2, 0, v2
	global_store_dwordx4 v[12:13], v[8:11], off sc0 sc1
	v_max_f32_e32 v4, 0, v4
	v_max_f32_e32 v3, 0, v3
	v_mul_f32_e32 v8, v0, v0
	v_max_f32_e32 v0, 0, v5
	v_mul_f32_e32 v5, v1, v1
	v_max_f32_e32 v1, 0, v6
	v_mul_f32_e32 v6, v2, v2
	v_max_f32_e32 v2, 0, v7
	v_mul_f32_e32 v4, v4, v4
	v_mul_f32_e32 v0, v0, v0
	v_mul_f32_e32 v1, v1, v1
	v_mul_f32_e32 v2, v2, v2
	v_mul_f32_e32 v3, v3, v3
	v_lshl_add_u64 v[16:17], v[144:145], 0, s[12:13]
	v_cvt_pk_bf16_f32 v0, v4, v0
	v_cvt_pk_bf16_f32 v1, v1, v2
	v_cvt_pk_bf16_f32 v2, v8, v5
	v_cvt_pk_bf16_f32 v3, v6, v3
	s_and_b64 vcc, exec, s[0:1]
	global_store_dwordx4 v[16:17], v[0:3], off offset:256 sc0 sc1
	s_cbranch_vccz .LBB0_905
	s_waitcnt vmcnt(0)
	s_cmpk_gt_u32 s33, 0xff
	s_cbranch_scc1 .LBB0_916
	s_barrier
